# K-loops: one static priority raise for the leading wave half (counterpart of the trailing-half raise), no per-cluster toggling
# speedup vs baseline: 1.0052x; 1.0014x over previous
.LBB0_165:
	s_add_u32 s16, s14, 0xfff80080
	s_addc_u32 s17, s15, -1
	s_cmp_eq_u32 s64, 28
	s_cselect_b32 s19, s1, s17
	s_cselect_b32 s18, s4, s16
	s_cselect_b32 s17, s11, s21
	s_cselect_b32 s16, s13, s20
	s_and_b64 vcc, exec, s[36:37]
	s_cbranch_vccz .Lk64_trail_p1
	s_setprio 1
	s_sub_u32 vcc_lo, s20, 0x80
	s_subb_u32 vcc_hi, s21, 0
	s_add_i32 m0, s23, 0x18000
	s_nop 0
	global_load_lds_dwordx4 v130, vcc
	s_add_i32 m0, s23, 0x1a000
	s_nop 0
	global_load_lds_dwordx4 v134, vcc
	s_add_u32 vcc_lo, vcc_lo, 0x20000
	s_addc_u32 vcc_hi, vcc_hi, 0
	s_add_i32 m0, s23, 0x19000
	s_nop 0
	global_load_lds_dwordx4 v130, vcc
	s_add_i32 m0, s23, 0x1b000
	s_nop 0
	global_load_lds_dwordx4 v134, vcc
	s_add_u32 vcc_lo, vcc_lo, 0x60000
	s_addc_u32 vcc_hi, vcc_hi, 0
	s_add_i32 m0, s23, 0x1c000
	s_nop 0
	global_load_lds_dwordx4 v130, vcc
	s_add_i32 m0, s23, 0x1e000
	s_nop 0
	global_load_lds_dwordx4 v134, vcc
	s_add_u32 vcc_lo, vcc_lo, 0x20000
	s_addc_u32 vcc_hi, vcc_hi, 0
	s_add_i32 m0, s23, 0x1d000
	s_nop 0
	global_load_lds_dwordx4 v130, vcc
	s_add_i32 m0, s23, 0x1f000
	s_nop 0
	global_load_lds_dwordx4 v134, vcc
	ds_read_b128 v[148:151], v168 offset:0
	ds_read_b128 v[152:155], v168 offset:1024
	ds_read_b128 v[156:159], v168 offset:2048
	ds_read_b128 v[172:175], v168 offset:3072
	ds_read_b128 v[176:179], v169 offset:0
	ds_read_b128 v[180:183], v169 offset:1024
	ds_read_b128 v[184:187], v169 offset:2048
	ds_read_b128 v[188:191], v169 offset:3072
	ds_read_b128 v[192:195], v170 offset:0
	ds_read_b128 v[196:199], v170 offset:1024
	ds_read_b128 v[200:203], v170 offset:2048
	ds_read_b128 v[204:207], v170 offset:3072
	ds_read_b128 v[208:211], v170 offset:4096
	ds_read_b128 v[212:215], v170 offset:5120
	ds_read_b128 v[216:219], v170 offset:6144
	ds_read_b128 v[220:223], v170 offset:7168
	ds_read_b128 v[142:145], v170 offset:16384
	ds_read_b128 v[224:227], v170 offset:17408
	ds_read_b128 v[228:231], v170 offset:18432
	ds_read_b128 v[232:235], v170 offset:19456
	ds_read_b128 v[236:239], v170 offset:20480
	ds_read_b128 v[240:243], v170 offset:21504
	ds_read_b128 v[244:247], v170 offset:22528
	ds_read_b128 v[248:251], v170 offset:23552
	s_nop 15
	s_nop 15
	s_waitcnt lgkmcnt(0)
	s_barrier
	v_mfma_f32_16x16x32_bf16 v[124:127], v[148:151], v[192:195], v[124:127]
	v_mfma_f32_16x16x32_bf16 v[120:123], v[156:159], v[192:195], v[120:123]
	v_mfma_f32_16x16x32_bf16 v[116:119], v[148:151], v[200:203], v[116:119]
	v_mfma_f32_16x16x32_bf16 v[112:115], v[156:159], v[200:203], v[112:115]
	v_mfma_f32_16x16x32_bf16 v[100:103], v[148:151], v[208:211], v[100:103]
	v_mfma_f32_16x16x32_bf16 v[96:99], v[156:159], v[208:211], v[96:99]
	v_mfma_f32_16x16x32_bf16 v[84:87], v[148:151], v[216:219], v[84:87]
	v_mfma_f32_16x16x32_bf16 v[80:83], v[156:159], v[216:219], v[80:83]
	v_mfma_f32_16x16x32_bf16 v[124:127], v[152:155], v[196:199], v[124:127]
	v_mfma_f32_16x16x32_bf16 v[120:123], v[172:175], v[196:199], v[120:123]
	v_mfma_f32_16x16x32_bf16 v[116:119], v[152:155], v[204:207], v[116:119]
	v_mfma_f32_16x16x32_bf16 v[112:115], v[172:175], v[204:207], v[112:115]
	v_mfma_f32_16x16x32_bf16 v[100:103], v[152:155], v[212:215], v[100:103]
	v_mfma_f32_16x16x32_bf16 v[96:99], v[172:175], v[212:215], v[96:99]
	v_mfma_f32_16x16x32_bf16 v[84:87], v[152:155], v[220:223], v[84:87]
	v_mfma_f32_16x16x32_bf16 v[80:83], v[172:175], v[220:223], v[80:83]
	v_mfma_f32_16x16x32_bf16 v[108:111], v[176:179], v[192:195], v[108:111]
	v_mfma_f32_16x16x32_bf16 v[104:107], v[184:187], v[192:195], v[104:107]
	v_mfma_f32_16x16x32_bf16 v[92:95], v[176:179], v[200:203], v[92:95]
	v_mfma_f32_16x16x32_bf16 v[88:91], v[184:187], v[200:203], v[88:91]
	v_mfma_f32_16x16x32_bf16 v[76:79], v[176:179], v[208:211], v[76:79]
	v_mfma_f32_16x16x32_bf16 v[72:75], v[184:187], v[208:211], v[72:75]
	v_mfma_f32_16x16x32_bf16 v[68:71], v[176:179], v[216:219], v[68:71]
	v_mfma_f32_16x16x32_bf16 v[64:67], v[184:187], v[216:219], v[64:67]
	v_mfma_f32_16x16x32_bf16 v[108:111], v[180:183], v[196:199], v[108:111]
	v_mfma_f32_16x16x32_bf16 v[104:107], v[188:191], v[196:199], v[104:107]
	v_mfma_f32_16x16x32_bf16 v[92:95], v[180:183], v[204:207], v[92:95]
	v_mfma_f32_16x16x32_bf16 v[88:91], v[188:191], v[204:207], v[88:91]
	v_mfma_f32_16x16x32_bf16 v[76:79], v[180:183], v[212:215], v[76:79]
	v_mfma_f32_16x16x32_bf16 v[72:75], v[188:191], v[212:215], v[72:75]
	v_mfma_f32_16x16x32_bf16 v[68:71], v[180:183], v[220:223], v[68:71]
	v_mfma_f32_16x16x32_bf16 v[64:67], v[188:191], v[220:223], v[64:67]
	v_mfma_f32_16x16x32_bf16 v[60:63], v[148:151], v[142:145], v[60:63]
	v_mfma_f32_16x16x32_bf16 v[56:59], v[156:159], v[142:145], v[56:59]
	v_mfma_f32_16x16x32_bf16 v[52:55], v[148:151], v[228:231], v[52:55]
	v_mfma_f32_16x16x32_bf16 v[48:51], v[156:159], v[228:231], v[48:51]
	v_mfma_f32_16x16x32_bf16 v[36:39], v[148:151], v[236:239], v[36:39]
	v_mfma_f32_16x16x32_bf16 v[32:35], v[156:159], v[236:239], v[32:35]
	v_mfma_f32_16x16x32_bf16 v[20:23], v[148:151], v[244:247], v[20:23]
	v_mfma_f32_16x16x32_bf16 v[16:19], v[156:159], v[244:247], v[16:19]
	v_mfma_f32_16x16x32_bf16 v[60:63], v[152:155], v[224:227], v[60:63]
	v_mfma_f32_16x16x32_bf16 v[56:59], v[172:175], v[224:227], v[56:59]
	v_mfma_f32_16x16x32_bf16 v[52:55], v[152:155], v[232:235], v[52:55]
	v_mfma_f32_16x16x32_bf16 v[48:51], v[172:175], v[232:235], v[48:51]
	v_mfma_f32_16x16x32_bf16 v[36:39], v[152:155], v[240:243], v[36:39]
	v_mfma_f32_16x16x32_bf16 v[32:35], v[172:175], v[240:243], v[32:35]
	v_mfma_f32_16x16x32_bf16 v[20:23], v[152:155], v[248:251], v[20:23]
	v_mfma_f32_16x16x32_bf16 v[16:19], v[172:175], v[248:251], v[16:19]
	v_mfma_f32_16x16x32_bf16 v[44:47], v[176:179], v[142:145], v[44:47]
	v_mfma_f32_16x16x32_bf16 v[40:43], v[184:187], v[142:145], v[40:43]
	v_mfma_f32_16x16x32_bf16 v[28:31], v[176:179], v[228:231], v[28:31]
	v_mfma_f32_16x16x32_bf16 v[24:27], v[184:187], v[228:231], v[24:27]
	v_mfma_f32_16x16x32_bf16 v[12:15], v[176:179], v[236:239], v[12:15]
	v_mfma_f32_16x16x32_bf16 v[8:11], v[184:187], v[236:239], v[8:11]
	v_mfma_f32_16x16x32_bf16 v[4:7], v[176:179], v[244:247], v[4:7]
	v_mfma_f32_16x16x32_bf16 v[0:3], v[184:187], v[244:247], v[0:3]
	v_mfma_f32_16x16x32_bf16 v[44:47], v[180:183], v[224:227], v[44:47]
	v_mfma_f32_16x16x32_bf16 v[40:43], v[188:191], v[224:227], v[40:43]
	v_mfma_f32_16x16x32_bf16 v[28:31], v[180:183], v[232:235], v[28:31]
	v_mfma_f32_16x16x32_bf16 v[24:27], v[188:191], v[232:235], v[24:27]
	v_mfma_f32_16x16x32_bf16 v[12:15], v[180:183], v[240:243], v[12:15]
	v_mfma_f32_16x16x32_bf16 v[8:11], v[188:191], v[240:243], v[8:11]
	v_mfma_f32_16x16x32_bf16 v[4:7], v[180:183], v[248:251], v[4:7]
	v_mfma_f32_16x16x32_bf16 v[0:3], v[188:191], v[248:251], v[0:3]
	s_waitcnt vmcnt(0)
	s_barrier
	s_add_u32 vcc_lo, s16, 0x0
	s_addc_u32 vcc_hi, s17, 0
	s_add_i32 m0, s23, 0x10000
	s_nop 0
	global_load_lds_dwordx4 v130, vcc
	s_add_i32 m0, s23, 0x12000
	s_nop 0
	global_load_lds_dwordx4 v134, vcc
	s_add_u32 vcc_lo, vcc_lo, 0x20000
	s_addc_u32 vcc_hi, vcc_hi, 0
	s_add_i32 m0, s23, 0x11000
	s_nop 0
	global_load_lds_dwordx4 v130, vcc
	s_add_i32 m0, s23, 0x13000
	s_nop 0
	global_load_lds_dwordx4 v134, vcc
	s_add_u32 vcc_lo, vcc_lo, 0x60000
	s_addc_u32 vcc_hi, vcc_hi, 0
	s_add_i32 m0, s23, 0x14000
	s_nop 0
	global_load_lds_dwordx4 v130, vcc
	s_add_i32 m0, s23, 0x16000
	s_nop 0
	global_load_lds_dwordx4 v134, vcc
	s_add_u32 vcc_lo, vcc_lo, 0x20000
	s_addc_u32 vcc_hi, vcc_hi, 0
	s_add_i32 m0, s23, 0x15000
	s_nop 0
	global_load_lds_dwordx4 v130, vcc
	s_add_i32 m0, s23, 0x17000
	s_nop 0
	global_load_lds_dwordx4 v134, vcc
	ds_read_b128 v[148:151], v168 offset:32768
	ds_read_b128 v[152:155], v168 offset:33792
	ds_read_b128 v[156:159], v168 offset:34816
	ds_read_b128 v[172:175], v168 offset:35840
	ds_read_b128 v[176:179], v169 offset:32768
	ds_read_b128 v[180:183], v169 offset:33792
	ds_read_b128 v[184:187], v169 offset:34816
	ds_read_b128 v[188:191], v169 offset:35840
	ds_read_b128 v[192:195], v170 offset:32768
	ds_read_b128 v[196:199], v170 offset:33792
	ds_read_b128 v[200:203], v170 offset:34816
	ds_read_b128 v[204:207], v170 offset:35840
	ds_read_b128 v[208:211], v170 offset:36864
	ds_read_b128 v[212:215], v170 offset:37888
	ds_read_b128 v[216:219], v170 offset:38912
	ds_read_b128 v[220:223], v170 offset:39936
	ds_read_b128 v[142:145], v170 offset:49152
	ds_read_b128 v[224:227], v170 offset:50176
	ds_read_b128 v[228:231], v170 offset:51200
	ds_read_b128 v[232:235], v170 offset:52224
	ds_read_b128 v[236:239], v170 offset:53248
	ds_read_b128 v[240:243], v170 offset:54272
	ds_read_b128 v[244:247], v170 offset:55296
	ds_read_b128 v[248:251], v170 offset:56320
	s_nop 15
	s_nop 15
	s_waitcnt lgkmcnt(0)
	s_barrier
	v_mfma_f32_16x16x32_bf16 v[124:127], v[148:151], v[192:195], v[124:127]
	v_mfma_f32_16x16x32_bf16 v[120:123], v[156:159], v[192:195], v[120:123]
	v_mfma_f32_16x16x32_bf16 v[116:119], v[148:151], v[200:203], v[116:119]
	v_mfma_f32_16x16x32_bf16 v[112:115], v[156:159], v[200:203], v[112:115]
	v_mfma_f32_16x16x32_bf16 v[100:103], v[148:151], v[208:211], v[100:103]
	v_mfma_f32_16x16x32_bf16 v[96:99], v[156:159], v[208:211], v[96:99]
	v_mfma_f32_16x16x32_bf16 v[84:87], v[148:151], v[216:219], v[84:87]
	v_mfma_f32_16x16x32_bf16 v[80:83], v[156:159], v[216:219], v[80:83]
	v_mfma_f32_16x16x32_bf16 v[124:127], v[152:155], v[196:199], v[124:127]
	v_mfma_f32_16x16x32_bf16 v[120:123], v[172:175], v[196:199], v[120:123]
	v_mfma_f32_16x16x32_bf16 v[116:119], v[152:155], v[204:207], v[116:119]
	v_mfma_f32_16x16x32_bf16 v[112:115], v[172:175], v[204:207], v[112:115]
	v_mfma_f32_16x16x32_bf16 v[100:103], v[152:155], v[212:215], v[100:103]
	v_mfma_f32_16x16x32_bf16 v[96:99], v[172:175], v[212:215], v[96:99]
	v_mfma_f32_16x16x32_bf16 v[84:87], v[152:155], v[220:223], v[84:87]
	v_mfma_f32_16x16x32_bf16 v[80:83], v[172:175], v[220:223], v[80:83]
	v_mfma_f32_16x16x32_bf16 v[108:111], v[176:179], v[192:195], v[108:111]
	v_mfma_f32_16x16x32_bf16 v[104:107], v[184:187], v[192:195], v[104:107]
	v_mfma_f32_16x16x32_bf16 v[92:95], v[176:179], v[200:203], v[92:95]
	v_mfma_f32_16x16x32_bf16 v[88:91], v[184:187], v[200:203], v[88:91]
	v_mfma_f32_16x16x32_bf16 v[76:79], v[176:179], v[208:211], v[76:79]
	v_mfma_f32_16x16x32_bf16 v[72:75], v[184:187], v[208:211], v[72:75]
	v_mfma_f32_16x16x32_bf16 v[68:71], v[176:179], v[216:219], v[68:71]
	v_mfma_f32_16x16x32_bf16 v[64:67], v[184:187], v[216:219], v[64:67]
	v_mfma_f32_16x16x32_bf16 v[108:111], v[180:183], v[196:199], v[108:111]
	v_mfma_f32_16x16x32_bf16 v[104:107], v[188:191], v[196:199], v[104:107]
	v_mfma_f32_16x16x32_bf16 v[92:95], v[180:183], v[204:207], v[92:95]
	v_mfma_f32_16x16x32_bf16 v[88:91], v[188:191], v[204:207], v[88:91]
	v_mfma_f32_16x16x32_bf16 v[76:79], v[180:183], v[212:215], v[76:79]
	v_mfma_f32_16x16x32_bf16 v[72:75], v[188:191], v[212:215], v[72:75]
	v_mfma_f32_16x16x32_bf16 v[68:71], v[180:183], v[220:223], v[68:71]
	v_mfma_f32_16x16x32_bf16 v[64:67], v[188:191], v[220:223], v[64:67]
	v_mfma_f32_16x16x32_bf16 v[60:63], v[148:151], v[142:145], v[60:63]
	v_mfma_f32_16x16x32_bf16 v[56:59], v[156:159], v[142:145], v[56:59]
	v_mfma_f32_16x16x32_bf16 v[52:55], v[148:151], v[228:231], v[52:55]
	v_mfma_f32_16x16x32_bf16 v[48:51], v[156:159], v[228:231], v[48:51]
	v_mfma_f32_16x16x32_bf16 v[36:39], v[148:151], v[236:239], v[36:39]
	v_mfma_f32_16x16x32_bf16 v[32:35], v[156:159], v[236:239], v[32:35]
	v_mfma_f32_16x16x32_bf16 v[20:23], v[148:151], v[244:247], v[20:23]
	v_mfma_f32_16x16x32_bf16 v[16:19], v[156:159], v[244:247], v[16:19]
	v_mfma_f32_16x16x32_bf16 v[60:63], v[152:155], v[224:227], v[60:63]
	v_mfma_f32_16x16x32_bf16 v[56:59], v[172:175], v[224:227], v[56:59]
	v_mfma_f32_16x16x32_bf16 v[52:55], v[152:155], v[232:235], v[52:55]
	v_mfma_f32_16x16x32_bf16 v[48:51], v[172:175], v[232:235], v[48:51]
	v_mfma_f32_16x16x32_bf16 v[36:39], v[152:155], v[240:243], v[36:39]
	v_mfma_f32_16x16x32_bf16 v[32:35], v[172:175], v[240:243], v[32:35]
	v_mfma_f32_16x16x32_bf16 v[20:23], v[152:155], v[248:251], v[20:23]
	v_mfma_f32_16x16x32_bf16 v[16:19], v[172:175], v[248:251], v[16:19]
	v_mfma_f32_16x16x32_bf16 v[44:47], v[176:179], v[142:145], v[44:47]
	v_mfma_f32_16x16x32_bf16 v[40:43], v[184:187], v[142:145], v[40:43]
	v_mfma_f32_16x16x32_bf16 v[28:31], v[176:179], v[228:231], v[28:31]
	v_mfma_f32_16x16x32_bf16 v[24:27], v[184:187], v[228:231], v[24:27]
	v_mfma_f32_16x16x32_bf16 v[12:15], v[176:179], v[236:239], v[12:15]
	v_mfma_f32_16x16x32_bf16 v[8:11], v[184:187], v[236:239], v[8:11]
	v_mfma_f32_16x16x32_bf16 v[4:7], v[176:179], v[244:247], v[4:7]
	v_mfma_f32_16x16x32_bf16 v[0:3], v[184:187], v[244:247], v[0:3]
	v_mfma_f32_16x16x32_bf16 v[44:47], v[180:183], v[224:227], v[44:47]
	v_mfma_f32_16x16x32_bf16 v[40:43], v[188:191], v[224:227], v[40:43]
	v_mfma_f32_16x16x32_bf16 v[28:31], v[180:183], v[232:235], v[28:31]
	v_mfma_f32_16x16x32_bf16 v[24:27], v[188:191], v[232:235], v[24:27]
	v_mfma_f32_16x16x32_bf16 v[12:15], v[180:183], v[240:243], v[12:15]
	v_mfma_f32_16x16x32_bf16 v[8:11], v[188:191], v[240:243], v[8:11]
	v_mfma_f32_16x16x32_bf16 v[4:7], v[180:183], v[248:251], v[4:7]
	v_mfma_f32_16x16x32_bf16 v[0:3], v[188:191], v[248:251], v[0:3]
	s_waitcnt vmcnt(0)
	s_barrier
	s_add_i32 s64, s64, 2
	s_add_u32 s14, s14, 0x100
	s_addc_u32 s15, s15, 0
	s_add_u32 s20, s20, 0x100
	s_addc_u32 s21, s21, 0
	s_cmp_gt_u32 s64, 29
	s_cbranch_scc0 .LBB0_165
	s_branch .Lk64_done_p1
.Lk64_trail_p1:
	s_sub_u32 vcc_lo, s14, 0x80000
	s_subb_u32 vcc_hi, s15, 0
	s_add_i32 m0, s23, 0xa000
	s_nop 0
	global_load_lds_dwordx4 v132, vcc
	s_add_u32 vcc_lo, vcc_lo, 0x20000
	s_addc_u32 vcc_hi, vcc_hi, 0
	s_add_i32 m0, s23, 0x9000
	s_nop 0
	global_load_lds_dwordx4 v128, vcc
	s_add_u32 vcc_lo, vcc_lo, 0x60000
	s_addc_u32 vcc_hi, vcc_hi, 0
	s_add_i32 m0, s23, 0xe000
	s_nop 0
	global_load_lds_dwordx4 v132, vcc
	s_add_u32 vcc_lo, vcc_lo, 0x20000
	s_addc_u32 vcc_hi, vcc_hi, 0
	s_add_i32 m0, s23, 0xd000
	s_nop 0
	global_load_lds_dwordx4 v128, vcc
	s_add_u32 vcc_lo, s18, 0x0
	s_addc_u32 vcc_hi, s19, 0
	s_mov_b32 m0, s23
	s_nop 0
	global_load_lds_dwordx4 v128, vcc
	s_sub_u32 vcc_lo, vcc_lo, 0x20000
	s_subb_u32 vcc_hi, vcc_hi, 0
	s_sub_i32 m0, s23, 0x1000
	s_nop 0
	global_load_lds_dwordx4 v128, vcc
	s_add_u32 vcc_lo, vcc_lo, 0xa0000
	s_addc_u32 vcc_hi, vcc_hi, 0
	s_add_i32 m0, s23, 0x4000
	s_nop 0
	global_load_lds_dwordx4 v128, vcc
	s_sub_u32 vcc_lo, vcc_lo, 0x20000
	s_subb_u32 vcc_hi, vcc_hi, 0
	s_add_i32 m0, s23, 0x3000
	s_nop 0
	global_load_lds_dwordx4 v128, vcc
	ds_read_b128 v[148:151], v168 offset:0
	ds_read_b128 v[152:155], v168 offset:1024
	ds_read_b128 v[156:159], v168 offset:2048
	ds_read_b128 v[172:175], v168 offset:3072
	ds_read_b128 v[176:179], v169 offset:0
	ds_read_b128 v[180:183], v169 offset:1024
	ds_read_b128 v[184:187], v169 offset:2048
	ds_read_b128 v[188:191], v169 offset:3072
	ds_read_b128 v[192:195], v170 offset:0
	ds_read_b128 v[196:199], v170 offset:1024
	ds_read_b128 v[200:203], v170 offset:2048
	ds_read_b128 v[204:207], v170 offset:3072
	ds_read_b128 v[208:211], v170 offset:4096
	ds_read_b128 v[212:215], v170 offset:5120
	ds_read_b128 v[216:219], v170 offset:6144
	ds_read_b128 v[220:223], v170 offset:7168
	ds_read_b128 v[142:145], v170 offset:16384
	ds_read_b128 v[224:227], v170 offset:17408
	ds_read_b128 v[228:231], v170 offset:18432
	ds_read_b128 v[232:235], v170 offset:19456
	ds_read_b128 v[236:239], v170 offset:20480
	ds_read_b128 v[240:243], v170 offset:21504
	ds_read_b128 v[244:247], v170 offset:22528
	ds_read_b128 v[248:251], v170 offset:23552
	s_nop 15
	s_nop 15
	s_waitcnt lgkmcnt(0)
	s_barrier
	v_mfma_f32_16x16x32_bf16 v[124:127], v[148:151], v[192:195], v[124:127]
	v_mfma_f32_16x16x32_bf16 v[120:123], v[156:159], v[192:195], v[120:123]
	v_mfma_f32_16x16x32_bf16 v[116:119], v[148:151], v[200:203], v[116:119]
	v_mfma_f32_16x16x32_bf16 v[112:115], v[156:159], v[200:203], v[112:115]
	v_mfma_f32_16x16x32_bf16 v[100:103], v[148:151], v[208:211], v[100:103]
	v_mfma_f32_16x16x32_bf16 v[96:99], v[156:159], v[208:211], v[96:99]
	v_mfma_f32_16x16x32_bf16 v[84:87], v[148:151], v[216:219], v[84:87]
	v_mfma_f32_16x16x32_bf16 v[80:83], v[156:159], v[216:219], v[80:83]
	v_mfma_f32_16x16x32_bf16 v[124:127], v[152:155], v[196:199], v[124:127]
	v_mfma_f32_16x16x32_bf16 v[120:123], v[172:175], v[196:199], v[120:123]
	v_mfma_f32_16x16x32_bf16 v[116:119], v[152:155], v[204:207], v[116:119]
	v_mfma_f32_16x16x32_bf16 v[112:115], v[172:175], v[204:207], v[112:115]
	v_mfma_f32_16x16x32_bf16 v[100:103], v[152:155], v[212:215], v[100:103]
	v_mfma_f32_16x16x32_bf16 v[96:99], v[172:175], v[212:215], v[96:99]
	v_mfma_f32_16x16x32_bf16 v[84:87], v[152:155], v[220:223], v[84:87]
	v_mfma_f32_16x16x32_bf16 v[80:83], v[172:175], v[220:223], v[80:83]
	v_mfma_f32_16x16x32_bf16 v[108:111], v[176:179], v[192:195], v[108:111]
	v_mfma_f32_16x16x32_bf16 v[104:107], v[184:187], v[192:195], v[104:107]
	v_mfma_f32_16x16x32_bf16 v[92:95], v[176:179], v[200:203], v[92:95]
	v_mfma_f32_16x16x32_bf16 v[88:91], v[184:187], v[200:203], v[88:91]
	v_mfma_f32_16x16x32_bf16 v[76:79], v[176:179], v[208:211], v[76:79]
	v_mfma_f32_16x16x32_bf16 v[72:75], v[184:187], v[208:211], v[72:75]
	v_mfma_f32_16x16x32_bf16 v[68:71], v[176:179], v[216:219], v[68:71]
	v_mfma_f32_16x16x32_bf16 v[64:67], v[184:187], v[216:219], v[64:67]
	v_mfma_f32_16x16x32_bf16 v[108:111], v[180:183], v[196:199], v[108:111]
	v_mfma_f32_16x16x32_bf16 v[104:107], v[188:191], v[196:199], v[104:107]
	v_mfma_f32_16x16x32_bf16 v[92:95], v[180:183], v[204:207], v[92:95]
	v_mfma_f32_16x16x32_bf16 v[88:91], v[188:191], v[204:207], v[88:91]
	v_mfma_f32_16x16x32_bf16 v[76:79], v[180:183], v[212:215], v[76:79]
	v_mfma_f32_16x16x32_bf16 v[72:75], v[188:191], v[212:215], v[72:75]
	v_mfma_f32_16x16x32_bf16 v[68:71], v[180:183], v[220:223], v[68:71]
	v_mfma_f32_16x16x32_bf16 v[64:67], v[188:191], v[220:223], v[64:67]
	v_mfma_f32_16x16x32_bf16 v[60:63], v[148:151], v[142:145], v[60:63]
	v_mfma_f32_16x16x32_bf16 v[56:59], v[156:159], v[142:145], v[56:59]
	v_mfma_f32_16x16x32_bf16 v[52:55], v[148:151], v[228:231], v[52:55]
	v_mfma_f32_16x16x32_bf16 v[48:51], v[156:159], v[228:231], v[48:51]
	v_mfma_f32_16x16x32_bf16 v[36:39], v[148:151], v[236:239], v[36:39]
	v_mfma_f32_16x16x32_bf16 v[32:35], v[156:159], v[236:239], v[32:35]
	v_mfma_f32_16x16x32_bf16 v[20:23], v[148:151], v[244:247], v[20:23]
	v_mfma_f32_16x16x32_bf16 v[16:19], v[156:159], v[244:247], v[16:19]
	v_mfma_f32_16x16x32_bf16 v[60:63], v[152:155], v[224:227], v[60:63]
	v_mfma_f32_16x16x32_bf16 v[56:59], v[172:175], v[224:227], v[56:59]
	v_mfma_f32_16x16x32_bf16 v[52:55], v[152:155], v[232:235], v[52:55]
	v_mfma_f32_16x16x32_bf16 v[48:51], v[172:175], v[232:235], v[48:51]
	v_mfma_f32_16x16x32_bf16 v[36:39], v[152:155], v[240:243], v[36:39]
	v_mfma_f32_16x16x32_bf16 v[32:35], v[172:175], v[240:243], v[32:35]
	v_mfma_f32_16x16x32_bf16 v[20:23], v[152:155], v[248:251], v[20:23]
	v_mfma_f32_16x16x32_bf16 v[16:19], v[172:175], v[248:251], v[16:19]
	v_mfma_f32_16x16x32_bf16 v[44:47], v[176:179], v[142:145], v[44:47]
	v_mfma_f32_16x16x32_bf16 v[40:43], v[184:187], v[142:145], v[40:43]
	v_mfma_f32_16x16x32_bf16 v[28:31], v[176:179], v[228:231], v[28:31]
	v_mfma_f32_16x16x32_bf16 v[24:27], v[184:187], v[228:231], v[24:27]
	v_mfma_f32_16x16x32_bf16 v[12:15], v[176:179], v[236:239], v[12:15]
	v_mfma_f32_16x16x32_bf16 v[8:11], v[184:187], v[236:239], v[8:11]
	v_mfma_f32_16x16x32_bf16 v[4:7], v[176:179], v[244:247], v[4:7]
	v_mfma_f32_16x16x32_bf16 v[0:3], v[184:187], v[244:247], v[0:3]
	v_mfma_f32_16x16x32_bf16 v[44:47], v[180:183], v[224:227], v[44:47]
	v_mfma_f32_16x16x32_bf16 v[40:43], v[188:191], v[224:227], v[40:43]
	v_mfma_f32_16x16x32_bf16 v[28:31], v[180:183], v[232:235], v[28:31]
	v_mfma_f32_16x16x32_bf16 v[24:27], v[188:191], v[232:235], v[24:27]
	v_mfma_f32_16x16x32_bf16 v[12:15], v[180:183], v[240:243], v[12:15]
	v_mfma_f32_16x16x32_bf16 v[8:11], v[188:191], v[240:243], v[8:11]
	v_mfma_f32_16x16x32_bf16 v[4:7], v[180:183], v[248:251], v[4:7]
	v_mfma_f32_16x16x32_bf16 v[0:3], v[188:191], v[248:251], v[0:3]
	s_waitcnt vmcnt(0)
	s_barrier
	s_add_u32 vcc_lo, s18, 0x0
	s_addc_u32 vcc_hi, s19, 0
	s_add_i32 m0, s23, 0x2000
	s_nop 0
	global_load_lds_dwordx4 v132, vcc
	s_add_u32 vcc_lo, vcc_lo, 0x20000
	s_addc_u32 vcc_hi, vcc_hi, 0
	s_add_i32 m0, s23, 0x1000
	s_nop 0
	global_load_lds_dwordx4 v128, vcc
	s_add_u32 vcc_lo, vcc_lo, 0x60000
	s_addc_u32 vcc_hi, vcc_hi, 0
	s_add_i32 m0, s23, 0x6000
	s_nop 0
	global_load_lds_dwordx4 v132, vcc
	s_add_u32 vcc_lo, vcc_lo, 0x20000
	s_addc_u32 vcc_hi, vcc_hi, 0
	s_add_i32 m0, s23, 0x5000
	s_nop 0
	global_load_lds_dwordx4 v128, vcc
	s_add_u32 vcc_lo, s18, 0x80
	s_addc_u32 vcc_hi, s19, 0
	s_add_i32 m0, s23, 0x8000
	s_nop 0
	global_load_lds_dwordx4 v128, vcc
	s_sub_u32 vcc_lo, vcc_lo, 0x20000
	s_subb_u32 vcc_hi, vcc_hi, 0
	s_add_i32 m0, s23, 0x7000
	s_nop 0
	global_load_lds_dwordx4 v128, vcc
	s_add_u32 vcc_lo, vcc_lo, 0xa0000
	s_addc_u32 vcc_hi, vcc_hi, 0
	s_add_i32 m0, s23, 0xc000
	s_nop 0
	global_load_lds_dwordx4 v128, vcc
	s_sub_u32 vcc_lo, vcc_lo, 0x20000
	s_subb_u32 vcc_hi, vcc_hi, 0
	s_add_i32 m0, s23, 0xb000
	s_nop 0
	global_load_lds_dwordx4 v128, vcc
	ds_read_b128 v[148:151], v168 offset:32768
	ds_read_b128 v[152:155], v168 offset:33792
	ds_read_b128 v[156:159], v168 offset:34816
	ds_read_b128 v[172:175], v168 offset:35840
	ds_read_b128 v[176:179], v169 offset:32768
	ds_read_b128 v[180:183], v169 offset:33792
	ds_read_b128 v[184:187], v169 offset:34816
	ds_read_b128 v[188:191], v169 offset:35840
	ds_read_b128 v[192:195], v170 offset:32768
	ds_read_b128 v[196:199], v170 offset:33792
	ds_read_b128 v[200:203], v170 offset:34816
	ds_read_b128 v[204:207], v170 offset:35840
	ds_read_b128 v[208:211], v170 offset:36864
	ds_read_b128 v[212:215], v170 offset:37888
	ds_read_b128 v[216:219], v170 offset:38912
	ds_read_b128 v[220:223], v170 offset:39936
	ds_read_b128 v[142:145], v170 offset:49152
	ds_read_b128 v[224:227], v170 offset:50176
	ds_read_b128 v[228:231], v170 offset:51200
	ds_read_b128 v[232:235], v170 offset:52224
	ds_read_b128 v[236:239], v170 offset:53248
	ds_read_b128 v[240:243], v170 offset:54272
	ds_read_b128 v[244:247], v170 offset:55296
	ds_read_b128 v[248:251], v170 offset:56320
	s_nop 15
	s_nop 15
	s_waitcnt lgkmcnt(0)
	s_barrier
	v_mfma_f32_16x16x32_bf16 v[124:127], v[148:151], v[192:195], v[124:127]
	v_mfma_f32_16x16x32_bf16 v[120:123], v[156:159], v[192:195], v[120:123]
	v_mfma_f32_16x16x32_bf16 v[116:119], v[148:151], v[200:203], v[116:119]
	v_mfma_f32_16x16x32_bf16 v[112:115], v[156:159], v[200:203], v[112:115]
	v_mfma_f32_16x16x32_bf16 v[100:103], v[148:151], v[208:211], v[100:103]
	v_mfma_f32_16x16x32_bf16 v[96:99], v[156:159], v[208:211], v[96:99]
	v_mfma_f32_16x16x32_bf16 v[84:87], v[148:151], v[216:219], v[84:87]
	v_mfma_f32_16x16x32_bf16 v[80:83], v[156:159], v[216:219], v[80:83]
	v_mfma_f32_16x16x32_bf16 v[124:127], v[152:155], v[196:199], v[124:127]
	v_mfma_f32_16x16x32_bf16 v[120:123], v[172:175], v[196:199], v[120:123]
	v_mfma_f32_16x16x32_bf16 v[116:119], v[152:155], v[204:207], v[116:119]
	v_mfma_f32_16x16x32_bf16 v[112:115], v[172:175], v[204:207], v[112:115]
	v_mfma_f32_16x16x32_bf16 v[100:103], v[152:155], v[212:215], v[100:103]
	v_mfma_f32_16x16x32_bf16 v[96:99], v[172:175], v[212:215], v[96:99]
	v_mfma_f32_16x16x32_bf16 v[84:87], v[152:155], v[220:223], v[84:87]
	v_mfma_f32_16x16x32_bf16 v[80:83], v[172:175], v[220:223], v[80:83]
	v_mfma_f32_16x16x32_bf16 v[108:111], v[176:179], v[192:195], v[108:111]
	v_mfma_f32_16x16x32_bf16 v[104:107], v[184:187], v[192:195], v[104:107]
	v_mfma_f32_16x16x32_bf16 v[92:95], v[176:179], v[200:203], v[92:95]
	v_mfma_f32_16x16x32_bf16 v[88:91], v[184:187], v[200:203], v[88:91]
	v_mfma_f32_16x16x32_bf16 v[76:79], v[176:179], v[208:211], v[76:79]
	v_mfma_f32_16x16x32_bf16 v[72:75], v[184:187], v[208:211], v[72:75]
	v_mfma_f32_16x16x32_bf16 v[68:71], v[176:179], v[216:219], v[68:71]
	v_mfma_f32_16x16x32_bf16 v[64:67], v[184:187], v[216:219], v[64:67]
	v_mfma_f32_16x16x32_bf16 v[108:111], v[180:183], v[196:199], v[108:111]
	v_mfma_f32_16x16x32_bf16 v[104:107], v[188:191], v[196:199], v[104:107]
	v_mfma_f32_16x16x32_bf16 v[92:95], v[180:183], v[204:207], v[92:95]
	v_mfma_f32_16x16x32_bf16 v[88:91], v[188:191], v[204:207], v[88:91]
	v_mfma_f32_16x16x32_bf16 v[76:79], v[180:183], v[212:215], v[76:79]
	v_mfma_f32_16x16x32_bf16 v[72:75], v[188:191], v[212:215], v[72:75]
	v_mfma_f32_16x16x32_bf16 v[68:71], v[180:183], v[220:223], v[68:71]
	v_mfma_f32_16x16x32_bf16 v[64:67], v[188:191], v[220:223], v[64:67]
	v_mfma_f32_16x16x32_bf16 v[60:63], v[148:151], v[142:145], v[60:63]
	v_mfma_f32_16x16x32_bf16 v[56:59], v[156:159], v[142:145], v[56:59]
	v_mfma_f32_16x16x32_bf16 v[52:55], v[148:151], v[228:231], v[52:55]
	v_mfma_f32_16x16x32_bf16 v[48:51], v[156:159], v[228:231], v[48:51]
	v_mfma_f32_16x16x32_bf16 v[36:39], v[148:151], v[236:239], v[36:39]
	v_mfma_f32_16x16x32_bf16 v[32:35], v[156:159], v[236:239], v[32:35]
	v_mfma_f32_16x16x32_bf16 v[20:23], v[148:151], v[244:247], v[20:23]
	v_mfma_f32_16x16x32_bf16 v[16:19], v[156:159], v[244:247], v[16:19]
	v_mfma_f32_16x16x32_bf16 v[60:63], v[152:155], v[224:227], v[60:63]
	v_mfma_f32_16x16x32_bf16 v[56:59], v[172:175], v[224:227], v[56:59]
	v_mfma_f32_16x16x32_bf16 v[52:55], v[152:155], v[232:235], v[52:55]
	v_mfma_f32_16x16x32_bf16 v[48:51], v[172:175], v[232:235], v[48:51]
	v_mfma_f32_16x16x32_bf16 v[36:39], v[152:155], v[240:243], v[36:39]
	v_mfma_f32_16x16x32_bf16 v[32:35], v[172:175], v[240:243], v[32:35]
	v_mfma_f32_16x16x32_bf16 v[20:23], v[152:155], v[248:251], v[20:23]
	v_mfma_f32_16x16x32_bf16 v[16:19], v[172:175], v[248:251], v[16:19]
	v_mfma_f32_16x16x32_bf16 v[44:47], v[176:179], v[142:145], v[44:47]
	v_mfma_f32_16x16x32_bf16 v[40:43], v[184:187], v[142:145], v[40:43]
	v_mfma_f32_16x16x32_bf16 v[28:31], v[176:179], v[228:231], v[28:31]
	v_mfma_f32_16x16x32_bf16 v[24:27], v[184:187], v[228:231], v[24:27]
	v_mfma_f32_16x16x32_bf16 v[12:15], v[176:179], v[236:239], v[12:15]
	v_mfma_f32_16x16x32_bf16 v[8:11], v[184:187], v[236:239], v[8:11]
	v_mfma_f32_16x16x32_bf16 v[4:7], v[176:179], v[244:247], v[4:7]
	v_mfma_f32_16x16x32_bf16 v[0:3], v[184:187], v[244:247], v[0:3]
	v_mfma_f32_16x16x32_bf16 v[44:47], v[180:183], v[224:227], v[44:47]
	v_mfma_f32_16x16x32_bf16 v[40:43], v[188:191], v[224:227], v[40:43]
	v_mfma_f32_16x16x32_bf16 v[28:31], v[180:183], v[232:235], v[28:31]
	v_mfma_f32_16x16x32_bf16 v[24:27], v[188:191], v[232:235], v[24:27]
	v_mfma_f32_16x16x32_bf16 v[12:15], v[180:183], v[240:243], v[12:15]
	v_mfma_f32_16x16x32_bf16 v[8:11], v[188:191], v[240:243], v[8:11]
	v_mfma_f32_16x16x32_bf16 v[4:7], v[180:183], v[248:251], v[4:7]
	v_mfma_f32_16x16x32_bf16 v[0:3], v[188:191], v[248:251], v[0:3]
	s_waitcnt vmcnt(0)
	s_barrier
	s_add_i32 s64, s64, 2
	s_add_u32 s14, s14, 0x100
	s_addc_u32 s15, s15, 0
	s_add_u32 s20, s20, 0x100
	s_addc_u32 s21, s21, 0
	s_cmp_gt_u32 s64, 29
	s_cbranch_scc0 .LBB0_165

.LBB0_613:
	s_add_u32 s24, s22, 0xfffc0080
	s_addc_u32 s25, s23, -1
	s_cmp_eq_u32 s49, 12
	s_cselect_b32 s27, s13, s25
	s_cselect_b32 s26, s41, s24
	s_cselect_b32 s25, s11, s48
	s_cselect_b32 s24, s46, s47
	s_and_b64 vcc, exec, s[6:7]
	s_cbranch_vccz .Lk64_trail_glu
	s_setprio 1
	s_sub_u32 vcc_lo, s47, 0x80
	s_subb_u32 vcc_hi, s48, 0
	s_add_i32 m0, s28, 0x18000
	s_nop 0
	global_load_lds_dwordx4 v132, vcc
	s_add_i32 m0, s28, 0x1a000
	s_nop 0
	global_load_lds_dwordx4 v128, vcc
	s_add_u32 vcc_lo, vcc_lo, 0x10000
	s_addc_u32 vcc_hi, vcc_hi, 0
	s_add_i32 m0, s28, 0x19000
	s_nop 0
	global_load_lds_dwordx4 v132, vcc
	s_add_i32 m0, s28, 0x1b000
	s_nop 0
	global_load_lds_dwordx4 v128, vcc
	s_add_u32 vcc_lo, vcc_lo, 0x30000
	s_addc_u32 vcc_hi, vcc_hi, 0
	s_add_i32 m0, s28, 0x1c000
	s_nop 0
	global_load_lds_dwordx4 v132, vcc
	s_add_i32 m0, s28, 0x1e000
	s_nop 0
	global_load_lds_dwordx4 v128, vcc
	s_add_u32 vcc_lo, vcc_lo, 0x10000
	s_addc_u32 vcc_hi, vcc_hi, 0
	s_add_i32 m0, s28, 0x1d000
	s_nop 0
	global_load_lds_dwordx4 v132, vcc
	s_add_i32 m0, s28, 0x1f000
	s_nop 0
	global_load_lds_dwordx4 v128, vcc
	ds_read_b128 v[144:147], v151 offset:0
	ds_read_b128 v[154:157], v151 offset:1024
	ds_read_b128 v[158:161], v151 offset:2048
	ds_read_b128 v[162:165], v151 offset:3072
	ds_read_b128 v[166:169], v152 offset:0
	ds_read_b128 v[170:173], v152 offset:1024
	ds_read_b128 v[174:177], v152 offset:2048
	ds_read_b128 v[178:181], v152 offset:3072
	ds_read_b128 v[182:185], v153 offset:0
	ds_read_b128 v[186:189], v153 offset:1024
	ds_read_b128 v[190:193], v153 offset:2048
	ds_read_b128 v[194:197], v153 offset:3072
	ds_read_b128 v[198:201], v153 offset:4096
	ds_read_b128 v[202:205], v153 offset:5120
	ds_read_b128 v[206:209], v153 offset:6144
	ds_read_b128 v[210:213], v153 offset:7168
	ds_read_b128 v[220:223], v153 offset:16384
	ds_read_b128 v[224:227], v153 offset:17408
	ds_read_b128 v[228:231], v153 offset:18432
	ds_read_b128 v[232:235], v153 offset:19456
	ds_read_b128 v[236:239], v153 offset:20480
	ds_read_b128 v[240:243], v153 offset:21504
	ds_read_b128 v[244:247], v153 offset:22528
	ds_read_b128 v[248:251], v153 offset:23552
	s_nop 15
	s_nop 15
	s_waitcnt lgkmcnt(0)
	s_barrier
	v_mfma_f32_16x16x32_bf16 v[124:127], v[144:147], v[182:185], v[124:127]
	v_mfma_f32_16x16x32_bf16 v[120:123], v[158:161], v[182:185], v[120:123]
	v_mfma_f32_16x16x32_bf16 v[108:111], v[144:147], v[190:193], v[108:111]
	v_mfma_f32_16x16x32_bf16 v[104:107], v[158:161], v[190:193], v[104:107]
	v_mfma_f32_16x16x32_bf16 v[92:95], v[144:147], v[198:201], v[92:95]
	v_mfma_f32_16x16x32_bf16 v[88:91], v[158:161], v[198:201], v[88:91]
	v_mfma_f32_16x16x32_bf16 v[76:79], v[144:147], v[206:209], v[76:79]
	v_mfma_f32_16x16x32_bf16 v[72:75], v[158:161], v[206:209], v[72:75]
	v_mfma_f32_16x16x32_bf16 v[124:127], v[154:157], v[186:189], v[124:127]
	v_mfma_f32_16x16x32_bf16 v[120:123], v[162:165], v[186:189], v[120:123]
	v_mfma_f32_16x16x32_bf16 v[108:111], v[154:157], v[194:197], v[108:111]
	v_mfma_f32_16x16x32_bf16 v[104:107], v[162:165], v[194:197], v[104:107]
	v_mfma_f32_16x16x32_bf16 v[92:95], v[154:157], v[202:205], v[92:95]
	v_mfma_f32_16x16x32_bf16 v[88:91], v[162:165], v[202:205], v[88:91]
	v_mfma_f32_16x16x32_bf16 v[76:79], v[154:157], v[210:213], v[76:79]
	v_mfma_f32_16x16x32_bf16 v[72:75], v[162:165], v[210:213], v[72:75]
	v_mfma_f32_16x16x32_bf16 v[116:119], v[166:169], v[182:185], v[116:119]
	v_mfma_f32_16x16x32_bf16 v[112:115], v[174:177], v[182:185], v[112:115]
	v_mfma_f32_16x16x32_bf16 v[100:103], v[166:169], v[190:193], v[100:103]
	v_mfma_f32_16x16x32_bf16 v[96:99], v[174:177], v[190:193], v[96:99]
	v_mfma_f32_16x16x32_bf16 v[84:87], v[166:169], v[198:201], v[84:87]
	v_mfma_f32_16x16x32_bf16 v[80:83], v[174:177], v[198:201], v[80:83]
	v_mfma_f32_16x16x32_bf16 v[68:71], v[166:169], v[206:209], v[68:71]
	v_mfma_f32_16x16x32_bf16 v[64:67], v[174:177], v[206:209], v[64:67]
	v_mfma_f32_16x16x32_bf16 v[116:119], v[170:173], v[186:189], v[116:119]
	v_mfma_f32_16x16x32_bf16 v[112:115], v[178:181], v[186:189], v[112:115]
	v_mfma_f32_16x16x32_bf16 v[100:103], v[170:173], v[194:197], v[100:103]
	v_mfma_f32_16x16x32_bf16 v[96:99], v[178:181], v[194:197], v[96:99]
	v_mfma_f32_16x16x32_bf16 v[84:87], v[170:173], v[202:205], v[84:87]
	v_mfma_f32_16x16x32_bf16 v[80:83], v[178:181], v[202:205], v[80:83]
	v_mfma_f32_16x16x32_bf16 v[68:71], v[170:173], v[210:213], v[68:71]
	v_mfma_f32_16x16x32_bf16 v[64:67], v[178:181], v[210:213], v[64:67]
	v_mfma_f32_16x16x32_bf16 v[60:63], v[144:147], v[220:223], v[60:63]
	v_mfma_f32_16x16x32_bf16 v[56:59], v[158:161], v[220:223], v[56:59]
	v_mfma_f32_16x16x32_bf16 v[44:47], v[144:147], v[228:231], v[44:47]
	v_mfma_f32_16x16x32_bf16 v[40:43], v[158:161], v[228:231], v[40:43]
	v_mfma_f32_16x16x32_bf16 v[28:31], v[144:147], v[236:239], v[28:31]
	v_mfma_f32_16x16x32_bf16 v[24:27], v[158:161], v[236:239], v[24:27]
	v_mfma_f32_16x16x32_bf16 v[12:15], v[144:147], v[244:247], v[12:15]
	v_mfma_f32_16x16x32_bf16 v[8:11], v[158:161], v[244:247], v[8:11]
	v_mfma_f32_16x16x32_bf16 v[60:63], v[154:157], v[224:227], v[60:63]
	v_mfma_f32_16x16x32_bf16 v[56:59], v[162:165], v[224:227], v[56:59]
	v_mfma_f32_16x16x32_bf16 v[44:47], v[154:157], v[232:235], v[44:47]
	v_mfma_f32_16x16x32_bf16 v[40:43], v[162:165], v[232:235], v[40:43]
	v_mfma_f32_16x16x32_bf16 v[28:31], v[154:157], v[240:243], v[28:31]
	v_mfma_f32_16x16x32_bf16 v[24:27], v[162:165], v[240:243], v[24:27]
	v_mfma_f32_16x16x32_bf16 v[12:15], v[154:157], v[248:251], v[12:15]
	v_mfma_f32_16x16x32_bf16 v[8:11], v[162:165], v[248:251], v[8:11]
	v_mfma_f32_16x16x32_bf16 v[52:55], v[166:169], v[220:223], v[52:55]
	v_mfma_f32_16x16x32_bf16 v[48:51], v[174:177], v[220:223], v[48:51]
	v_mfma_f32_16x16x32_bf16 v[36:39], v[166:169], v[228:231], v[36:39]
	v_mfma_f32_16x16x32_bf16 v[32:35], v[174:177], v[228:231], v[32:35]
	v_mfma_f32_16x16x32_bf16 v[20:23], v[166:169], v[236:239], v[20:23]
	v_mfma_f32_16x16x32_bf16 v[16:19], v[174:177], v[236:239], v[16:19]
	v_mfma_f32_16x16x32_bf16 v[4:7], v[166:169], v[244:247], v[4:7]
	v_mfma_f32_16x16x32_bf16 v[0:3], v[174:177], v[244:247], v[0:3]
	v_mfma_f32_16x16x32_bf16 v[52:55], v[170:173], v[224:227], v[52:55]
	v_mfma_f32_16x16x32_bf16 v[48:51], v[178:181], v[224:227], v[48:51]
	v_mfma_f32_16x16x32_bf16 v[36:39], v[170:173], v[232:235], v[36:39]
	v_mfma_f32_16x16x32_bf16 v[32:35], v[178:181], v[232:235], v[32:35]
	v_mfma_f32_16x16x32_bf16 v[20:23], v[170:173], v[240:243], v[20:23]
	v_mfma_f32_16x16x32_bf16 v[16:19], v[178:181], v[240:243], v[16:19]
	v_mfma_f32_16x16x32_bf16 v[4:7], v[170:173], v[248:251], v[4:7]
	v_mfma_f32_16x16x32_bf16 v[0:3], v[178:181], v[248:251], v[0:3]
	s_waitcnt vmcnt(0)
	s_barrier
	s_add_u32 vcc_lo, s24, 0x0
	s_addc_u32 vcc_hi, s25, 0
	s_add_i32 m0, s28, 0x10000
	s_nop 0
	global_load_lds_dwordx4 v132, vcc
	s_add_i32 m0, s28, 0x12000
	s_nop 0
	global_load_lds_dwordx4 v128, vcc
	s_add_u32 vcc_lo, vcc_lo, 0x10000
	s_addc_u32 vcc_hi, vcc_hi, 0
	s_add_i32 m0, s28, 0x11000
	s_nop 0
	global_load_lds_dwordx4 v132, vcc
	s_add_i32 m0, s28, 0x13000
	s_nop 0
	global_load_lds_dwordx4 v128, vcc
	s_add_u32 vcc_lo, vcc_lo, 0x30000
	s_addc_u32 vcc_hi, vcc_hi, 0
	s_add_i32 m0, s28, 0x14000
	s_nop 0
	global_load_lds_dwordx4 v132, vcc
	s_add_i32 m0, s28, 0x16000
	s_nop 0
	global_load_lds_dwordx4 v128, vcc
	s_add_u32 vcc_lo, vcc_lo, 0x10000
	s_addc_u32 vcc_hi, vcc_hi, 0
	s_add_i32 m0, s28, 0x15000
	s_nop 0
	global_load_lds_dwordx4 v132, vcc
	s_add_i32 m0, s28, 0x17000
	s_nop 0
	global_load_lds_dwordx4 v128, vcc
	ds_read_b128 v[144:147], v151 offset:32768
	ds_read_b128 v[154:157], v151 offset:33792
	ds_read_b128 v[158:161], v151 offset:34816
	ds_read_b128 v[162:165], v151 offset:35840
	ds_read_b128 v[166:169], v152 offset:32768
	ds_read_b128 v[170:173], v152 offset:33792
	ds_read_b128 v[174:177], v152 offset:34816
	ds_read_b128 v[178:181], v152 offset:35840
	ds_read_b128 v[182:185], v153 offset:32768
	ds_read_b128 v[186:189], v153 offset:33792
	ds_read_b128 v[190:193], v153 offset:34816
	ds_read_b128 v[194:197], v153 offset:35840
	ds_read_b128 v[198:201], v153 offset:36864
	ds_read_b128 v[202:205], v153 offset:37888
	ds_read_b128 v[206:209], v153 offset:38912
	ds_read_b128 v[210:213], v153 offset:39936
	ds_read_b128 v[220:223], v153 offset:49152
	ds_read_b128 v[224:227], v153 offset:50176
	ds_read_b128 v[228:231], v153 offset:51200
	ds_read_b128 v[232:235], v153 offset:52224
	ds_read_b128 v[236:239], v153 offset:53248
	ds_read_b128 v[240:243], v153 offset:54272
	ds_read_b128 v[244:247], v153 offset:55296
	ds_read_b128 v[248:251], v153 offset:56320
	s_nop 15
	s_nop 15
	s_waitcnt lgkmcnt(0)
	s_barrier
	v_mfma_f32_16x16x32_bf16 v[124:127], v[144:147], v[182:185], v[124:127]
	v_mfma_f32_16x16x32_bf16 v[120:123], v[158:161], v[182:185], v[120:123]
	v_mfma_f32_16x16x32_bf16 v[108:111], v[144:147], v[190:193], v[108:111]
	v_mfma_f32_16x16x32_bf16 v[104:107], v[158:161], v[190:193], v[104:107]
	v_mfma_f32_16x16x32_bf16 v[92:95], v[144:147], v[198:201], v[92:95]
	v_mfma_f32_16x16x32_bf16 v[88:91], v[158:161], v[198:201], v[88:91]
	v_mfma_f32_16x16x32_bf16 v[76:79], v[144:147], v[206:209], v[76:79]
	v_mfma_f32_16x16x32_bf16 v[72:75], v[158:161], v[206:209], v[72:75]
	v_mfma_f32_16x16x32_bf16 v[124:127], v[154:157], v[186:189], v[124:127]
	v_mfma_f32_16x16x32_bf16 v[120:123], v[162:165], v[186:189], v[120:123]
	v_mfma_f32_16x16x32_bf16 v[108:111], v[154:157], v[194:197], v[108:111]
	v_mfma_f32_16x16x32_bf16 v[104:107], v[162:165], v[194:197], v[104:107]
	v_mfma_f32_16x16x32_bf16 v[92:95], v[154:157], v[202:205], v[92:95]
	v_mfma_f32_16x16x32_bf16 v[88:91], v[162:165], v[202:205], v[88:91]
	v_mfma_f32_16x16x32_bf16 v[76:79], v[154:157], v[210:213], v[76:79]
	v_mfma_f32_16x16x32_bf16 v[72:75], v[162:165], v[210:213], v[72:75]
	v_mfma_f32_16x16x32_bf16 v[116:119], v[166:169], v[182:185], v[116:119]
	v_mfma_f32_16x16x32_bf16 v[112:115], v[174:177], v[182:185], v[112:115]
	v_mfma_f32_16x16x32_bf16 v[100:103], v[166:169], v[190:193], v[100:103]
	v_mfma_f32_16x16x32_bf16 v[96:99], v[174:177], v[190:193], v[96:99]
	v_mfma_f32_16x16x32_bf16 v[84:87], v[166:169], v[198:201], v[84:87]
	v_mfma_f32_16x16x32_bf16 v[80:83], v[174:177], v[198:201], v[80:83]
	v_mfma_f32_16x16x32_bf16 v[68:71], v[166:169], v[206:209], v[68:71]
	v_mfma_f32_16x16x32_bf16 v[64:67], v[174:177], v[206:209], v[64:67]
	v_mfma_f32_16x16x32_bf16 v[116:119], v[170:173], v[186:189], v[116:119]
	v_mfma_f32_16x16x32_bf16 v[112:115], v[178:181], v[186:189], v[112:115]
	v_mfma_f32_16x16x32_bf16 v[100:103], v[170:173], v[194:197], v[100:103]
	v_mfma_f32_16x16x32_bf16 v[96:99], v[178:181], v[194:197], v[96:99]
	v_mfma_f32_16x16x32_bf16 v[84:87], v[170:173], v[202:205], v[84:87]
	v_mfma_f32_16x16x32_bf16 v[80:83], v[178:181], v[202:205], v[80:83]
	v_mfma_f32_16x16x32_bf16 v[68:71], v[170:173], v[210:213], v[68:71]
	v_mfma_f32_16x16x32_bf16 v[64:67], v[178:181], v[210:213], v[64:67]
	v_mfma_f32_16x16x32_bf16 v[60:63], v[144:147], v[220:223], v[60:63]
	v_mfma_f32_16x16x32_bf16 v[56:59], v[158:161], v[220:223], v[56:59]
	v_mfma_f32_16x16x32_bf16 v[44:47], v[144:147], v[228:231], v[44:47]
	v_mfma_f32_16x16x32_bf16 v[40:43], v[158:161], v[228:231], v[40:43]
	v_mfma_f32_16x16x32_bf16 v[28:31], v[144:147], v[236:239], v[28:31]
	v_mfma_f32_16x16x32_bf16 v[24:27], v[158:161], v[236:239], v[24:27]
	v_mfma_f32_16x16x32_bf16 v[12:15], v[144:147], v[244:247], v[12:15]
	v_mfma_f32_16x16x32_bf16 v[8:11], v[158:161], v[244:247], v[8:11]
	v_mfma_f32_16x16x32_bf16 v[60:63], v[154:157], v[224:227], v[60:63]
	v_mfma_f32_16x16x32_bf16 v[56:59], v[162:165], v[224:227], v[56:59]
	v_mfma_f32_16x16x32_bf16 v[44:47], v[154:157], v[232:235], v[44:47]
	v_mfma_f32_16x16x32_bf16 v[40:43], v[162:165], v[232:235], v[40:43]
	v_mfma_f32_16x16x32_bf16 v[28:31], v[154:157], v[240:243], v[28:31]
	v_mfma_f32_16x16x32_bf16 v[24:27], v[162:165], v[240:243], v[24:27]
	v_mfma_f32_16x16x32_bf16 v[12:15], v[154:157], v[248:251], v[12:15]
	v_mfma_f32_16x16x32_bf16 v[8:11], v[162:165], v[248:251], v[8:11]
	v_mfma_f32_16x16x32_bf16 v[52:55], v[166:169], v[220:223], v[52:55]
	v_mfma_f32_16x16x32_bf16 v[48:51], v[174:177], v[220:223], v[48:51]
	v_mfma_f32_16x16x32_bf16 v[36:39], v[166:169], v[228:231], v[36:39]
	v_mfma_f32_16x16x32_bf16 v[32:35], v[174:177], v[228:231], v[32:35]
	v_mfma_f32_16x16x32_bf16 v[20:23], v[166:169], v[236:239], v[20:23]
	v_mfma_f32_16x16x32_bf16 v[16:19], v[174:177], v[236:239], v[16:19]
	v_mfma_f32_16x16x32_bf16 v[4:7], v[166:169], v[244:247], v[4:7]
	v_mfma_f32_16x16x32_bf16 v[0:3], v[174:177], v[244:247], v[0:3]
	v_mfma_f32_16x16x32_bf16 v[52:55], v[170:173], v[224:227], v[52:55]
	v_mfma_f32_16x16x32_bf16 v[48:51], v[178:181], v[224:227], v[48:51]
	v_mfma_f32_16x16x32_bf16 v[36:39], v[170:173], v[232:235], v[36:39]
	v_mfma_f32_16x16x32_bf16 v[32:35], v[178:181], v[232:235], v[32:35]
	v_mfma_f32_16x16x32_bf16 v[20:23], v[170:173], v[240:243], v[20:23]
	v_mfma_f32_16x16x32_bf16 v[16:19], v[178:181], v[240:243], v[16:19]
	v_mfma_f32_16x16x32_bf16 v[4:7], v[170:173], v[248:251], v[4:7]
	v_mfma_f32_16x16x32_bf16 v[0:3], v[178:181], v[248:251], v[0:3]
	s_waitcnt vmcnt(0)
	s_barrier
	s_add_i32 s49, s49, 2
	s_add_u32 s22, s22, 0x100
	s_addc_u32 s23, s23, 0
	s_add_u32 s47, s47, 0x100
	s_addc_u32 s48, s48, 0
	s_cmp_gt_u32 s49, 13
	s_cbranch_scc0 .LBB0_613
	s_branch .Lk64_done_glu
.Lk64_trail_glu:
	s_sub_u32 vcc_lo, s22, 0x40000
	s_subb_u32 vcc_hi, s23, 0
	s_add_i32 m0, s28, 0xa000
	s_nop 0
	global_load_lds_dwordx4 v130, vcc
	s_add_u32 vcc_lo, vcc_lo, 0x10000
	s_addc_u32 vcc_hi, vcc_hi, 0
	s_add_i32 m0, s28, 0x9000
	s_nop 0
	global_load_lds_dwordx4 v134, vcc
	s_add_u32 vcc_lo, vcc_lo, 0x30000
	s_addc_u32 vcc_hi, vcc_hi, 0
	s_add_i32 m0, s28, 0xe000
	s_nop 0
	global_load_lds_dwordx4 v130, vcc
	s_add_u32 vcc_lo, vcc_lo, 0x10000
	s_addc_u32 vcc_hi, vcc_hi, 0
	s_add_i32 m0, s28, 0xd000
	s_nop 0
	global_load_lds_dwordx4 v134, vcc
	s_add_u32 vcc_lo, s26, 0x0
	s_addc_u32 vcc_hi, s27, 0
	s_mov_b32 m0, s28
	s_nop 0
	global_load_lds_dwordx4 v134, vcc
	s_sub_u32 vcc_lo, vcc_lo, 0x10000
	s_subb_u32 vcc_hi, vcc_hi, 0
	s_sub_i32 m0, s28, 0x1000
	s_nop 0
	global_load_lds_dwordx4 v134, vcc
	s_add_u32 vcc_lo, vcc_lo, 0x50000
	s_addc_u32 vcc_hi, vcc_hi, 0
	s_add_i32 m0, s28, 0x4000
	s_nop 0
	global_load_lds_dwordx4 v134, vcc
	s_sub_u32 vcc_lo, vcc_lo, 0x10000
	s_subb_u32 vcc_hi, vcc_hi, 0
	s_add_i32 m0, s28, 0x3000
	s_nop 0
	global_load_lds_dwordx4 v134, vcc
	ds_read_b128 v[144:147], v151 offset:0
	ds_read_b128 v[154:157], v151 offset:1024
	ds_read_b128 v[158:161], v151 offset:2048
	ds_read_b128 v[162:165], v151 offset:3072
	ds_read_b128 v[166:169], v152 offset:0
	ds_read_b128 v[170:173], v152 offset:1024
	ds_read_b128 v[174:177], v152 offset:2048
	ds_read_b128 v[178:181], v152 offset:3072
	ds_read_b128 v[182:185], v153 offset:0
	ds_read_b128 v[186:189], v153 offset:1024
	ds_read_b128 v[190:193], v153 offset:2048
	ds_read_b128 v[194:197], v153 offset:3072
	ds_read_b128 v[198:201], v153 offset:4096
	ds_read_b128 v[202:205], v153 offset:5120
	ds_read_b128 v[206:209], v153 offset:6144
	ds_read_b128 v[210:213], v153 offset:7168
	ds_read_b128 v[220:223], v153 offset:16384
	ds_read_b128 v[224:227], v153 offset:17408
	ds_read_b128 v[228:231], v153 offset:18432
	ds_read_b128 v[232:235], v153 offset:19456
	ds_read_b128 v[236:239], v153 offset:20480
	ds_read_b128 v[240:243], v153 offset:21504
	ds_read_b128 v[244:247], v153 offset:22528
	ds_read_b128 v[248:251], v153 offset:23552
	s_nop 15
	s_nop 15
	s_waitcnt lgkmcnt(0)
	s_barrier
	v_mfma_f32_16x16x32_bf16 v[124:127], v[144:147], v[182:185], v[124:127]
	v_mfma_f32_16x16x32_bf16 v[120:123], v[158:161], v[182:185], v[120:123]
	v_mfma_f32_16x16x32_bf16 v[108:111], v[144:147], v[190:193], v[108:111]
	v_mfma_f32_16x16x32_bf16 v[104:107], v[158:161], v[190:193], v[104:107]
	v_mfma_f32_16x16x32_bf16 v[92:95], v[144:147], v[198:201], v[92:95]
	v_mfma_f32_16x16x32_bf16 v[88:91], v[158:161], v[198:201], v[88:91]
	v_mfma_f32_16x16x32_bf16 v[76:79], v[144:147], v[206:209], v[76:79]
	v_mfma_f32_16x16x32_bf16 v[72:75], v[158:161], v[206:209], v[72:75]
	v_mfma_f32_16x16x32_bf16 v[124:127], v[154:157], v[186:189], v[124:127]
	v_mfma_f32_16x16x32_bf16 v[120:123], v[162:165], v[186:189], v[120:123]
	v_mfma_f32_16x16x32_bf16 v[108:111], v[154:157], v[194:197], v[108:111]
	v_mfma_f32_16x16x32_bf16 v[104:107], v[162:165], v[194:197], v[104:107]
	v_mfma_f32_16x16x32_bf16 v[92:95], v[154:157], v[202:205], v[92:95]
	v_mfma_f32_16x16x32_bf16 v[88:91], v[162:165], v[202:205], v[88:91]
	v_mfma_f32_16x16x32_bf16 v[76:79], v[154:157], v[210:213], v[76:79]
	v_mfma_f32_16x16x32_bf16 v[72:75], v[162:165], v[210:213], v[72:75]
	v_mfma_f32_16x16x32_bf16 v[116:119], v[166:169], v[182:185], v[116:119]
	v_mfma_f32_16x16x32_bf16 v[112:115], v[174:177], v[182:185], v[112:115]
	v_mfma_f32_16x16x32_bf16 v[100:103], v[166:169], v[190:193], v[100:103]
	v_mfma_f32_16x16x32_bf16 v[96:99], v[174:177], v[190:193], v[96:99]
	v_mfma_f32_16x16x32_bf16 v[84:87], v[166:169], v[198:201], v[84:87]
	v_mfma_f32_16x16x32_bf16 v[80:83], v[174:177], v[198:201], v[80:83]
	v_mfma_f32_16x16x32_bf16 v[68:71], v[166:169], v[206:209], v[68:71]
	v_mfma_f32_16x16x32_bf16 v[64:67], v[174:177], v[206:209], v[64:67]
	v_mfma_f32_16x16x32_bf16 v[116:119], v[170:173], v[186:189], v[116:119]
	v_mfma_f32_16x16x32_bf16 v[112:115], v[178:181], v[186:189], v[112:115]
	v_mfma_f32_16x16x32_bf16 v[100:103], v[170:173], v[194:197], v[100:103]
	v_mfma_f32_16x16x32_bf16 v[96:99], v[178:181], v[194:197], v[96:99]
	v_mfma_f32_16x16x32_bf16 v[84:87], v[170:173], v[202:205], v[84:87]
	v_mfma_f32_16x16x32_bf16 v[80:83], v[178:181], v[202:205], v[80:83]
	v_mfma_f32_16x16x32_bf16 v[68:71], v[170:173], v[210:213], v[68:71]
	v_mfma_f32_16x16x32_bf16 v[64:67], v[178:181], v[210:213], v[64:67]
	v_mfma_f32_16x16x32_bf16 v[60:63], v[144:147], v[220:223], v[60:63]
	v_mfma_f32_16x16x32_bf16 v[56:59], v[158:161], v[220:223], v[56:59]
	v_mfma_f32_16x16x32_bf16 v[44:47], v[144:147], v[228:231], v[44:47]
	v_mfma_f32_16x16x32_bf16 v[40:43], v[158:161], v[228:231], v[40:43]
	v_mfma_f32_16x16x32_bf16 v[28:31], v[144:147], v[236:239], v[28:31]
	v_mfma_f32_16x16x32_bf16 v[24:27], v[158:161], v[236:239], v[24:27]
	v_mfma_f32_16x16x32_bf16 v[12:15], v[144:147], v[244:247], v[12:15]
	v_mfma_f32_16x16x32_bf16 v[8:11], v[158:161], v[244:247], v[8:11]
	v_mfma_f32_16x16x32_bf16 v[60:63], v[154:157], v[224:227], v[60:63]
	v_mfma_f32_16x16x32_bf16 v[56:59], v[162:165], v[224:227], v[56:59]
	v_mfma_f32_16x16x32_bf16 v[44:47], v[154:157], v[232:235], v[44:47]
	v_mfma_f32_16x16x32_bf16 v[40:43], v[162:165], v[232:235], v[40:43]
	v_mfma_f32_16x16x32_bf16 v[28:31], v[154:157], v[240:243], v[28:31]
	v_mfma_f32_16x16x32_bf16 v[24:27], v[162:165], v[240:243], v[24:27]
	v_mfma_f32_16x16x32_bf16 v[12:15], v[154:157], v[248:251], v[12:15]
	v_mfma_f32_16x16x32_bf16 v[8:11], v[162:165], v[248:251], v[8:11]
	v_mfma_f32_16x16x32_bf16 v[52:55], v[166:169], v[220:223], v[52:55]
	v_mfma_f32_16x16x32_bf16 v[48:51], v[174:177], v[220:223], v[48:51]
	v_mfma_f32_16x16x32_bf16 v[36:39], v[166:169], v[228:231], v[36:39]
	v_mfma_f32_16x16x32_bf16 v[32:35], v[174:177], v[228:231], v[32:35]
	v_mfma_f32_16x16x32_bf16 v[20:23], v[166:169], v[236:239], v[20:23]
	v_mfma_f32_16x16x32_bf16 v[16:19], v[174:177], v[236:239], v[16:19]
	v_mfma_f32_16x16x32_bf16 v[4:7], v[166:169], v[244:247], v[4:7]
	v_mfma_f32_16x16x32_bf16 v[0:3], v[174:177], v[244:247], v[0:3]
	v_mfma_f32_16x16x32_bf16 v[52:55], v[170:173], v[224:227], v[52:55]
	v_mfma_f32_16x16x32_bf16 v[48:51], v[178:181], v[224:227], v[48:51]
	v_mfma_f32_16x16x32_bf16 v[36:39], v[170:173], v[232:235], v[36:39]
	v_mfma_f32_16x16x32_bf16 v[32:35], v[178:181], v[232:235], v[32:35]
	v_mfma_f32_16x16x32_bf16 v[20:23], v[170:173], v[240:243], v[20:23]
	v_mfma_f32_16x16x32_bf16 v[16:19], v[178:181], v[240:243], v[16:19]
	v_mfma_f32_16x16x32_bf16 v[4:7], v[170:173], v[248:251], v[4:7]
	v_mfma_f32_16x16x32_bf16 v[0:3], v[178:181], v[248:251], v[0:3]
	s_waitcnt vmcnt(0)
	s_barrier
	s_add_u32 vcc_lo, s26, 0x0
	s_addc_u32 vcc_hi, s27, 0
	s_add_i32 m0, s28, 0x2000
	s_nop 0
	global_load_lds_dwordx4 v130, vcc
	s_add_u32 vcc_lo, vcc_lo, 0x10000
	s_addc_u32 vcc_hi, vcc_hi, 0
	s_add_i32 m0, s28, 0x1000
	s_nop 0
	global_load_lds_dwordx4 v134, vcc
	s_add_u32 vcc_lo, vcc_lo, 0x30000
	s_addc_u32 vcc_hi, vcc_hi, 0
	s_add_i32 m0, s28, 0x6000
	s_nop 0
	global_load_lds_dwordx4 v130, vcc
	s_add_u32 vcc_lo, vcc_lo, 0x10000
	s_addc_u32 vcc_hi, vcc_hi, 0
	s_add_i32 m0, s28, 0x5000
	s_nop 0
	global_load_lds_dwordx4 v134, vcc
	s_add_u32 vcc_lo, s26, 0x80
	s_addc_u32 vcc_hi, s27, 0
	s_add_i32 m0, s28, 0x8000
	s_nop 0
	global_load_lds_dwordx4 v134, vcc
	s_sub_u32 vcc_lo, vcc_lo, 0x10000
	s_subb_u32 vcc_hi, vcc_hi, 0
	s_add_i32 m0, s28, 0x7000
	s_nop 0
	global_load_lds_dwordx4 v134, vcc
	s_add_u32 vcc_lo, vcc_lo, 0x50000
	s_addc_u32 vcc_hi, vcc_hi, 0
	s_add_i32 m0, s28, 0xc000
	s_nop 0
	global_load_lds_dwordx4 v134, vcc
	s_sub_u32 vcc_lo, vcc_lo, 0x10000
	s_subb_u32 vcc_hi, vcc_hi, 0
	s_add_i32 m0, s28, 0xb000
	s_nop 0
	global_load_lds_dwordx4 v134, vcc
	ds_read_b128 v[144:147], v151 offset:32768
	ds_read_b128 v[154:157], v151 offset:33792
	ds_read_b128 v[158:161], v151 offset:34816
	ds_read_b128 v[162:165], v151 offset:35840
	ds_read_b128 v[166:169], v152 offset:32768
	ds_read_b128 v[170:173], v152 offset:33792
	ds_read_b128 v[174:177], v152 offset:34816
	ds_read_b128 v[178:181], v152 offset:35840
	ds_read_b128 v[182:185], v153 offset:32768
	ds_read_b128 v[186:189], v153 offset:33792
	ds_read_b128 v[190:193], v153 offset:34816
	ds_read_b128 v[194:197], v153 offset:35840
	ds_read_b128 v[198:201], v153 offset:36864
	ds_read_b128 v[202:205], v153 offset:37888
	ds_read_b128 v[206:209], v153 offset:38912
	ds_read_b128 v[210:213], v153 offset:39936
	ds_read_b128 v[220:223], v153 offset:49152
	ds_read_b128 v[224:227], v153 offset:50176
	ds_read_b128 v[228:231], v153 offset:51200
	ds_read_b128 v[232:235], v153 offset:52224
	ds_read_b128 v[236:239], v153 offset:53248
	ds_read_b128 v[240:243], v153 offset:54272
	ds_read_b128 v[244:247], v153 offset:55296
	ds_read_b128 v[248:251], v153 offset:56320
	s_nop 15
	s_nop 15
	s_waitcnt lgkmcnt(0)
	s_barrier
	v_mfma_f32_16x16x32_bf16 v[124:127], v[144:147], v[182:185], v[124:127]
	v_mfma_f32_16x16x32_bf16 v[120:123], v[158:161], v[182:185], v[120:123]
	v_mfma_f32_16x16x32_bf16 v[108:111], v[144:147], v[190:193], v[108:111]
	v_mfma_f32_16x16x32_bf16 v[104:107], v[158:161], v[190:193], v[104:107]
	v_mfma_f32_16x16x32_bf16 v[92:95], v[144:147], v[198:201], v[92:95]
	v_mfma_f32_16x16x32_bf16 v[88:91], v[158:161], v[198:201], v[88:91]
	v_mfma_f32_16x16x32_bf16 v[76:79], v[144:147], v[206:209], v[76:79]
	v_mfma_f32_16x16x32_bf16 v[72:75], v[158:161], v[206:209], v[72:75]
	v_mfma_f32_16x16x32_bf16 v[124:127], v[154:157], v[186:189], v[124:127]
	v_mfma_f32_16x16x32_bf16 v[120:123], v[162:165], v[186:189], v[120:123]
	v_mfma_f32_16x16x32_bf16 v[108:111], v[154:157], v[194:197], v[108:111]
	v_mfma_f32_16x16x32_bf16 v[104:107], v[162:165], v[194:197], v[104:107]
	v_mfma_f32_16x16x32_bf16 v[92:95], v[154:157], v[202:205], v[92:95]
	v_mfma_f32_16x16x32_bf16 v[88:91], v[162:165], v[202:205], v[88:91]
	v_mfma_f32_16x16x32_bf16 v[76:79], v[154:157], v[210:213], v[76:79]
	v_mfma_f32_16x16x32_bf16 v[72:75], v[162:165], v[210:213], v[72:75]
	v_mfma_f32_16x16x32_bf16 v[116:119], v[166:169], v[182:185], v[116:119]
	v_mfma_f32_16x16x32_bf16 v[112:115], v[174:177], v[182:185], v[112:115]
	v_mfma_f32_16x16x32_bf16 v[100:103], v[166:169], v[190:193], v[100:103]
	v_mfma_f32_16x16x32_bf16 v[96:99], v[174:177], v[190:193], v[96:99]
	v_mfma_f32_16x16x32_bf16 v[84:87], v[166:169], v[198:201], v[84:87]
	v_mfma_f32_16x16x32_bf16 v[80:83], v[174:177], v[198:201], v[80:83]
	v_mfma_f32_16x16x32_bf16 v[68:71], v[166:169], v[206:209], v[68:71]
	v_mfma_f32_16x16x32_bf16 v[64:67], v[174:177], v[206:209], v[64:67]
	v_mfma_f32_16x16x32_bf16 v[116:119], v[170:173], v[186:189], v[116:119]
	v_mfma_f32_16x16x32_bf16 v[112:115], v[178:181], v[186:189], v[112:115]
	v_mfma_f32_16x16x32_bf16 v[100:103], v[170:173], v[194:197], v[100:103]
	v_mfma_f32_16x16x32_bf16 v[96:99], v[178:181], v[194:197], v[96:99]
	v_mfma_f32_16x16x32_bf16 v[84:87], v[170:173], v[202:205], v[84:87]
	v_mfma_f32_16x16x32_bf16 v[80:83], v[178:181], v[202:205], v[80:83]
	v_mfma_f32_16x16x32_bf16 v[68:71], v[170:173], v[210:213], v[68:71]
	v_mfma_f32_16x16x32_bf16 v[64:67], v[178:181], v[210:213], v[64:67]
	v_mfma_f32_16x16x32_bf16 v[60:63], v[144:147], v[220:223], v[60:63]
	v_mfma_f32_16x16x32_bf16 v[56:59], v[158:161], v[220:223], v[56:59]
	v_mfma_f32_16x16x32_bf16 v[44:47], v[144:147], v[228:231], v[44:47]
	v_mfma_f32_16x16x32_bf16 v[40:43], v[158:161], v[228:231], v[40:43]
	v_mfma_f32_16x16x32_bf16 v[28:31], v[144:147], v[236:239], v[28:31]
	v_mfma_f32_16x16x32_bf16 v[24:27], v[158:161], v[236:239], v[24:27]
	v_mfma_f32_16x16x32_bf16 v[12:15], v[144:147], v[244:247], v[12:15]
	v_mfma_f32_16x16x32_bf16 v[8:11], v[158:161], v[244:247], v[8:11]
	v_mfma_f32_16x16x32_bf16 v[60:63], v[154:157], v[224:227], v[60:63]
	v_mfma_f32_16x16x32_bf16 v[56:59], v[162:165], v[224:227], v[56:59]
	v_mfma_f32_16x16x32_bf16 v[44:47], v[154:157], v[232:235], v[44:47]
	v_mfma_f32_16x16x32_bf16 v[40:43], v[162:165], v[232:235], v[40:43]
	v_mfma_f32_16x16x32_bf16 v[28:31], v[154:157], v[240:243], v[28:31]
	v_mfma_f32_16x16x32_bf16 v[24:27], v[162:165], v[240:243], v[24:27]
	v_mfma_f32_16x16x32_bf16 v[12:15], v[154:157], v[248:251], v[12:15]
	v_mfma_f32_16x16x32_bf16 v[8:11], v[162:165], v[248:251], v[8:11]
	v_mfma_f32_16x16x32_bf16 v[52:55], v[166:169], v[220:223], v[52:55]
	v_mfma_f32_16x16x32_bf16 v[48:51], v[174:177], v[220:223], v[48:51]
	v_mfma_f32_16x16x32_bf16 v[36:39], v[166:169], v[228:231], v[36:39]
	v_mfma_f32_16x16x32_bf16 v[32:35], v[174:177], v[228:231], v[32:35]
	v_mfma_f32_16x16x32_bf16 v[20:23], v[166:169], v[236:239], v[20:23]
	v_mfma_f32_16x16x32_bf16 v[16:19], v[174:177], v[236:239], v[16:19]
	v_mfma_f32_16x16x32_bf16 v[4:7], v[166:169], v[244:247], v[4:7]
	v_mfma_f32_16x16x32_bf16 v[0:3], v[174:177], v[244:247], v[0:3]
	v_mfma_f32_16x16x32_bf16 v[52:55], v[170:173], v[224:227], v[52:55]
	v_mfma_f32_16x16x32_bf16 v[48:51], v[178:181], v[224:227], v[48:51]
	v_mfma_f32_16x16x32_bf16 v[36:39], v[170:173], v[232:235], v[36:39]
	v_mfma_f32_16x16x32_bf16 v[32:35], v[178:181], v[232:235], v[32:35]
	v_mfma_f32_16x16x32_bf16 v[20:23], v[170:173], v[240:243], v[20:23]
	v_mfma_f32_16x16x32_bf16 v[16:19], v[178:181], v[240:243], v[16:19]
	v_mfma_f32_16x16x32_bf16 v[4:7], v[170:173], v[248:251], v[4:7]
	v_mfma_f32_16x16x32_bf16 v[0:3], v[178:181], v[248:251], v[0:3]
	s_waitcnt vmcnt(0)
	s_barrier
	s_add_i32 s49, s49, 2
	s_add_u32 s22, s22, 0x100
	s_addc_u32 s23, s23, 0
	s_add_u32 s47, s47, 0x100
	s_addc_u32 s48, s48, 0
	s_cmp_gt_u32 s49, 13
	s_cbranch_scc0 .LBB0_613

.LBB0_686:
	s_add_u32 s30, s12, 0xfffc0080
	s_addc_u32 s31, s13, -1
	s_cmp_eq_u32 s56, 12
	s_cselect_b32 s35, s25, s31
	s_cselect_b32 s34, s49, s30
	s_cselect_b32 s31, s23, s55
	s_cselect_b32 s30, s51, s54
	s_and_b64 vcc, exec, s[4:5]
	s_cbranch_vccz .Lk64_trail_p4
	s_setprio 1
	s_sub_u32 vcc_lo, s54, 0x80
	s_subb_u32 vcc_hi, s55, 0
	s_add_i32 m0, s36, 0x18000
	s_nop 0
	global_load_lds_dwordx4 v132, vcc
	s_add_i32 m0, s36, 0x1a000
	s_nop 0
	global_load_lds_dwordx4 v128, vcc
	s_add_u32 vcc_lo, vcc_lo, 0x10000
	s_addc_u32 vcc_hi, vcc_hi, 0
	s_add_i32 m0, s36, 0x19000
	s_nop 0
	global_load_lds_dwordx4 v132, vcc
	s_add_i32 m0, s36, 0x1b000
	s_nop 0
	global_load_lds_dwordx4 v128, vcc
	s_add_u32 vcc_lo, vcc_lo, 0x30000
	s_addc_u32 vcc_hi, vcc_hi, 0
	s_add_i32 m0, s36, 0x1c000
	s_nop 0
	global_load_lds_dwordx4 v132, vcc
	s_add_i32 m0, s36, 0x1e000
	s_nop 0
	global_load_lds_dwordx4 v128, vcc
	s_add_u32 vcc_lo, vcc_lo, 0x10000
	s_addc_u32 vcc_hi, vcc_hi, 0
	s_add_i32 m0, s36, 0x1d000
	s_nop 0
	global_load_lds_dwordx4 v132, vcc
	s_add_i32 m0, s36, 0x1f000
	s_nop 0
	global_load_lds_dwordx4 v128, vcc
	ds_read_b128 v[144:147], v151 offset:0
	ds_read_b128 v[154:157], v151 offset:1024
	ds_read_b128 v[158:161], v151 offset:2048
	ds_read_b128 v[162:165], v151 offset:3072
	ds_read_b128 v[166:169], v152 offset:0
	ds_read_b128 v[170:173], v152 offset:1024
	ds_read_b128 v[174:177], v152 offset:2048
	ds_read_b128 v[178:181], v152 offset:3072
	ds_read_b128 v[182:185], v153 offset:0
	ds_read_b128 v[186:189], v153 offset:1024
	ds_read_b128 v[190:193], v153 offset:2048
	ds_read_b128 v[194:197], v153 offset:3072
	ds_read_b128 v[198:201], v153 offset:4096
	ds_read_b128 v[202:205], v153 offset:5120
	ds_read_b128 v[206:209], v153 offset:6144
	ds_read_b128 v[210:213], v153 offset:7168
	ds_read_b128 v[220:223], v153 offset:16384
	ds_read_b128 v[224:227], v153 offset:17408
	ds_read_b128 v[228:231], v153 offset:18432
	ds_read_b128 v[232:235], v153 offset:19456
	ds_read_b128 v[236:239], v153 offset:20480
	ds_read_b128 v[240:243], v153 offset:21504
	ds_read_b128 v[244:247], v153 offset:22528
	ds_read_b128 v[248:251], v153 offset:23552
	s_nop 15
	s_nop 15
	s_waitcnt lgkmcnt(0)
	s_barrier
	v_mfma_f32_16x16x32_bf16 v[124:127], v[144:147], v[182:185], v[124:127]
	v_mfma_f32_16x16x32_bf16 v[120:123], v[158:161], v[182:185], v[120:123]
	v_mfma_f32_16x16x32_bf16 v[108:111], v[144:147], v[190:193], v[108:111]
	v_mfma_f32_16x16x32_bf16 v[104:107], v[158:161], v[190:193], v[104:107]
	v_mfma_f32_16x16x32_bf16 v[92:95], v[144:147], v[198:201], v[92:95]
	v_mfma_f32_16x16x32_bf16 v[88:91], v[158:161], v[198:201], v[88:91]
	v_mfma_f32_16x16x32_bf16 v[76:79], v[144:147], v[206:209], v[76:79]
	v_mfma_f32_16x16x32_bf16 v[72:75], v[158:161], v[206:209], v[72:75]
	v_mfma_f32_16x16x32_bf16 v[124:127], v[154:157], v[186:189], v[124:127]
	v_mfma_f32_16x16x32_bf16 v[120:123], v[162:165], v[186:189], v[120:123]
	v_mfma_f32_16x16x32_bf16 v[108:111], v[154:157], v[194:197], v[108:111]
	v_mfma_f32_16x16x32_bf16 v[104:107], v[162:165], v[194:197], v[104:107]
	v_mfma_f32_16x16x32_bf16 v[92:95], v[154:157], v[202:205], v[92:95]
	v_mfma_f32_16x16x32_bf16 v[88:91], v[162:165], v[202:205], v[88:91]
	v_mfma_f32_16x16x32_bf16 v[76:79], v[154:157], v[210:213], v[76:79]
	v_mfma_f32_16x16x32_bf16 v[72:75], v[162:165], v[210:213], v[72:75]
	v_mfma_f32_16x16x32_bf16 v[116:119], v[166:169], v[182:185], v[116:119]
	v_mfma_f32_16x16x32_bf16 v[112:115], v[174:177], v[182:185], v[112:115]
	v_mfma_f32_16x16x32_bf16 v[100:103], v[166:169], v[190:193], v[100:103]
	v_mfma_f32_16x16x32_bf16 v[96:99], v[174:177], v[190:193], v[96:99]
	v_mfma_f32_16x16x32_bf16 v[84:87], v[166:169], v[198:201], v[84:87]
	v_mfma_f32_16x16x32_bf16 v[80:83], v[174:177], v[198:201], v[80:83]
	v_mfma_f32_16x16x32_bf16 v[68:71], v[166:169], v[206:209], v[68:71]
	v_mfma_f32_16x16x32_bf16 v[64:67], v[174:177], v[206:209], v[64:67]
	v_mfma_f32_16x16x32_bf16 v[116:119], v[170:173], v[186:189], v[116:119]
	v_mfma_f32_16x16x32_bf16 v[112:115], v[178:181], v[186:189], v[112:115]
	v_mfma_f32_16x16x32_bf16 v[100:103], v[170:173], v[194:197], v[100:103]
	v_mfma_f32_16x16x32_bf16 v[96:99], v[178:181], v[194:197], v[96:99]
	v_mfma_f32_16x16x32_bf16 v[84:87], v[170:173], v[202:205], v[84:87]
	v_mfma_f32_16x16x32_bf16 v[80:83], v[178:181], v[202:205], v[80:83]
	v_mfma_f32_16x16x32_bf16 v[68:71], v[170:173], v[210:213], v[68:71]
	v_mfma_f32_16x16x32_bf16 v[64:67], v[178:181], v[210:213], v[64:67]
	v_mfma_f32_16x16x32_bf16 v[60:63], v[144:147], v[220:223], v[60:63]
	v_mfma_f32_16x16x32_bf16 v[56:59], v[158:161], v[220:223], v[56:59]
	v_mfma_f32_16x16x32_bf16 v[44:47], v[144:147], v[228:231], v[44:47]
	v_mfma_f32_16x16x32_bf16 v[40:43], v[158:161], v[228:231], v[40:43]
	v_mfma_f32_16x16x32_bf16 v[28:31], v[144:147], v[236:239], v[28:31]
	v_mfma_f32_16x16x32_bf16 v[24:27], v[158:161], v[236:239], v[24:27]
	v_mfma_f32_16x16x32_bf16 v[12:15], v[144:147], v[244:247], v[12:15]
	v_mfma_f32_16x16x32_bf16 v[8:11], v[158:161], v[244:247], v[8:11]
	v_mfma_f32_16x16x32_bf16 v[60:63], v[154:157], v[224:227], v[60:63]
	v_mfma_f32_16x16x32_bf16 v[56:59], v[162:165], v[224:227], v[56:59]
	v_mfma_f32_16x16x32_bf16 v[44:47], v[154:157], v[232:235], v[44:47]
	v_mfma_f32_16x16x32_bf16 v[40:43], v[162:165], v[232:235], v[40:43]
	v_mfma_f32_16x16x32_bf16 v[28:31], v[154:157], v[240:243], v[28:31]
	v_mfma_f32_16x16x32_bf16 v[24:27], v[162:165], v[240:243], v[24:27]
	v_mfma_f32_16x16x32_bf16 v[12:15], v[154:157], v[248:251], v[12:15]
	v_mfma_f32_16x16x32_bf16 v[8:11], v[162:165], v[248:251], v[8:11]
	v_mfma_f32_16x16x32_bf16 v[52:55], v[166:169], v[220:223], v[52:55]
	v_mfma_f32_16x16x32_bf16 v[48:51], v[174:177], v[220:223], v[48:51]
	v_mfma_f32_16x16x32_bf16 v[36:39], v[166:169], v[228:231], v[36:39]
	v_mfma_f32_16x16x32_bf16 v[32:35], v[174:177], v[228:231], v[32:35]
	v_mfma_f32_16x16x32_bf16 v[20:23], v[166:169], v[236:239], v[20:23]
	v_mfma_f32_16x16x32_bf16 v[16:19], v[174:177], v[236:239], v[16:19]
	v_mfma_f32_16x16x32_bf16 v[4:7], v[166:169], v[244:247], v[4:7]
	v_mfma_f32_16x16x32_bf16 v[0:3], v[174:177], v[244:247], v[0:3]
	v_mfma_f32_16x16x32_bf16 v[52:55], v[170:173], v[224:227], v[52:55]
	v_mfma_f32_16x16x32_bf16 v[48:51], v[178:181], v[224:227], v[48:51]
	v_mfma_f32_16x16x32_bf16 v[36:39], v[170:173], v[232:235], v[36:39]
	v_mfma_f32_16x16x32_bf16 v[32:35], v[178:181], v[232:235], v[32:35]
	v_mfma_f32_16x16x32_bf16 v[20:23], v[170:173], v[240:243], v[20:23]
	v_mfma_f32_16x16x32_bf16 v[16:19], v[178:181], v[240:243], v[16:19]
	v_mfma_f32_16x16x32_bf16 v[4:7], v[170:173], v[248:251], v[4:7]
	v_mfma_f32_16x16x32_bf16 v[0:3], v[178:181], v[248:251], v[0:3]
	s_waitcnt vmcnt(0)
	s_barrier
	s_add_u32 vcc_lo, s30, 0x0
	s_addc_u32 vcc_hi, s31, 0
	s_add_i32 m0, s36, 0x10000
	s_nop 0
	global_load_lds_dwordx4 v132, vcc
	s_add_i32 m0, s36, 0x12000
	s_nop 0
	global_load_lds_dwordx4 v128, vcc
	s_add_u32 vcc_lo, vcc_lo, 0x10000
	s_addc_u32 vcc_hi, vcc_hi, 0
	s_add_i32 m0, s36, 0x11000
	s_nop 0
	global_load_lds_dwordx4 v132, vcc
	s_add_i32 m0, s36, 0x13000
	s_nop 0
	global_load_lds_dwordx4 v128, vcc
	s_add_u32 vcc_lo, vcc_lo, 0x30000
	s_addc_u32 vcc_hi, vcc_hi, 0
	s_add_i32 m0, s36, 0x14000
	s_nop 0
	global_load_lds_dwordx4 v132, vcc
	s_add_i32 m0, s36, 0x16000
	s_nop 0
	global_load_lds_dwordx4 v128, vcc
	s_add_u32 vcc_lo, vcc_lo, 0x10000
	s_addc_u32 vcc_hi, vcc_hi, 0
	s_add_i32 m0, s36, 0x15000
	s_nop 0
	global_load_lds_dwordx4 v132, vcc
	s_add_i32 m0, s36, 0x17000
	s_nop 0
	global_load_lds_dwordx4 v128, vcc
	ds_read_b128 v[144:147], v151 offset:32768
	ds_read_b128 v[154:157], v151 offset:33792
	ds_read_b128 v[158:161], v151 offset:34816
	ds_read_b128 v[162:165], v151 offset:35840
	ds_read_b128 v[166:169], v152 offset:32768
	ds_read_b128 v[170:173], v152 offset:33792
	ds_read_b128 v[174:177], v152 offset:34816
	ds_read_b128 v[178:181], v152 offset:35840
	ds_read_b128 v[182:185], v153 offset:32768
	ds_read_b128 v[186:189], v153 offset:33792
	ds_read_b128 v[190:193], v153 offset:34816
	ds_read_b128 v[194:197], v153 offset:35840
	ds_read_b128 v[198:201], v153 offset:36864
	ds_read_b128 v[202:205], v153 offset:37888
	ds_read_b128 v[206:209], v153 offset:38912
	ds_read_b128 v[210:213], v153 offset:39936
	ds_read_b128 v[220:223], v153 offset:49152
	ds_read_b128 v[224:227], v153 offset:50176
	ds_read_b128 v[228:231], v153 offset:51200
	ds_read_b128 v[232:235], v153 offset:52224
	ds_read_b128 v[236:239], v153 offset:53248
	ds_read_b128 v[240:243], v153 offset:54272
	ds_read_b128 v[244:247], v153 offset:55296
	ds_read_b128 v[248:251], v153 offset:56320
	s_nop 15
	s_nop 15
	s_waitcnt lgkmcnt(0)
	s_barrier
	v_mfma_f32_16x16x32_bf16 v[124:127], v[144:147], v[182:185], v[124:127]
	v_mfma_f32_16x16x32_bf16 v[120:123], v[158:161], v[182:185], v[120:123]
	v_mfma_f32_16x16x32_bf16 v[108:111], v[144:147], v[190:193], v[108:111]
	v_mfma_f32_16x16x32_bf16 v[104:107], v[158:161], v[190:193], v[104:107]
	v_mfma_f32_16x16x32_bf16 v[92:95], v[144:147], v[198:201], v[92:95]
	v_mfma_f32_16x16x32_bf16 v[88:91], v[158:161], v[198:201], v[88:91]
	v_mfma_f32_16x16x32_bf16 v[76:79], v[144:147], v[206:209], v[76:79]
	v_mfma_f32_16x16x32_bf16 v[72:75], v[158:161], v[206:209], v[72:75]
	v_mfma_f32_16x16x32_bf16 v[124:127], v[154:157], v[186:189], v[124:127]
	v_mfma_f32_16x16x32_bf16 v[120:123], v[162:165], v[186:189], v[120:123]
	v_mfma_f32_16x16x32_bf16 v[108:111], v[154:157], v[194:197], v[108:111]
	v_mfma_f32_16x16x32_bf16 v[104:107], v[162:165], v[194:197], v[104:107]
	v_mfma_f32_16x16x32_bf16 v[92:95], v[154:157], v[202:205], v[92:95]
	v_mfma_f32_16x16x32_bf16 v[88:91], v[162:165], v[202:205], v[88:91]
	v_mfma_f32_16x16x32_bf16 v[76:79], v[154:157], v[210:213], v[76:79]
	v_mfma_f32_16x16x32_bf16 v[72:75], v[162:165], v[210:213], v[72:75]
	v_mfma_f32_16x16x32_bf16 v[116:119], v[166:169], v[182:185], v[116:119]
	v_mfma_f32_16x16x32_bf16 v[112:115], v[174:177], v[182:185], v[112:115]
	v_mfma_f32_16x16x32_bf16 v[100:103], v[166:169], v[190:193], v[100:103]
	v_mfma_f32_16x16x32_bf16 v[96:99], v[174:177], v[190:193], v[96:99]
	v_mfma_f32_16x16x32_bf16 v[84:87], v[166:169], v[198:201], v[84:87]
	v_mfma_f32_16x16x32_bf16 v[80:83], v[174:177], v[198:201], v[80:83]
	v_mfma_f32_16x16x32_bf16 v[68:71], v[166:169], v[206:209], v[68:71]
	v_mfma_f32_16x16x32_bf16 v[64:67], v[174:177], v[206:209], v[64:67]
	v_mfma_f32_16x16x32_bf16 v[116:119], v[170:173], v[186:189], v[116:119]
	v_mfma_f32_16x16x32_bf16 v[112:115], v[178:181], v[186:189], v[112:115]
	v_mfma_f32_16x16x32_bf16 v[100:103], v[170:173], v[194:197], v[100:103]
	v_mfma_f32_16x16x32_bf16 v[96:99], v[178:181], v[194:197], v[96:99]
	v_mfma_f32_16x16x32_bf16 v[84:87], v[170:173], v[202:205], v[84:87]
	v_mfma_f32_16x16x32_bf16 v[80:83], v[178:181], v[202:205], v[80:83]
	v_mfma_f32_16x16x32_bf16 v[68:71], v[170:173], v[210:213], v[68:71]
	v_mfma_f32_16x16x32_bf16 v[64:67], v[178:181], v[210:213], v[64:67]
	v_mfma_f32_16x16x32_bf16 v[60:63], v[144:147], v[220:223], v[60:63]
	v_mfma_f32_16x16x32_bf16 v[56:59], v[158:161], v[220:223], v[56:59]
	v_mfma_f32_16x16x32_bf16 v[44:47], v[144:147], v[228:231], v[44:47]
	v_mfma_f32_16x16x32_bf16 v[40:43], v[158:161], v[228:231], v[40:43]
	v_mfma_f32_16x16x32_bf16 v[28:31], v[144:147], v[236:239], v[28:31]
	v_mfma_f32_16x16x32_bf16 v[24:27], v[158:161], v[236:239], v[24:27]
	v_mfma_f32_16x16x32_bf16 v[12:15], v[144:147], v[244:247], v[12:15]
	v_mfma_f32_16x16x32_bf16 v[8:11], v[158:161], v[244:247], v[8:11]
	v_mfma_f32_16x16x32_bf16 v[60:63], v[154:157], v[224:227], v[60:63]
	v_mfma_f32_16x16x32_bf16 v[56:59], v[162:165], v[224:227], v[56:59]
	v_mfma_f32_16x16x32_bf16 v[44:47], v[154:157], v[232:235], v[44:47]
	v_mfma_f32_16x16x32_bf16 v[40:43], v[162:165], v[232:235], v[40:43]
	v_mfma_f32_16x16x32_bf16 v[28:31], v[154:157], v[240:243], v[28:31]
	v_mfma_f32_16x16x32_bf16 v[24:27], v[162:165], v[240:243], v[24:27]
	v_mfma_f32_16x16x32_bf16 v[12:15], v[154:157], v[248:251], v[12:15]
	v_mfma_f32_16x16x32_bf16 v[8:11], v[162:165], v[248:251], v[8:11]
	v_mfma_f32_16x16x32_bf16 v[52:55], v[166:169], v[220:223], v[52:55]
	v_mfma_f32_16x16x32_bf16 v[48:51], v[174:177], v[220:223], v[48:51]
	v_mfma_f32_16x16x32_bf16 v[36:39], v[166:169], v[228:231], v[36:39]
	v_mfma_f32_16x16x32_bf16 v[32:35], v[174:177], v[228:231], v[32:35]
	v_mfma_f32_16x16x32_bf16 v[20:23], v[166:169], v[236:239], v[20:23]
	v_mfma_f32_16x16x32_bf16 v[16:19], v[174:177], v[236:239], v[16:19]
	v_mfma_f32_16x16x32_bf16 v[4:7], v[166:169], v[244:247], v[4:7]
	v_mfma_f32_16x16x32_bf16 v[0:3], v[174:177], v[244:247], v[0:3]
	v_mfma_f32_16x16x32_bf16 v[52:55], v[170:173], v[224:227], v[52:55]
	v_mfma_f32_16x16x32_bf16 v[48:51], v[178:181], v[224:227], v[48:51]
	v_mfma_f32_16x16x32_bf16 v[36:39], v[170:173], v[232:235], v[36:39]
	v_mfma_f32_16x16x32_bf16 v[32:35], v[178:181], v[232:235], v[32:35]
	v_mfma_f32_16x16x32_bf16 v[20:23], v[170:173], v[240:243], v[20:23]
	v_mfma_f32_16x16x32_bf16 v[16:19], v[178:181], v[240:243], v[16:19]
	v_mfma_f32_16x16x32_bf16 v[4:7], v[170:173], v[248:251], v[4:7]
	v_mfma_f32_16x16x32_bf16 v[0:3], v[178:181], v[248:251], v[0:3]
	s_waitcnt vmcnt(0)
	s_barrier
	s_add_i32 s56, s56, 2
	s_add_u32 s12, s12, 0x100
	s_addc_u32 s13, s13, 0
	s_add_u32 s54, s54, 0x100
	s_addc_u32 s55, s55, 0
	s_cmp_gt_u32 s56, 13
	s_cbranch_scc0 .LBB0_686
	s_branch .Lk64_done_p4
.Lk64_trail_p4:
	s_sub_u32 vcc_lo, s12, 0x40000
	s_subb_u32 vcc_hi, s13, 0
	s_add_i32 m0, s36, 0xa000
	s_nop 0
	global_load_lds_dwordx4 v130, vcc
	s_add_u32 vcc_lo, vcc_lo, 0x10000
	s_addc_u32 vcc_hi, vcc_hi, 0
	s_add_i32 m0, s36, 0x9000
	s_nop 0
	global_load_lds_dwordx4 v134, vcc
	s_add_u32 vcc_lo, vcc_lo, 0x30000
	s_addc_u32 vcc_hi, vcc_hi, 0
	s_add_i32 m0, s36, 0xe000
	s_nop 0
	global_load_lds_dwordx4 v130, vcc
	s_add_u32 vcc_lo, vcc_lo, 0x10000
	s_addc_u32 vcc_hi, vcc_hi, 0
	s_add_i32 m0, s36, 0xd000
	s_nop 0
	global_load_lds_dwordx4 v134, vcc
	s_add_u32 vcc_lo, s34, 0x0
	s_addc_u32 vcc_hi, s35, 0
	s_mov_b32 m0, s36
	s_nop 0
	global_load_lds_dwordx4 v134, vcc
	s_sub_u32 vcc_lo, vcc_lo, 0x10000
	s_subb_u32 vcc_hi, vcc_hi, 0
	s_sub_i32 m0, s36, 0x1000
	s_nop 0
	global_load_lds_dwordx4 v134, vcc
	s_add_u32 vcc_lo, vcc_lo, 0x50000
	s_addc_u32 vcc_hi, vcc_hi, 0
	s_add_i32 m0, s36, 0x4000
	s_nop 0
	global_load_lds_dwordx4 v134, vcc
	s_sub_u32 vcc_lo, vcc_lo, 0x10000
	s_subb_u32 vcc_hi, vcc_hi, 0
	s_add_i32 m0, s36, 0x3000
	s_nop 0
	global_load_lds_dwordx4 v134, vcc
	ds_read_b128 v[144:147], v151 offset:0
	ds_read_b128 v[154:157], v151 offset:1024
	ds_read_b128 v[158:161], v151 offset:2048
	ds_read_b128 v[162:165], v151 offset:3072
	ds_read_b128 v[166:169], v152 offset:0
	ds_read_b128 v[170:173], v152 offset:1024
	ds_read_b128 v[174:177], v152 offset:2048
	ds_read_b128 v[178:181], v152 offset:3072
	ds_read_b128 v[182:185], v153 offset:0
	ds_read_b128 v[186:189], v153 offset:1024
	ds_read_b128 v[190:193], v153 offset:2048
	ds_read_b128 v[194:197], v153 offset:3072
	ds_read_b128 v[198:201], v153 offset:4096
	ds_read_b128 v[202:205], v153 offset:5120
	ds_read_b128 v[206:209], v153 offset:6144
	ds_read_b128 v[210:213], v153 offset:7168
	ds_read_b128 v[220:223], v153 offset:16384
	ds_read_b128 v[224:227], v153 offset:17408
	ds_read_b128 v[228:231], v153 offset:18432
	ds_read_b128 v[232:235], v153 offset:19456
	ds_read_b128 v[236:239], v153 offset:20480
	ds_read_b128 v[240:243], v153 offset:21504
	ds_read_b128 v[244:247], v153 offset:22528
	ds_read_b128 v[248:251], v153 offset:23552
	s_nop 15
	s_nop 15
	s_waitcnt lgkmcnt(0)
	s_barrier
	v_mfma_f32_16x16x32_bf16 v[124:127], v[144:147], v[182:185], v[124:127]
	v_mfma_f32_16x16x32_bf16 v[120:123], v[158:161], v[182:185], v[120:123]
	v_mfma_f32_16x16x32_bf16 v[108:111], v[144:147], v[190:193], v[108:111]
	v_mfma_f32_16x16x32_bf16 v[104:107], v[158:161], v[190:193], v[104:107]
	v_mfma_f32_16x16x32_bf16 v[92:95], v[144:147], v[198:201], v[92:95]
	v_mfma_f32_16x16x32_bf16 v[88:91], v[158:161], v[198:201], v[88:91]
	v_mfma_f32_16x16x32_bf16 v[76:79], v[144:147], v[206:209], v[76:79]
	v_mfma_f32_16x16x32_bf16 v[72:75], v[158:161], v[206:209], v[72:75]
	v_mfma_f32_16x16x32_bf16 v[124:127], v[154:157], v[186:189], v[124:127]
	v_mfma_f32_16x16x32_bf16 v[120:123], v[162:165], v[186:189], v[120:123]
	v_mfma_f32_16x16x32_bf16 v[108:111], v[154:157], v[194:197], v[108:111]
	v_mfma_f32_16x16x32_bf16 v[104:107], v[162:165], v[194:197], v[104:107]
	v_mfma_f32_16x16x32_bf16 v[92:95], v[154:157], v[202:205], v[92:95]
	v_mfma_f32_16x16x32_bf16 v[88:91], v[162:165], v[202:205], v[88:91]
	v_mfma_f32_16x16x32_bf16 v[76:79], v[154:157], v[210:213], v[76:79]
	v_mfma_f32_16x16x32_bf16 v[72:75], v[162:165], v[210:213], v[72:75]
	v_mfma_f32_16x16x32_bf16 v[116:119], v[166:169], v[182:185], v[116:119]
	v_mfma_f32_16x16x32_bf16 v[112:115], v[174:177], v[182:185], v[112:115]
	v_mfma_f32_16x16x32_bf16 v[100:103], v[166:169], v[190:193], v[100:103]
	v_mfma_f32_16x16x32_bf16 v[96:99], v[174:177], v[190:193], v[96:99]
	v_mfma_f32_16x16x32_bf16 v[84:87], v[166:169], v[198:201], v[84:87]
	v_mfma_f32_16x16x32_bf16 v[80:83], v[174:177], v[198:201], v[80:83]
	v_mfma_f32_16x16x32_bf16 v[68:71], v[166:169], v[206:209], v[68:71]
	v_mfma_f32_16x16x32_bf16 v[64:67], v[174:177], v[206:209], v[64:67]
	v_mfma_f32_16x16x32_bf16 v[116:119], v[170:173], v[186:189], v[116:119]
	v_mfma_f32_16x16x32_bf16 v[112:115], v[178:181], v[186:189], v[112:115]
	v_mfma_f32_16x16x32_bf16 v[100:103], v[170:173], v[194:197], v[100:103]
	v_mfma_f32_16x16x32_bf16 v[96:99], v[178:181], v[194:197], v[96:99]
	v_mfma_f32_16x16x32_bf16 v[84:87], v[170:173], v[202:205], v[84:87]
	v_mfma_f32_16x16x32_bf16 v[80:83], v[178:181], v[202:205], v[80:83]
	v_mfma_f32_16x16x32_bf16 v[68:71], v[170:173], v[210:213], v[68:71]
	v_mfma_f32_16x16x32_bf16 v[64:67], v[178:181], v[210:213], v[64:67]
	v_mfma_f32_16x16x32_bf16 v[60:63], v[144:147], v[220:223], v[60:63]
	v_mfma_f32_16x16x32_bf16 v[56:59], v[158:161], v[220:223], v[56:59]
	v_mfma_f32_16x16x32_bf16 v[44:47], v[144:147], v[228:231], v[44:47]
	v_mfma_f32_16x16x32_bf16 v[40:43], v[158:161], v[228:231], v[40:43]
	v_mfma_f32_16x16x32_bf16 v[28:31], v[144:147], v[236:239], v[28:31]
	v_mfma_f32_16x16x32_bf16 v[24:27], v[158:161], v[236:239], v[24:27]
	v_mfma_f32_16x16x32_bf16 v[12:15], v[144:147], v[244:247], v[12:15]
	v_mfma_f32_16x16x32_bf16 v[8:11], v[158:161], v[244:247], v[8:11]
	v_mfma_f32_16x16x32_bf16 v[60:63], v[154:157], v[224:227], v[60:63]
	v_mfma_f32_16x16x32_bf16 v[56:59], v[162:165], v[224:227], v[56:59]
	v_mfma_f32_16x16x32_bf16 v[44:47], v[154:157], v[232:235], v[44:47]
	v_mfma_f32_16x16x32_bf16 v[40:43], v[162:165], v[232:235], v[40:43]
	v_mfma_f32_16x16x32_bf16 v[28:31], v[154:157], v[240:243], v[28:31]
	v_mfma_f32_16x16x32_bf16 v[24:27], v[162:165], v[240:243], v[24:27]
	v_mfma_f32_16x16x32_bf16 v[12:15], v[154:157], v[248:251], v[12:15]
	v_mfma_f32_16x16x32_bf16 v[8:11], v[162:165], v[248:251], v[8:11]
	v_mfma_f32_16x16x32_bf16 v[52:55], v[166:169], v[220:223], v[52:55]
	v_mfma_f32_16x16x32_bf16 v[48:51], v[174:177], v[220:223], v[48:51]
	v_mfma_f32_16x16x32_bf16 v[36:39], v[166:169], v[228:231], v[36:39]
	v_mfma_f32_16x16x32_bf16 v[32:35], v[174:177], v[228:231], v[32:35]
	v_mfma_f32_16x16x32_bf16 v[20:23], v[166:169], v[236:239], v[20:23]
	v_mfma_f32_16x16x32_bf16 v[16:19], v[174:177], v[236:239], v[16:19]
	v_mfma_f32_16x16x32_bf16 v[4:7], v[166:169], v[244:247], v[4:7]
	v_mfma_f32_16x16x32_bf16 v[0:3], v[174:177], v[244:247], v[0:3]
	v_mfma_f32_16x16x32_bf16 v[52:55], v[170:173], v[224:227], v[52:55]
	v_mfma_f32_16x16x32_bf16 v[48:51], v[178:181], v[224:227], v[48:51]
	v_mfma_f32_16x16x32_bf16 v[36:39], v[170:173], v[232:235], v[36:39]
	v_mfma_f32_16x16x32_bf16 v[32:35], v[178:181], v[232:235], v[32:35]
	v_mfma_f32_16x16x32_bf16 v[20:23], v[170:173], v[240:243], v[20:23]
	v_mfma_f32_16x16x32_bf16 v[16:19], v[178:181], v[240:243], v[16:19]
	v_mfma_f32_16x16x32_bf16 v[4:7], v[170:173], v[248:251], v[4:7]
	v_mfma_f32_16x16x32_bf16 v[0:3], v[178:181], v[248:251], v[0:3]
	s_waitcnt vmcnt(0)
	s_barrier
	s_add_u32 vcc_lo, s34, 0x0
	s_addc_u32 vcc_hi, s35, 0
	s_add_i32 m0, s36, 0x2000
	s_nop 0
	global_load_lds_dwordx4 v130, vcc
	s_add_u32 vcc_lo, vcc_lo, 0x10000
	s_addc_u32 vcc_hi, vcc_hi, 0
	s_add_i32 m0, s36, 0x1000
	s_nop 0
	global_load_lds_dwordx4 v134, vcc
	s_add_u32 vcc_lo, vcc_lo, 0x30000
	s_addc_u32 vcc_hi, vcc_hi, 0
	s_add_i32 m0, s36, 0x6000
	s_nop 0
	global_load_lds_dwordx4 v130, vcc
	s_add_u32 vcc_lo, vcc_lo, 0x10000
	s_addc_u32 vcc_hi, vcc_hi, 0
	s_add_i32 m0, s36, 0x5000
	s_nop 0
	global_load_lds_dwordx4 v134, vcc
	s_add_u32 vcc_lo, s34, 0x80
	s_addc_u32 vcc_hi, s35, 0
	s_add_i32 m0, s36, 0x8000
	s_nop 0
	global_load_lds_dwordx4 v134, vcc
	s_sub_u32 vcc_lo, vcc_lo, 0x10000
	s_subb_u32 vcc_hi, vcc_hi, 0
	s_add_i32 m0, s36, 0x7000
	s_nop 0
	global_load_lds_dwordx4 v134, vcc
	s_add_u32 vcc_lo, vcc_lo, 0x50000
	s_addc_u32 vcc_hi, vcc_hi, 0
	s_add_i32 m0, s36, 0xc000
	s_nop 0
	global_load_lds_dwordx4 v134, vcc
	s_sub_u32 vcc_lo, vcc_lo, 0x10000
	s_subb_u32 vcc_hi, vcc_hi, 0
	s_add_i32 m0, s36, 0xb000
	s_nop 0
	global_load_lds_dwordx4 v134, vcc
	ds_read_b128 v[144:147], v151 offset:32768
	ds_read_b128 v[154:157], v151 offset:33792
	ds_read_b128 v[158:161], v151 offset:34816
	ds_read_b128 v[162:165], v151 offset:35840
	ds_read_b128 v[166:169], v152 offset:32768
	ds_read_b128 v[170:173], v152 offset:33792
	ds_read_b128 v[174:177], v152 offset:34816
	ds_read_b128 v[178:181], v152 offset:35840
	ds_read_b128 v[182:185], v153 offset:32768
	ds_read_b128 v[186:189], v153 offset:33792
	ds_read_b128 v[190:193], v153 offset:34816
	ds_read_b128 v[194:197], v153 offset:35840
	ds_read_b128 v[198:201], v153 offset:36864
	ds_read_b128 v[202:205], v153 offset:37888
	ds_read_b128 v[206:209], v153 offset:38912
	ds_read_b128 v[210:213], v153 offset:39936
	ds_read_b128 v[220:223], v153 offset:49152
	ds_read_b128 v[224:227], v153 offset:50176
	ds_read_b128 v[228:231], v153 offset:51200
	ds_read_b128 v[232:235], v153 offset:52224
	ds_read_b128 v[236:239], v153 offset:53248
	ds_read_b128 v[240:243], v153 offset:54272
	ds_read_b128 v[244:247], v153 offset:55296
	ds_read_b128 v[248:251], v153 offset:56320
	s_nop 15
	s_nop 15
	s_waitcnt lgkmcnt(0)
	s_barrier
	v_mfma_f32_16x16x32_bf16 v[124:127], v[144:147], v[182:185], v[124:127]
	v_mfma_f32_16x16x32_bf16 v[120:123], v[158:161], v[182:185], v[120:123]
	v_mfma_f32_16x16x32_bf16 v[108:111], v[144:147], v[190:193], v[108:111]
	v_mfma_f32_16x16x32_bf16 v[104:107], v[158:161], v[190:193], v[104:107]
	v_mfma_f32_16x16x32_bf16 v[92:95], v[144:147], v[198:201], v[92:95]
	v_mfma_f32_16x16x32_bf16 v[88:91], v[158:161], v[198:201], v[88:91]
	v_mfma_f32_16x16x32_bf16 v[76:79], v[144:147], v[206:209], v[76:79]
	v_mfma_f32_16x16x32_bf16 v[72:75], v[158:161], v[206:209], v[72:75]
	v_mfma_f32_16x16x32_bf16 v[124:127], v[154:157], v[186:189], v[124:127]
	v_mfma_f32_16x16x32_bf16 v[120:123], v[162:165], v[186:189], v[120:123]
	v_mfma_f32_16x16x32_bf16 v[108:111], v[154:157], v[194:197], v[108:111]
	v_mfma_f32_16x16x32_bf16 v[104:107], v[162:165], v[194:197], v[104:107]
	v_mfma_f32_16x16x32_bf16 v[92:95], v[154:157], v[202:205], v[92:95]
	v_mfma_f32_16x16x32_bf16 v[88:91], v[162:165], v[202:205], v[88:91]
	v_mfma_f32_16x16x32_bf16 v[76:79], v[154:157], v[210:213], v[76:79]
	v_mfma_f32_16x16x32_bf16 v[72:75], v[162:165], v[210:213], v[72:75]
	v_mfma_f32_16x16x32_bf16 v[116:119], v[166:169], v[182:185], v[116:119]
	v_mfma_f32_16x16x32_bf16 v[112:115], v[174:177], v[182:185], v[112:115]
	v_mfma_f32_16x16x32_bf16 v[100:103], v[166:169], v[190:193], v[100:103]
	v_mfma_f32_16x16x32_bf16 v[96:99], v[174:177], v[190:193], v[96:99]
	v_mfma_f32_16x16x32_bf16 v[84:87], v[166:169], v[198:201], v[84:87]
	v_mfma_f32_16x16x32_bf16 v[80:83], v[174:177], v[198:201], v[80:83]
	v_mfma_f32_16x16x32_bf16 v[68:71], v[166:169], v[206:209], v[68:71]
	v_mfma_f32_16x16x32_bf16 v[64:67], v[174:177], v[206:209], v[64:67]
	v_mfma_f32_16x16x32_bf16 v[116:119], v[170:173], v[186:189], v[116:119]
	v_mfma_f32_16x16x32_bf16 v[112:115], v[178:181], v[186:189], v[112:115]
	v_mfma_f32_16x16x32_bf16 v[100:103], v[170:173], v[194:197], v[100:103]
	v_mfma_f32_16x16x32_bf16 v[96:99], v[178:181], v[194:197], v[96:99]
	v_mfma_f32_16x16x32_bf16 v[84:87], v[170:173], v[202:205], v[84:87]
	v_mfma_f32_16x16x32_bf16 v[80:83], v[178:181], v[202:205], v[80:83]
	v_mfma_f32_16x16x32_bf16 v[68:71], v[170:173], v[210:213], v[68:71]
	v_mfma_f32_16x16x32_bf16 v[64:67], v[178:181], v[210:213], v[64:67]
	v_mfma_f32_16x16x32_bf16 v[60:63], v[144:147], v[220:223], v[60:63]
	v_mfma_f32_16x16x32_bf16 v[56:59], v[158:161], v[220:223], v[56:59]
	v_mfma_f32_16x16x32_bf16 v[44:47], v[144:147], v[228:231], v[44:47]
	v_mfma_f32_16x16x32_bf16 v[40:43], v[158:161], v[228:231], v[40:43]
	v_mfma_f32_16x16x32_bf16 v[28:31], v[144:147], v[236:239], v[28:31]
	v_mfma_f32_16x16x32_bf16 v[24:27], v[158:161], v[236:239], v[24:27]
	v_mfma_f32_16x16x32_bf16 v[12:15], v[144:147], v[244:247], v[12:15]
	v_mfma_f32_16x16x32_bf16 v[8:11], v[158:161], v[244:247], v[8:11]
	v_mfma_f32_16x16x32_bf16 v[60:63], v[154:157], v[224:227], v[60:63]
	v_mfma_f32_16x16x32_bf16 v[56:59], v[162:165], v[224:227], v[56:59]
	v_mfma_f32_16x16x32_bf16 v[44:47], v[154:157], v[232:235], v[44:47]
	v_mfma_f32_16x16x32_bf16 v[40:43], v[162:165], v[232:235], v[40:43]
	v_mfma_f32_16x16x32_bf16 v[28:31], v[154:157], v[240:243], v[28:31]
	v_mfma_f32_16x16x32_bf16 v[24:27], v[162:165], v[240:243], v[24:27]
	v_mfma_f32_16x16x32_bf16 v[12:15], v[154:157], v[248:251], v[12:15]
	v_mfma_f32_16x16x32_bf16 v[8:11], v[162:165], v[248:251], v[8:11]
	v_mfma_f32_16x16x32_bf16 v[52:55], v[166:169], v[220:223], v[52:55]
	v_mfma_f32_16x16x32_bf16 v[48:51], v[174:177], v[220:223], v[48:51]
	v_mfma_f32_16x16x32_bf16 v[36:39], v[166:169], v[228:231], v[36:39]
	v_mfma_f32_16x16x32_bf16 v[32:35], v[174:177], v[228:231], v[32:35]
	v_mfma_f32_16x16x32_bf16 v[20:23], v[166:169], v[236:239], v[20:23]
	v_mfma_f32_16x16x32_bf16 v[16:19], v[174:177], v[236:239], v[16:19]
	v_mfma_f32_16x16x32_bf16 v[4:7], v[166:169], v[244:247], v[4:7]
	v_mfma_f32_16x16x32_bf16 v[0:3], v[174:177], v[244:247], v[0:3]
	v_mfma_f32_16x16x32_bf16 v[52:55], v[170:173], v[224:227], v[52:55]
	v_mfma_f32_16x16x32_bf16 v[48:51], v[178:181], v[224:227], v[48:51]
	v_mfma_f32_16x16x32_bf16 v[36:39], v[170:173], v[232:235], v[36:39]
	v_mfma_f32_16x16x32_bf16 v[32:35], v[178:181], v[232:235], v[32:35]
	v_mfma_f32_16x16x32_bf16 v[20:23], v[170:173], v[240:243], v[20:23]
	v_mfma_f32_16x16x32_bf16 v[16:19], v[178:181], v[240:243], v[16:19]
	v_mfma_f32_16x16x32_bf16 v[4:7], v[170:173], v[248:251], v[4:7]
	v_mfma_f32_16x16x32_bf16 v[0:3], v[178:181], v[248:251], v[0:3]
	s_waitcnt vmcnt(0)
	s_barrier
	s_add_i32 s56, s56, 2
	s_add_u32 s12, s12, 0x100
	s_addc_u32 s13, s13, 0
	s_add_u32 s54, s54, 0x100
	s_addc_u32 s55, s55, 0
	s_cmp_gt_u32 s56, 13
	s_cbranch_scc0 .LBB0_686

.LBB0_761:
	s_add_u32 s36, s34, 0xfff80080
	s_addc_u32 s37, s35, -1
	s_cmp_eq_u32 s58, 28
	s_cselect_b32 s43, s23, s37
	s_cselect_b32 s42, s29, s36
	s_cselect_b32 s37, s13, s57
	s_cselect_b32 s36, s31, s56
	s_and_b64 vcc, exec, s[10:11]
	s_cbranch_vccz .Lk64_trail_p5
	s_setprio 1
	s_sub_u32 vcc_lo, s56, 0x80
	s_subb_u32 vcc_hi, s57, 0
	s_add_i32 m0, s44, 0x18000
	s_nop 0
	global_load_lds_dwordx4 v130, vcc
	s_add_i32 m0, s44, 0x1a000
	s_nop 0
	global_load_lds_dwordx4 v134, vcc
	s_add_u32 vcc_lo, vcc_lo, 0x20000
	s_addc_u32 vcc_hi, vcc_hi, 0
	s_add_i32 m0, s44, 0x19000
	s_nop 0
	global_load_lds_dwordx4 v130, vcc
	s_add_i32 m0, s44, 0x1b000
	s_nop 0
	global_load_lds_dwordx4 v134, vcc
	s_add_u32 vcc_lo, vcc_lo, 0x60000
	s_addc_u32 vcc_hi, vcc_hi, 0
	s_add_i32 m0, s44, 0x1c000
	s_nop 0
	global_load_lds_dwordx4 v130, vcc
	s_add_i32 m0, s44, 0x1e000
	s_nop 0
	global_load_lds_dwordx4 v134, vcc
	s_add_u32 vcc_lo, vcc_lo, 0x20000
	s_addc_u32 vcc_hi, vcc_hi, 0
	s_add_i32 m0, s44, 0x1d000
	s_nop 0
	global_load_lds_dwordx4 v130, vcc
	s_add_i32 m0, s44, 0x1f000
	s_nop 0
	global_load_lds_dwordx4 v134, vcc
	ds_read_b128 v[144:147], v153 offset:0
	ds_read_b128 v[158:161], v153 offset:1024
	ds_read_b128 v[162:165], v153 offset:2048
	ds_read_b128 v[166:169], v153 offset:3072
	ds_read_b128 v[170:173], v154 offset:0
	ds_read_b128 v[174:177], v154 offset:1024
	ds_read_b128 v[178:181], v154 offset:2048
	ds_read_b128 v[182:185], v154 offset:3072
	ds_read_b128 v[186:189], v155 offset:0
	ds_read_b128 v[190:193], v155 offset:1024
	ds_read_b128 v[194:197], v155 offset:2048
	ds_read_b128 v[198:201], v155 offset:3072
	ds_read_b128 v[202:205], v155 offset:4096
	ds_read_b128 v[206:209], v155 offset:5120
	ds_read_b128 v[210:213], v155 offset:6144
	ds_read_b128 v[214:217], v155 offset:7168
	ds_read_b128 v[220:223], v155 offset:16384
	ds_read_b128 v[224:227], v155 offset:17408
	ds_read_b128 v[228:231], v155 offset:18432
	ds_read_b128 v[232:235], v155 offset:19456
	ds_read_b128 v[236:239], v155 offset:20480
	ds_read_b128 v[240:243], v155 offset:21504
	ds_read_b128 v[244:247], v155 offset:22528
	ds_read_b128 v[248:251], v155 offset:23552
	s_nop 15
	s_nop 15
	s_waitcnt lgkmcnt(0)
	s_barrier
	v_mfma_f32_16x16x32_bf16 v[124:127], v[144:147], v[186:189], v[124:127]
	v_mfma_f32_16x16x32_bf16 v[120:123], v[162:165], v[186:189], v[120:123]
	v_mfma_f32_16x16x32_bf16 v[108:111], v[144:147], v[194:197], v[108:111]
	v_mfma_f32_16x16x32_bf16 v[104:107], v[162:165], v[194:197], v[104:107]
	v_mfma_f32_16x16x32_bf16 v[92:95], v[144:147], v[202:205], v[92:95]
	v_mfma_f32_16x16x32_bf16 v[88:91], v[162:165], v[202:205], v[88:91]
	v_mfma_f32_16x16x32_bf16 v[76:79], v[144:147], v[210:213], v[76:79]
	v_mfma_f32_16x16x32_bf16 v[72:75], v[162:165], v[210:213], v[72:75]
	v_mfma_f32_16x16x32_bf16 v[124:127], v[158:161], v[190:193], v[124:127]
	v_mfma_f32_16x16x32_bf16 v[120:123], v[166:169], v[190:193], v[120:123]
	v_mfma_f32_16x16x32_bf16 v[108:111], v[158:161], v[198:201], v[108:111]
	v_mfma_f32_16x16x32_bf16 v[104:107], v[166:169], v[198:201], v[104:107]
	v_mfma_f32_16x16x32_bf16 v[92:95], v[158:161], v[206:209], v[92:95]
	v_mfma_f32_16x16x32_bf16 v[88:91], v[166:169], v[206:209], v[88:91]
	v_mfma_f32_16x16x32_bf16 v[76:79], v[158:161], v[214:217], v[76:79]
	v_mfma_f32_16x16x32_bf16 v[72:75], v[166:169], v[214:217], v[72:75]
	v_mfma_f32_16x16x32_bf16 v[116:119], v[170:173], v[186:189], v[116:119]
	v_mfma_f32_16x16x32_bf16 v[112:115], v[178:181], v[186:189], v[112:115]
	v_mfma_f32_16x16x32_bf16 v[100:103], v[170:173], v[194:197], v[100:103]
	v_mfma_f32_16x16x32_bf16 v[96:99], v[178:181], v[194:197], v[96:99]
	v_mfma_f32_16x16x32_bf16 v[84:87], v[170:173], v[202:205], v[84:87]
	v_mfma_f32_16x16x32_bf16 v[80:83], v[178:181], v[202:205], v[80:83]
	v_mfma_f32_16x16x32_bf16 v[68:71], v[170:173], v[210:213], v[68:71]
	v_mfma_f32_16x16x32_bf16 v[64:67], v[178:181], v[210:213], v[64:67]
	v_mfma_f32_16x16x32_bf16 v[116:119], v[174:177], v[190:193], v[116:119]
	v_mfma_f32_16x16x32_bf16 v[112:115], v[182:185], v[190:193], v[112:115]
	v_mfma_f32_16x16x32_bf16 v[100:103], v[174:177], v[198:201], v[100:103]
	v_mfma_f32_16x16x32_bf16 v[96:99], v[182:185], v[198:201], v[96:99]
	v_mfma_f32_16x16x32_bf16 v[84:87], v[174:177], v[206:209], v[84:87]
	v_mfma_f32_16x16x32_bf16 v[80:83], v[182:185], v[206:209], v[80:83]
	v_mfma_f32_16x16x32_bf16 v[68:71], v[174:177], v[214:217], v[68:71]
	v_mfma_f32_16x16x32_bf16 v[64:67], v[182:185], v[214:217], v[64:67]
	v_mfma_f32_16x16x32_bf16 v[60:63], v[144:147], v[220:223], v[60:63]
	v_mfma_f32_16x16x32_bf16 v[56:59], v[162:165], v[220:223], v[56:59]
	v_mfma_f32_16x16x32_bf16 v[44:47], v[144:147], v[228:231], v[44:47]
	v_mfma_f32_16x16x32_bf16 v[40:43], v[162:165], v[228:231], v[40:43]
	v_mfma_f32_16x16x32_bf16 v[28:31], v[144:147], v[236:239], v[28:31]
	v_mfma_f32_16x16x32_bf16 v[24:27], v[162:165], v[236:239], v[24:27]
	v_mfma_f32_16x16x32_bf16 v[12:15], v[144:147], v[244:247], v[12:15]
	v_mfma_f32_16x16x32_bf16 v[8:11], v[162:165], v[244:247], v[8:11]
	v_mfma_f32_16x16x32_bf16 v[60:63], v[158:161], v[224:227], v[60:63]
	v_mfma_f32_16x16x32_bf16 v[56:59], v[166:169], v[224:227], v[56:59]
	v_mfma_f32_16x16x32_bf16 v[44:47], v[158:161], v[232:235], v[44:47]
	v_mfma_f32_16x16x32_bf16 v[40:43], v[166:169], v[232:235], v[40:43]
	v_mfma_f32_16x16x32_bf16 v[28:31], v[158:161], v[240:243], v[28:31]
	v_mfma_f32_16x16x32_bf16 v[24:27], v[166:169], v[240:243], v[24:27]
	v_mfma_f32_16x16x32_bf16 v[12:15], v[158:161], v[248:251], v[12:15]
	v_mfma_f32_16x16x32_bf16 v[8:11], v[166:169], v[248:251], v[8:11]
	v_mfma_f32_16x16x32_bf16 v[52:55], v[170:173], v[220:223], v[52:55]
	v_mfma_f32_16x16x32_bf16 v[48:51], v[178:181], v[220:223], v[48:51]
	v_mfma_f32_16x16x32_bf16 v[36:39], v[170:173], v[228:231], v[36:39]
	v_mfma_f32_16x16x32_bf16 v[32:35], v[178:181], v[228:231], v[32:35]
	v_mfma_f32_16x16x32_bf16 v[20:23], v[170:173], v[236:239], v[20:23]
	v_mfma_f32_16x16x32_bf16 v[16:19], v[178:181], v[236:239], v[16:19]
	v_mfma_f32_16x16x32_bf16 v[4:7], v[170:173], v[244:247], v[4:7]
	v_mfma_f32_16x16x32_bf16 v[0:3], v[178:181], v[244:247], v[0:3]
	v_mfma_f32_16x16x32_bf16 v[52:55], v[174:177], v[224:227], v[52:55]
	v_mfma_f32_16x16x32_bf16 v[48:51], v[182:185], v[224:227], v[48:51]
	v_mfma_f32_16x16x32_bf16 v[36:39], v[174:177], v[232:235], v[36:39]
	v_mfma_f32_16x16x32_bf16 v[32:35], v[182:185], v[232:235], v[32:35]
	v_mfma_f32_16x16x32_bf16 v[20:23], v[174:177], v[240:243], v[20:23]
	v_mfma_f32_16x16x32_bf16 v[16:19], v[182:185], v[240:243], v[16:19]
	v_mfma_f32_16x16x32_bf16 v[4:7], v[174:177], v[248:251], v[4:7]
	v_mfma_f32_16x16x32_bf16 v[0:3], v[182:185], v[248:251], v[0:3]
	s_waitcnt vmcnt(0)
	s_barrier
	s_add_u32 vcc_lo, s36, 0x0
	s_addc_u32 vcc_hi, s37, 0
	s_add_i32 m0, s44, 0x10000
	s_nop 0
	global_load_lds_dwordx4 v130, vcc
	s_add_i32 m0, s44, 0x12000
	s_nop 0
	global_load_lds_dwordx4 v134, vcc
	s_add_u32 vcc_lo, vcc_lo, 0x20000
	s_addc_u32 vcc_hi, vcc_hi, 0
	s_add_i32 m0, s44, 0x11000
	s_nop 0
	global_load_lds_dwordx4 v130, vcc
	s_add_i32 m0, s44, 0x13000
	s_nop 0
	global_load_lds_dwordx4 v134, vcc
	s_add_u32 vcc_lo, vcc_lo, 0x60000
	s_addc_u32 vcc_hi, vcc_hi, 0
	s_add_i32 m0, s44, 0x14000
	s_nop 0
	global_load_lds_dwordx4 v130, vcc
	s_add_i32 m0, s44, 0x16000
	s_nop 0
	global_load_lds_dwordx4 v134, vcc
	s_add_u32 vcc_lo, vcc_lo, 0x20000
	s_addc_u32 vcc_hi, vcc_hi, 0
	s_add_i32 m0, s44, 0x15000
	s_nop 0
	global_load_lds_dwordx4 v130, vcc
	s_add_i32 m0, s44, 0x17000
	s_nop 0
	global_load_lds_dwordx4 v134, vcc
	ds_read_b128 v[144:147], v153 offset:32768
	ds_read_b128 v[158:161], v153 offset:33792
	ds_read_b128 v[162:165], v153 offset:34816
	ds_read_b128 v[166:169], v153 offset:35840
	ds_read_b128 v[170:173], v154 offset:32768
	ds_read_b128 v[174:177], v154 offset:33792
	ds_read_b128 v[178:181], v154 offset:34816
	ds_read_b128 v[182:185], v154 offset:35840
	ds_read_b128 v[186:189], v155 offset:32768
	ds_read_b128 v[190:193], v155 offset:33792
	ds_read_b128 v[194:197], v155 offset:34816
	ds_read_b128 v[198:201], v155 offset:35840
	ds_read_b128 v[202:205], v155 offset:36864
	ds_read_b128 v[206:209], v155 offset:37888
	ds_read_b128 v[210:213], v155 offset:38912
	ds_read_b128 v[214:217], v155 offset:39936
	ds_read_b128 v[220:223], v155 offset:49152
	ds_read_b128 v[224:227], v155 offset:50176
	ds_read_b128 v[228:231], v155 offset:51200
	ds_read_b128 v[232:235], v155 offset:52224
	ds_read_b128 v[236:239], v155 offset:53248
	ds_read_b128 v[240:243], v155 offset:54272
	ds_read_b128 v[244:247], v155 offset:55296
	ds_read_b128 v[248:251], v155 offset:56320
	s_nop 15
	s_nop 15
	s_waitcnt lgkmcnt(0)
	s_barrier
	v_mfma_f32_16x16x32_bf16 v[124:127], v[144:147], v[186:189], v[124:127]
	v_mfma_f32_16x16x32_bf16 v[120:123], v[162:165], v[186:189], v[120:123]
	v_mfma_f32_16x16x32_bf16 v[108:111], v[144:147], v[194:197], v[108:111]
	v_mfma_f32_16x16x32_bf16 v[104:107], v[162:165], v[194:197], v[104:107]
	v_mfma_f32_16x16x32_bf16 v[92:95], v[144:147], v[202:205], v[92:95]
	v_mfma_f32_16x16x32_bf16 v[88:91], v[162:165], v[202:205], v[88:91]
	v_mfma_f32_16x16x32_bf16 v[76:79], v[144:147], v[210:213], v[76:79]
	v_mfma_f32_16x16x32_bf16 v[72:75], v[162:165], v[210:213], v[72:75]
	v_mfma_f32_16x16x32_bf16 v[124:127], v[158:161], v[190:193], v[124:127]
	v_mfma_f32_16x16x32_bf16 v[120:123], v[166:169], v[190:193], v[120:123]
	v_mfma_f32_16x16x32_bf16 v[108:111], v[158:161], v[198:201], v[108:111]
	v_mfma_f32_16x16x32_bf16 v[104:107], v[166:169], v[198:201], v[104:107]
	v_mfma_f32_16x16x32_bf16 v[92:95], v[158:161], v[206:209], v[92:95]
	v_mfma_f32_16x16x32_bf16 v[88:91], v[166:169], v[206:209], v[88:91]
	v_mfma_f32_16x16x32_bf16 v[76:79], v[158:161], v[214:217], v[76:79]
	v_mfma_f32_16x16x32_bf16 v[72:75], v[166:169], v[214:217], v[72:75]
	v_mfma_f32_16x16x32_bf16 v[116:119], v[170:173], v[186:189], v[116:119]
	v_mfma_f32_16x16x32_bf16 v[112:115], v[178:181], v[186:189], v[112:115]
	v_mfma_f32_16x16x32_bf16 v[100:103], v[170:173], v[194:197], v[100:103]
	v_mfma_f32_16x16x32_bf16 v[96:99], v[178:181], v[194:197], v[96:99]
	v_mfma_f32_16x16x32_bf16 v[84:87], v[170:173], v[202:205], v[84:87]
	v_mfma_f32_16x16x32_bf16 v[80:83], v[178:181], v[202:205], v[80:83]
	v_mfma_f32_16x16x32_bf16 v[68:71], v[170:173], v[210:213], v[68:71]
	v_mfma_f32_16x16x32_bf16 v[64:67], v[178:181], v[210:213], v[64:67]
	v_mfma_f32_16x16x32_bf16 v[116:119], v[174:177], v[190:193], v[116:119]
	v_mfma_f32_16x16x32_bf16 v[112:115], v[182:185], v[190:193], v[112:115]
	v_mfma_f32_16x16x32_bf16 v[100:103], v[174:177], v[198:201], v[100:103]
	v_mfma_f32_16x16x32_bf16 v[96:99], v[182:185], v[198:201], v[96:99]
	v_mfma_f32_16x16x32_bf16 v[84:87], v[174:177], v[206:209], v[84:87]
	v_mfma_f32_16x16x32_bf16 v[80:83], v[182:185], v[206:209], v[80:83]
	v_mfma_f32_16x16x32_bf16 v[68:71], v[174:177], v[214:217], v[68:71]
	v_mfma_f32_16x16x32_bf16 v[64:67], v[182:185], v[214:217], v[64:67]
	v_mfma_f32_16x16x32_bf16 v[60:63], v[144:147], v[220:223], v[60:63]
	v_mfma_f32_16x16x32_bf16 v[56:59], v[162:165], v[220:223], v[56:59]
	v_mfma_f32_16x16x32_bf16 v[44:47], v[144:147], v[228:231], v[44:47]
	v_mfma_f32_16x16x32_bf16 v[40:43], v[162:165], v[228:231], v[40:43]
	v_mfma_f32_16x16x32_bf16 v[28:31], v[144:147], v[236:239], v[28:31]
	v_mfma_f32_16x16x32_bf16 v[24:27], v[162:165], v[236:239], v[24:27]
	v_mfma_f32_16x16x32_bf16 v[12:15], v[144:147], v[244:247], v[12:15]
	v_mfma_f32_16x16x32_bf16 v[8:11], v[162:165], v[244:247], v[8:11]
	v_mfma_f32_16x16x32_bf16 v[60:63], v[158:161], v[224:227], v[60:63]
	v_mfma_f32_16x16x32_bf16 v[56:59], v[166:169], v[224:227], v[56:59]
	v_mfma_f32_16x16x32_bf16 v[44:47], v[158:161], v[232:235], v[44:47]
	v_mfma_f32_16x16x32_bf16 v[40:43], v[166:169], v[232:235], v[40:43]
	v_mfma_f32_16x16x32_bf16 v[28:31], v[158:161], v[240:243], v[28:31]
	v_mfma_f32_16x16x32_bf16 v[24:27], v[166:169], v[240:243], v[24:27]
	v_mfma_f32_16x16x32_bf16 v[12:15], v[158:161], v[248:251], v[12:15]
	v_mfma_f32_16x16x32_bf16 v[8:11], v[166:169], v[248:251], v[8:11]
	v_mfma_f32_16x16x32_bf16 v[52:55], v[170:173], v[220:223], v[52:55]
	v_mfma_f32_16x16x32_bf16 v[48:51], v[178:181], v[220:223], v[48:51]
	v_mfma_f32_16x16x32_bf16 v[36:39], v[170:173], v[228:231], v[36:39]
	v_mfma_f32_16x16x32_bf16 v[32:35], v[178:181], v[228:231], v[32:35]
	v_mfma_f32_16x16x32_bf16 v[20:23], v[170:173], v[236:239], v[20:23]
	v_mfma_f32_16x16x32_bf16 v[16:19], v[178:181], v[236:239], v[16:19]
	v_mfma_f32_16x16x32_bf16 v[4:7], v[170:173], v[244:247], v[4:7]
	v_mfma_f32_16x16x32_bf16 v[0:3], v[178:181], v[244:247], v[0:3]
	v_mfma_f32_16x16x32_bf16 v[52:55], v[174:177], v[224:227], v[52:55]
	v_mfma_f32_16x16x32_bf16 v[48:51], v[182:185], v[224:227], v[48:51]
	v_mfma_f32_16x16x32_bf16 v[36:39], v[174:177], v[232:235], v[36:39]
	v_mfma_f32_16x16x32_bf16 v[32:35], v[182:185], v[232:235], v[32:35]
	v_mfma_f32_16x16x32_bf16 v[20:23], v[174:177], v[240:243], v[20:23]
	v_mfma_f32_16x16x32_bf16 v[16:19], v[182:185], v[240:243], v[16:19]
	v_mfma_f32_16x16x32_bf16 v[4:7], v[174:177], v[248:251], v[4:7]
	v_mfma_f32_16x16x32_bf16 v[0:3], v[182:185], v[248:251], v[0:3]
	s_waitcnt vmcnt(0)
	s_barrier
	s_add_i32 s58, s58, 2
	s_add_u32 s34, s34, 0x100
	s_addc_u32 s35, s35, 0
	s_add_u32 s56, s56, 0x100
	s_addc_u32 s57, s57, 0
	s_cmp_gt_u32 s58, 29
	s_cbranch_scc0 .LBB0_761
	s_branch .Lk64_done_p5
.Lk64_trail_p5:
	s_sub_u32 vcc_lo, s34, 0x80000
	s_subb_u32 vcc_hi, s35, 0
	s_add_i32 m0, s44, 0xa000
	s_nop 0
	global_load_lds_dwordx4 v132, vcc
	s_add_u32 vcc_lo, vcc_lo, 0x20000
	s_addc_u32 vcc_hi, vcc_hi, 0
	s_add_i32 m0, s44, 0x9000
	s_nop 0
	global_load_lds_dwordx4 v128, vcc
	s_add_u32 vcc_lo, vcc_lo, 0x60000
	s_addc_u32 vcc_hi, vcc_hi, 0
	s_add_i32 m0, s44, 0xe000
	s_nop 0
	global_load_lds_dwordx4 v132, vcc
	s_add_u32 vcc_lo, vcc_lo, 0x20000
	s_addc_u32 vcc_hi, vcc_hi, 0
	s_add_i32 m0, s44, 0xd000
	s_nop 0
	global_load_lds_dwordx4 v128, vcc
	s_add_u32 vcc_lo, s42, 0x0
	s_addc_u32 vcc_hi, s43, 0
	s_mov_b32 m0, s44
	s_nop 0
	global_load_lds_dwordx4 v128, vcc
	s_sub_u32 vcc_lo, vcc_lo, 0x20000
	s_subb_u32 vcc_hi, vcc_hi, 0
	s_sub_i32 m0, s44, 0x1000
	s_nop 0
	global_load_lds_dwordx4 v128, vcc
	s_add_u32 vcc_lo, vcc_lo, 0xa0000
	s_addc_u32 vcc_hi, vcc_hi, 0
	s_add_i32 m0, s44, 0x4000
	s_nop 0
	global_load_lds_dwordx4 v128, vcc
	s_sub_u32 vcc_lo, vcc_lo, 0x20000
	s_subb_u32 vcc_hi, vcc_hi, 0
	s_add_i32 m0, s44, 0x3000
	s_nop 0
	global_load_lds_dwordx4 v128, vcc
	ds_read_b128 v[144:147], v153 offset:0
	ds_read_b128 v[158:161], v153 offset:1024
	ds_read_b128 v[162:165], v153 offset:2048
	ds_read_b128 v[166:169], v153 offset:3072
	ds_read_b128 v[170:173], v154 offset:0
	ds_read_b128 v[174:177], v154 offset:1024
	ds_read_b128 v[178:181], v154 offset:2048
	ds_read_b128 v[182:185], v154 offset:3072
	ds_read_b128 v[186:189], v155 offset:0
	ds_read_b128 v[190:193], v155 offset:1024
	ds_read_b128 v[194:197], v155 offset:2048
	ds_read_b128 v[198:201], v155 offset:3072
	ds_read_b128 v[202:205], v155 offset:4096
	ds_read_b128 v[206:209], v155 offset:5120
	ds_read_b128 v[210:213], v155 offset:6144
	ds_read_b128 v[214:217], v155 offset:7168
	ds_read_b128 v[220:223], v155 offset:16384
	ds_read_b128 v[224:227], v155 offset:17408
	ds_read_b128 v[228:231], v155 offset:18432
	ds_read_b128 v[232:235], v155 offset:19456
	ds_read_b128 v[236:239], v155 offset:20480
	ds_read_b128 v[240:243], v155 offset:21504
	ds_read_b128 v[244:247], v155 offset:22528
	ds_read_b128 v[248:251], v155 offset:23552
	s_nop 15
	s_nop 15
	s_waitcnt lgkmcnt(0)
	s_barrier
	v_mfma_f32_16x16x32_bf16 v[124:127], v[144:147], v[186:189], v[124:127]
	v_mfma_f32_16x16x32_bf16 v[120:123], v[162:165], v[186:189], v[120:123]
	v_mfma_f32_16x16x32_bf16 v[108:111], v[144:147], v[194:197], v[108:111]
	v_mfma_f32_16x16x32_bf16 v[104:107], v[162:165], v[194:197], v[104:107]
	v_mfma_f32_16x16x32_bf16 v[92:95], v[144:147], v[202:205], v[92:95]
	v_mfma_f32_16x16x32_bf16 v[88:91], v[162:165], v[202:205], v[88:91]
	v_mfma_f32_16x16x32_bf16 v[76:79], v[144:147], v[210:213], v[76:79]
	v_mfma_f32_16x16x32_bf16 v[72:75], v[162:165], v[210:213], v[72:75]
	v_mfma_f32_16x16x32_bf16 v[124:127], v[158:161], v[190:193], v[124:127]
	v_mfma_f32_16x16x32_bf16 v[120:123], v[166:169], v[190:193], v[120:123]
	v_mfma_f32_16x16x32_bf16 v[108:111], v[158:161], v[198:201], v[108:111]
	v_mfma_f32_16x16x32_bf16 v[104:107], v[166:169], v[198:201], v[104:107]
	v_mfma_f32_16x16x32_bf16 v[92:95], v[158:161], v[206:209], v[92:95]
	v_mfma_f32_16x16x32_bf16 v[88:91], v[166:169], v[206:209], v[88:91]
	v_mfma_f32_16x16x32_bf16 v[76:79], v[158:161], v[214:217], v[76:79]
	v_mfma_f32_16x16x32_bf16 v[72:75], v[166:169], v[214:217], v[72:75]
	v_mfma_f32_16x16x32_bf16 v[116:119], v[170:173], v[186:189], v[116:119]
	v_mfma_f32_16x16x32_bf16 v[112:115], v[178:181], v[186:189], v[112:115]
	v_mfma_f32_16x16x32_bf16 v[100:103], v[170:173], v[194:197], v[100:103]
	v_mfma_f32_16x16x32_bf16 v[96:99], v[178:181], v[194:197], v[96:99]
	v_mfma_f32_16x16x32_bf16 v[84:87], v[170:173], v[202:205], v[84:87]
	v_mfma_f32_16x16x32_bf16 v[80:83], v[178:181], v[202:205], v[80:83]
	v_mfma_f32_16x16x32_bf16 v[68:71], v[170:173], v[210:213], v[68:71]
	v_mfma_f32_16x16x32_bf16 v[64:67], v[178:181], v[210:213], v[64:67]
	v_mfma_f32_16x16x32_bf16 v[116:119], v[174:177], v[190:193], v[116:119]
	v_mfma_f32_16x16x32_bf16 v[112:115], v[182:185], v[190:193], v[112:115]
	v_mfma_f32_16x16x32_bf16 v[100:103], v[174:177], v[198:201], v[100:103]
	v_mfma_f32_16x16x32_bf16 v[96:99], v[182:185], v[198:201], v[96:99]
	v_mfma_f32_16x16x32_bf16 v[84:87], v[174:177], v[206:209], v[84:87]
	v_mfma_f32_16x16x32_bf16 v[80:83], v[182:185], v[206:209], v[80:83]
	v_mfma_f32_16x16x32_bf16 v[68:71], v[174:177], v[214:217], v[68:71]
	v_mfma_f32_16x16x32_bf16 v[64:67], v[182:185], v[214:217], v[64:67]
	v_mfma_f32_16x16x32_bf16 v[60:63], v[144:147], v[220:223], v[60:63]
	v_mfma_f32_16x16x32_bf16 v[56:59], v[162:165], v[220:223], v[56:59]
	v_mfma_f32_16x16x32_bf16 v[44:47], v[144:147], v[228:231], v[44:47]
	v_mfma_f32_16x16x32_bf16 v[40:43], v[162:165], v[228:231], v[40:43]
	v_mfma_f32_16x16x32_bf16 v[28:31], v[144:147], v[236:239], v[28:31]
	v_mfma_f32_16x16x32_bf16 v[24:27], v[162:165], v[236:239], v[24:27]
	v_mfma_f32_16x16x32_bf16 v[12:15], v[144:147], v[244:247], v[12:15]
	v_mfma_f32_16x16x32_bf16 v[8:11], v[162:165], v[244:247], v[8:11]
	v_mfma_f32_16x16x32_bf16 v[60:63], v[158:161], v[224:227], v[60:63]
	v_mfma_f32_16x16x32_bf16 v[56:59], v[166:169], v[224:227], v[56:59]
	v_mfma_f32_16x16x32_bf16 v[44:47], v[158:161], v[232:235], v[44:47]
	v_mfma_f32_16x16x32_bf16 v[40:43], v[166:169], v[232:235], v[40:43]
	v_mfma_f32_16x16x32_bf16 v[28:31], v[158:161], v[240:243], v[28:31]
	v_mfma_f32_16x16x32_bf16 v[24:27], v[166:169], v[240:243], v[24:27]
	v_mfma_f32_16x16x32_bf16 v[12:15], v[158:161], v[248:251], v[12:15]
	v_mfma_f32_16x16x32_bf16 v[8:11], v[166:169], v[248:251], v[8:11]
	v_mfma_f32_16x16x32_bf16 v[52:55], v[170:173], v[220:223], v[52:55]
	v_mfma_f32_16x16x32_bf16 v[48:51], v[178:181], v[220:223], v[48:51]
	v_mfma_f32_16x16x32_bf16 v[36:39], v[170:173], v[228:231], v[36:39]
	v_mfma_f32_16x16x32_bf16 v[32:35], v[178:181], v[228:231], v[32:35]
	v_mfma_f32_16x16x32_bf16 v[20:23], v[170:173], v[236:239], v[20:23]
	v_mfma_f32_16x16x32_bf16 v[16:19], v[178:181], v[236:239], v[16:19]
	v_mfma_f32_16x16x32_bf16 v[4:7], v[170:173], v[244:247], v[4:7]
	v_mfma_f32_16x16x32_bf16 v[0:3], v[178:181], v[244:247], v[0:3]
	v_mfma_f32_16x16x32_bf16 v[52:55], v[174:177], v[224:227], v[52:55]
	v_mfma_f32_16x16x32_bf16 v[48:51], v[182:185], v[224:227], v[48:51]
	v_mfma_f32_16x16x32_bf16 v[36:39], v[174:177], v[232:235], v[36:39]
	v_mfma_f32_16x16x32_bf16 v[32:35], v[182:185], v[232:235], v[32:35]
	v_mfma_f32_16x16x32_bf16 v[20:23], v[174:177], v[240:243], v[20:23]
	v_mfma_f32_16x16x32_bf16 v[16:19], v[182:185], v[240:243], v[16:19]
	v_mfma_f32_16x16x32_bf16 v[4:7], v[174:177], v[248:251], v[4:7]
	v_mfma_f32_16x16x32_bf16 v[0:3], v[182:185], v[248:251], v[0:3]
	s_waitcnt vmcnt(0)
	s_barrier
	s_add_u32 vcc_lo, s42, 0x0
	s_addc_u32 vcc_hi, s43, 0
	s_add_i32 m0, s44, 0x2000
	s_nop 0
	global_load_lds_dwordx4 v132, vcc
	s_add_u32 vcc_lo, vcc_lo, 0x20000
	s_addc_u32 vcc_hi, vcc_hi, 0
	s_add_i32 m0, s44, 0x1000
	s_nop 0
	global_load_lds_dwordx4 v128, vcc
	s_add_u32 vcc_lo, vcc_lo, 0x60000
	s_addc_u32 vcc_hi, vcc_hi, 0
	s_add_i32 m0, s44, 0x6000
	s_nop 0
	global_load_lds_dwordx4 v132, vcc
	s_add_u32 vcc_lo, vcc_lo, 0x20000
	s_addc_u32 vcc_hi, vcc_hi, 0
	s_add_i32 m0, s44, 0x5000
	s_nop 0
	global_load_lds_dwordx4 v128, vcc
	s_add_u32 vcc_lo, s42, 0x80
	s_addc_u32 vcc_hi, s43, 0
	s_add_i32 m0, s44, 0x8000
	s_nop 0
	global_load_lds_dwordx4 v128, vcc
	s_sub_u32 vcc_lo, vcc_lo, 0x20000
	s_subb_u32 vcc_hi, vcc_hi, 0
	s_add_i32 m0, s44, 0x7000
	s_nop 0
	global_load_lds_dwordx4 v128, vcc
	s_add_u32 vcc_lo, vcc_lo, 0xa0000
	s_addc_u32 vcc_hi, vcc_hi, 0
	s_add_i32 m0, s44, 0xc000
	s_nop 0
	global_load_lds_dwordx4 v128, vcc
	s_sub_u32 vcc_lo, vcc_lo, 0x20000
	s_subb_u32 vcc_hi, vcc_hi, 0
	s_add_i32 m0, s44, 0xb000
	s_nop 0
	global_load_lds_dwordx4 v128, vcc
	ds_read_b128 v[144:147], v153 offset:32768
	ds_read_b128 v[158:161], v153 offset:33792
	ds_read_b128 v[162:165], v153 offset:34816
	ds_read_b128 v[166:169], v153 offset:35840
	ds_read_b128 v[170:173], v154 offset:32768
	ds_read_b128 v[174:177], v154 offset:33792
	ds_read_b128 v[178:181], v154 offset:34816
	ds_read_b128 v[182:185], v154 offset:35840
	ds_read_b128 v[186:189], v155 offset:32768
	ds_read_b128 v[190:193], v155 offset:33792
	ds_read_b128 v[194:197], v155 offset:34816
	ds_read_b128 v[198:201], v155 offset:35840
	ds_read_b128 v[202:205], v155 offset:36864
	ds_read_b128 v[206:209], v155 offset:37888
	ds_read_b128 v[210:213], v155 offset:38912
	ds_read_b128 v[214:217], v155 offset:39936
	ds_read_b128 v[220:223], v155 offset:49152
	ds_read_b128 v[224:227], v155 offset:50176
	ds_read_b128 v[228:231], v155 offset:51200
	ds_read_b128 v[232:235], v155 offset:52224
	ds_read_b128 v[236:239], v155 offset:53248
	ds_read_b128 v[240:243], v155 offset:54272
	ds_read_b128 v[244:247], v155 offset:55296
	ds_read_b128 v[248:251], v155 offset:56320
	s_nop 15
	s_nop 15
	s_waitcnt lgkmcnt(0)
	s_barrier
	v_mfma_f32_16x16x32_bf16 v[124:127], v[144:147], v[186:189], v[124:127]
	v_mfma_f32_16x16x32_bf16 v[120:123], v[162:165], v[186:189], v[120:123]
	v_mfma_f32_16x16x32_bf16 v[108:111], v[144:147], v[194:197], v[108:111]
	v_mfma_f32_16x16x32_bf16 v[104:107], v[162:165], v[194:197], v[104:107]
	v_mfma_f32_16x16x32_bf16 v[92:95], v[144:147], v[202:205], v[92:95]
	v_mfma_f32_16x16x32_bf16 v[88:91], v[162:165], v[202:205], v[88:91]
	v_mfma_f32_16x16x32_bf16 v[76:79], v[144:147], v[210:213], v[76:79]
	v_mfma_f32_16x16x32_bf16 v[72:75], v[162:165], v[210:213], v[72:75]
	v_mfma_f32_16x16x32_bf16 v[124:127], v[158:161], v[190:193], v[124:127]
	v_mfma_f32_16x16x32_bf16 v[120:123], v[166:169], v[190:193], v[120:123]
	v_mfma_f32_16x16x32_bf16 v[108:111], v[158:161], v[198:201], v[108:111]
	v_mfma_f32_16x16x32_bf16 v[104:107], v[166:169], v[198:201], v[104:107]
	v_mfma_f32_16x16x32_bf16 v[92:95], v[158:161], v[206:209], v[92:95]
	v_mfma_f32_16x16x32_bf16 v[88:91], v[166:169], v[206:209], v[88:91]
	v_mfma_f32_16x16x32_bf16 v[76:79], v[158:161], v[214:217], v[76:79]
	v_mfma_f32_16x16x32_bf16 v[72:75], v[166:169], v[214:217], v[72:75]
	v_mfma_f32_16x16x32_bf16 v[116:119], v[170:173], v[186:189], v[116:119]
	v_mfma_f32_16x16x32_bf16 v[112:115], v[178:181], v[186:189], v[112:115]
	v_mfma_f32_16x16x32_bf16 v[100:103], v[170:173], v[194:197], v[100:103]
	v_mfma_f32_16x16x32_bf16 v[96:99], v[178:181], v[194:197], v[96:99]
	v_mfma_f32_16x16x32_bf16 v[84:87], v[170:173], v[202:205], v[84:87]
	v_mfma_f32_16x16x32_bf16 v[80:83], v[178:181], v[202:205], v[80:83]
	v_mfma_f32_16x16x32_bf16 v[68:71], v[170:173], v[210:213], v[68:71]
	v_mfma_f32_16x16x32_bf16 v[64:67], v[178:181], v[210:213], v[64:67]
	v_mfma_f32_16x16x32_bf16 v[116:119], v[174:177], v[190:193], v[116:119]
	v_mfma_f32_16x16x32_bf16 v[112:115], v[182:185], v[190:193], v[112:115]
	v_mfma_f32_16x16x32_bf16 v[100:103], v[174:177], v[198:201], v[100:103]
	v_mfma_f32_16x16x32_bf16 v[96:99], v[182:185], v[198:201], v[96:99]
	v_mfma_f32_16x16x32_bf16 v[84:87], v[174:177], v[206:209], v[84:87]
	v_mfma_f32_16x16x32_bf16 v[80:83], v[182:185], v[206:209], v[80:83]
	v_mfma_f32_16x16x32_bf16 v[68:71], v[174:177], v[214:217], v[68:71]
	v_mfma_f32_16x16x32_bf16 v[64:67], v[182:185], v[214:217], v[64:67]
	v_mfma_f32_16x16x32_bf16 v[60:63], v[144:147], v[220:223], v[60:63]
	v_mfma_f32_16x16x32_bf16 v[56:59], v[162:165], v[220:223], v[56:59]
	v_mfma_f32_16x16x32_bf16 v[44:47], v[144:147], v[228:231], v[44:47]
	v_mfma_f32_16x16x32_bf16 v[40:43], v[162:165], v[228:231], v[40:43]
	v_mfma_f32_16x16x32_bf16 v[28:31], v[144:147], v[236:239], v[28:31]
	v_mfma_f32_16x16x32_bf16 v[24:27], v[162:165], v[236:239], v[24:27]
	v_mfma_f32_16x16x32_bf16 v[12:15], v[144:147], v[244:247], v[12:15]
	v_mfma_f32_16x16x32_bf16 v[8:11], v[162:165], v[244:247], v[8:11]
	v_mfma_f32_16x16x32_bf16 v[60:63], v[158:161], v[224:227], v[60:63]
	v_mfma_f32_16x16x32_bf16 v[56:59], v[166:169], v[224:227], v[56:59]
	v_mfma_f32_16x16x32_bf16 v[44:47], v[158:161], v[232:235], v[44:47]
	v_mfma_f32_16x16x32_bf16 v[40:43], v[166:169], v[232:235], v[40:43]
	v_mfma_f32_16x16x32_bf16 v[28:31], v[158:161], v[240:243], v[28:31]
	v_mfma_f32_16x16x32_bf16 v[24:27], v[166:169], v[240:243], v[24:27]
	v_mfma_f32_16x16x32_bf16 v[12:15], v[158:161], v[248:251], v[12:15]
	v_mfma_f32_16x16x32_bf16 v[8:11], v[166:169], v[248:251], v[8:11]
	v_mfma_f32_16x16x32_bf16 v[52:55], v[170:173], v[220:223], v[52:55]
	v_mfma_f32_16x16x32_bf16 v[48:51], v[178:181], v[220:223], v[48:51]
	v_mfma_f32_16x16x32_bf16 v[36:39], v[170:173], v[228:231], v[36:39]
	v_mfma_f32_16x16x32_bf16 v[32:35], v[178:181], v[228:231], v[32:35]
	v_mfma_f32_16x16x32_bf16 v[20:23], v[170:173], v[236:239], v[20:23]
	v_mfma_f32_16x16x32_bf16 v[16:19], v[178:181], v[236:239], v[16:19]
	v_mfma_f32_16x16x32_bf16 v[4:7], v[170:173], v[244:247], v[4:7]
	v_mfma_f32_16x16x32_bf16 v[0:3], v[178:181], v[244:247], v[0:3]
	v_mfma_f32_16x16x32_bf16 v[52:55], v[174:177], v[224:227], v[52:55]
	v_mfma_f32_16x16x32_bf16 v[48:51], v[182:185], v[224:227], v[48:51]
	v_mfma_f32_16x16x32_bf16 v[36:39], v[174:177], v[232:235], v[36:39]
	v_mfma_f32_16x16x32_bf16 v[32:35], v[182:185], v[232:235], v[32:35]
	v_mfma_f32_16x16x32_bf16 v[20:23], v[174:177], v[240:243], v[20:23]
	v_mfma_f32_16x16x32_bf16 v[16:19], v[182:185], v[240:243], v[16:19]
	v_mfma_f32_16x16x32_bf16 v[4:7], v[174:177], v[248:251], v[4:7]
	v_mfma_f32_16x16x32_bf16 v[0:3], v[182:185], v[248:251], v[0:3]
	s_waitcnt vmcnt(0)
	s_barrier
	s_add_i32 s58, s58, 2
	s_add_u32 s34, s34, 0x100
	s_addc_u32 s35, s35, 0
	s_add_u32 s56, s56, 0x100
	s_addc_u32 s57, s57, 0
	s_cmp_gt_u32 s58, 29
	s_cbranch_scc0 .LBB0_761

.LBB0_846:
	s_add_u32 s30, s12, 0xfff80080
	s_addc_u32 s31, s13, -1
	s_cmp_eq_u32 s56, 28
	s_cselect_b32 s35, s25, s31
	s_cselect_b32 s34, s52, s30
	s_cselect_b32 s31, s23, s55
	s_cselect_b32 s30, s53, s54
	s_and_b64 vcc, exec, s[16:17]
	s_cbranch_vccz .Lk64_trail_p6
	s_setprio 1
	s_sub_u32 vcc_lo, s54, 0x80
	s_subb_u32 vcc_hi, s55, 0
	s_add_i32 m0, s37, 0x18000
	s_nop 0
	global_load_lds_dwordx4 v148, vcc
	s_add_i32 m0, s37, 0x1a000
	s_nop 0
	global_load_lds_dwordx4 v144, vcc
	s_add_u32 vcc_lo, vcc_lo, 0x20000
	s_addc_u32 vcc_hi, vcc_hi, 0
	s_add_i32 m0, s37, 0x19000
	s_nop 0
	global_load_lds_dwordx4 v148, vcc
	s_add_i32 m0, s37, 0x1b000
	s_nop 0
	global_load_lds_dwordx4 v144, vcc
	s_add_u32 vcc_lo, vcc_lo, 0x60000
	s_addc_u32 vcc_hi, vcc_hi, 0
	s_add_i32 m0, s37, 0x1c000
	s_nop 0
	global_load_lds_dwordx4 v148, vcc
	s_add_i32 m0, s37, 0x1e000
	s_nop 0
	global_load_lds_dwordx4 v144, vcc
	s_add_u32 vcc_lo, vcc_lo, 0x20000
	s_addc_u32 vcc_hi, vcc_hi, 0
	s_add_i32 m0, s37, 0x1d000
	s_nop 0
	global_load_lds_dwordx4 v148, vcc
	s_add_i32 m0, s37, 0x1f000
	s_nop 0
	global_load_lds_dwordx4 v144, vcc
	s_cmp_eq_u32 s56, 28
	s_cbranch_scc0 .Lk64_epd_p6_l
	s_ashr_i32 vcc_lo, s10, 3
	s_mul_i32 vcc_lo, vcc_lo, 0xb000
	s_lshl_b32 vcc_hi, s11, 10
	s_add_i32 vcc_lo, vcc_lo, vcc_hi
	s_lshr_b32 vcc_hi, s37, 2
	s_add_i32 vcc_lo, vcc_lo, vcc_hi
	s_add_u32 vcc_lo, s66, vcc_lo
	s_addc_u32 vcc_hi, s67, 0
	v_and_b32_e32 v248, 63, v252
	v_lshlrev_b32_e32 v248, 2, v248
	s_lshr_b32 m0, s37, 2
	s_add_i32 m0, m0, 0x20000
	s_nop 0
	global_load_lds_dword v248, vcc

.LBB0_940:
	s_add_u32 s24, s22, 0x100
	s_addc_u32 s25, s23, 0
	s_cmpk_eq_i32 s56, 0x54
	s_cselect_b32 s29, s19, s25
	s_cselect_b32 s28, s18, s24
	s_cselect_b32 s27, s21, s47
	s_cselect_b32 s26, s20, s46
	s_and_b64 vcc, exec, s[12:13]
	s_cbranch_vccz .Lk64_trail_p7
	s_setprio 1
	s_sub_u32 vcc_lo, s46, 0x80
	s_subb_u32 vcc_hi, s47, 0
	s_add_i32 m0, s30, 0x18000
	s_nop 0
	global_load_lds_dwordx4 v130, vcc
	s_add_i32 m0, s30, 0x1a000
	s_nop 0
	global_load_lds_dwordx4 v134, vcc
	s_add_u32 vcc_lo, vcc_lo, 0x58000
	s_addc_u32 vcc_hi, vcc_hi, 0
	s_add_i32 m0, s30, 0x19000
	s_nop 0
	global_load_lds_dwordx4 v130, vcc
	s_add_i32 m0, s30, 0x1b000
	s_nop 0
	global_load_lds_dwordx4 v134, vcc
	s_add_u32 vcc_lo, vcc_lo, 0x108000
	s_addc_u32 vcc_hi, vcc_hi, 0
	s_add_i32 m0, s30, 0x1c000
	s_nop 0
	global_load_lds_dwordx4 v130, vcc
	s_add_i32 m0, s30, 0x1e000
	s_nop 0
	global_load_lds_dwordx4 v134, vcc
	s_add_u32 vcc_lo, vcc_lo, 0x58000
	s_addc_u32 vcc_hi, vcc_hi, 0
	s_add_i32 m0, s30, 0x1d000
	s_nop 0
	global_load_lds_dwordx4 v130, vcc
	s_add_i32 m0, s30, 0x1f000
	s_nop 0
	global_load_lds_dwordx4 v134, vcc
	ds_read_b128 v[144:147], v185 offset:0
	ds_read_b128 v[148:151], v185 offset:1024
	ds_read_b128 v[152:155], v185 offset:2048
	ds_read_b128 v[156:159], v185 offset:3072
	ds_read_b128 v[160:163], v186 offset:0
	ds_read_b128 v[164:167], v186 offset:1024
	ds_read_b128 v[168:171], v186 offset:2048
	ds_read_b128 v[172:175], v186 offset:3072
	ds_read_b128 v[176:179], v187 offset:0
	ds_read_b128 v[190:193], v187 offset:1024
	ds_read_b128 v[194:197], v187 offset:2048
	ds_read_b128 v[198:201], v187 offset:3072
	ds_read_b128 v[202:205], v187 offset:4096
	ds_read_b128 v[206:209], v187 offset:5120
	ds_read_b128 v[210:213], v187 offset:6144
	ds_read_b128 v[214:217], v187 offset:7168
	ds_read_b128 v[220:223], v187 offset:16384
	ds_read_b128 v[224:227], v187 offset:17408
	ds_read_b128 v[228:231], v187 offset:18432
	ds_read_b128 v[232:235], v187 offset:19456
	ds_read_b128 v[236:239], v187 offset:20480
	ds_read_b128 v[240:243], v187 offset:21504
	ds_read_b128 v[244:247], v187 offset:22528
	ds_read_b128 v[248:251], v187 offset:23552
	s_nop 15
	s_nop 15
	s_waitcnt lgkmcnt(0)
	s_barrier
	v_mfma_f32_16x16x32_bf16 v[72:75], v[144:147], v[176:179], v[72:75]
	v_mfma_f32_16x16x32_bf16 v[76:79], v[152:155], v[176:179], v[76:79]
	v_mfma_f32_16x16x32_bf16 v[96:99], v[144:147], v[194:197], v[96:99]
	v_mfma_f32_16x16x32_bf16 v[100:103], v[152:155], v[194:197], v[100:103]
	v_mfma_f32_16x16x32_bf16 v[120:123], v[144:147], v[202:205], v[120:123]
	v_mfma_f32_16x16x32_bf16 v[124:127], v[152:155], v[202:205], v[124:127]
	v_mfma_f32_16x16x32_bf16 v[92:95], v[144:147], v[210:213], v[92:95]
	v_mfma_f32_16x16x32_bf16 v[84:87], v[152:155], v[210:213], v[84:87]
	v_mfma_f32_16x16x32_bf16 v[72:75], v[148:151], v[190:193], v[72:75]
	v_mfma_f32_16x16x32_bf16 v[76:79], v[156:159], v[190:193], v[76:79]
	v_mfma_f32_16x16x32_bf16 v[96:99], v[148:151], v[198:201], v[96:99]
	v_mfma_f32_16x16x32_bf16 v[100:103], v[156:159], v[198:201], v[100:103]
	v_mfma_f32_16x16x32_bf16 v[120:123], v[148:151], v[206:209], v[120:123]
	v_mfma_f32_16x16x32_bf16 v[124:127], v[156:159], v[206:209], v[124:127]
	v_mfma_f32_16x16x32_bf16 v[92:95], v[148:151], v[214:217], v[92:95]
	v_mfma_f32_16x16x32_bf16 v[84:87], v[156:159], v[214:217], v[84:87]
	v_mfma_f32_16x16x32_bf16 v[80:83], v[160:163], v[176:179], v[80:83]
	v_mfma_f32_16x16x32_bf16 v[88:91], v[168:171], v[176:179], v[88:91]
	v_mfma_f32_16x16x32_bf16 v[108:111], v[160:163], v[194:197], v[108:111]
	v_mfma_f32_16x16x32_bf16 v[112:115], v[168:171], v[194:197], v[112:115]
	v_mfma_f32_16x16x32_bf16 v[116:119], v[160:163], v[202:205], v[116:119]
	v_mfma_f32_16x16x32_bf16 v[104:107], v[168:171], v[202:205], v[104:107]
	v_mfma_f32_16x16x32_bf16 v[68:71], v[160:163], v[210:213], v[68:71]
	v_mfma_f32_16x16x32_bf16 v[64:67], v[168:171], v[210:213], v[64:67]
	v_mfma_f32_16x16x32_bf16 v[80:83], v[164:167], v[190:193], v[80:83]
	v_mfma_f32_16x16x32_bf16 v[88:91], v[172:175], v[190:193], v[88:91]
	v_mfma_f32_16x16x32_bf16 v[108:111], v[164:167], v[198:201], v[108:111]
	v_mfma_f32_16x16x32_bf16 v[112:115], v[172:175], v[198:201], v[112:115]
	v_mfma_f32_16x16x32_bf16 v[116:119], v[164:167], v[206:209], v[116:119]
	v_mfma_f32_16x16x32_bf16 v[104:107], v[172:175], v[206:209], v[104:107]
	v_mfma_f32_16x16x32_bf16 v[68:71], v[164:167], v[214:217], v[68:71]
	v_mfma_f32_16x16x32_bf16 v[64:67], v[172:175], v[214:217], v[64:67]
	v_mfma_f32_16x16x32_bf16 v[60:63], v[144:147], v[220:223], v[60:63]
	v_mfma_f32_16x16x32_bf16 v[56:59], v[152:155], v[220:223], v[56:59]
	v_mfma_f32_16x16x32_bf16 v[44:47], v[144:147], v[228:231], v[44:47]
	v_mfma_f32_16x16x32_bf16 v[40:43], v[152:155], v[228:231], v[40:43]
	v_mfma_f32_16x16x32_bf16 v[28:31], v[144:147], v[236:239], v[28:31]
	v_mfma_f32_16x16x32_bf16 v[24:27], v[152:155], v[236:239], v[24:27]
	v_mfma_f32_16x16x32_bf16 v[12:15], v[144:147], v[244:247], v[12:15]
	v_mfma_f32_16x16x32_bf16 v[8:11], v[152:155], v[244:247], v[8:11]
	v_mfma_f32_16x16x32_bf16 v[60:63], v[148:151], v[224:227], v[60:63]
	v_mfma_f32_16x16x32_bf16 v[56:59], v[156:159], v[224:227], v[56:59]
	v_mfma_f32_16x16x32_bf16 v[44:47], v[148:151], v[232:235], v[44:47]
	v_mfma_f32_16x16x32_bf16 v[40:43], v[156:159], v[232:235], v[40:43]
	v_mfma_f32_16x16x32_bf16 v[28:31], v[148:151], v[240:243], v[28:31]
	v_mfma_f32_16x16x32_bf16 v[24:27], v[156:159], v[240:243], v[24:27]
	v_mfma_f32_16x16x32_bf16 v[12:15], v[148:151], v[248:251], v[12:15]
	v_mfma_f32_16x16x32_bf16 v[8:11], v[156:159], v[248:251], v[8:11]
	v_mfma_f32_16x16x32_bf16 v[52:55], v[160:163], v[220:223], v[52:55]
	v_mfma_f32_16x16x32_bf16 v[48:51], v[168:171], v[220:223], v[48:51]
	v_mfma_f32_16x16x32_bf16 v[36:39], v[160:163], v[228:231], v[36:39]
	v_mfma_f32_16x16x32_bf16 v[32:35], v[168:171], v[228:231], v[32:35]
	v_mfma_f32_16x16x32_bf16 v[20:23], v[160:163], v[236:239], v[20:23]
	v_mfma_f32_16x16x32_bf16 v[16:19], v[168:171], v[236:239], v[16:19]
	v_mfma_f32_16x16x32_bf16 v[4:7], v[160:163], v[244:247], v[4:7]
	v_mfma_f32_16x16x32_bf16 v[0:3], v[168:171], v[244:247], v[0:3]
	v_mfma_f32_16x16x32_bf16 v[52:55], v[164:167], v[224:227], v[52:55]
	v_mfma_f32_16x16x32_bf16 v[48:51], v[172:175], v[224:227], v[48:51]
	v_mfma_f32_16x16x32_bf16 v[36:39], v[164:167], v[232:235], v[36:39]
	v_mfma_f32_16x16x32_bf16 v[32:35], v[172:175], v[232:235], v[32:35]
	v_mfma_f32_16x16x32_bf16 v[20:23], v[164:167], v[240:243], v[20:23]
	v_mfma_f32_16x16x32_bf16 v[16:19], v[172:175], v[240:243], v[16:19]
	v_mfma_f32_16x16x32_bf16 v[4:7], v[164:167], v[248:251], v[4:7]
	v_mfma_f32_16x16x32_bf16 v[0:3], v[172:175], v[248:251], v[0:3]
	s_waitcnt vmcnt(0)
	s_barrier
	s_add_u32 vcc_lo, s26, 0x0
	s_addc_u32 vcc_hi, s27, 0
	s_add_i32 m0, s30, 0x10000
	s_nop 0
	global_load_lds_dwordx4 v130, vcc
	s_add_i32 m0, s30, 0x12000
	s_nop 0
	global_load_lds_dwordx4 v134, vcc
	s_add_u32 vcc_lo, vcc_lo, 0x58000
	s_addc_u32 vcc_hi, vcc_hi, 0
	s_add_i32 m0, s30, 0x11000
	s_nop 0
	global_load_lds_dwordx4 v130, vcc
	s_add_i32 m0, s30, 0x13000
	s_nop 0
	global_load_lds_dwordx4 v134, vcc
	s_add_u32 vcc_lo, vcc_lo, 0x108000
	s_addc_u32 vcc_hi, vcc_hi, 0
	s_add_i32 m0, s30, 0x14000
	s_nop 0
	global_load_lds_dwordx4 v130, vcc
	s_add_i32 m0, s30, 0x16000
	s_nop 0
	global_load_lds_dwordx4 v134, vcc
	s_add_u32 vcc_lo, vcc_lo, 0x58000
	s_addc_u32 vcc_hi, vcc_hi, 0
	s_add_i32 m0, s30, 0x15000
	s_nop 0
	global_load_lds_dwordx4 v130, vcc
	s_add_i32 m0, s30, 0x17000
	s_nop 0
	global_load_lds_dwordx4 v134, vcc
	ds_read_b128 v[144:147], v185 offset:32768
	ds_read_b128 v[148:151], v185 offset:33792
	ds_read_b128 v[152:155], v185 offset:34816
	ds_read_b128 v[156:159], v185 offset:35840
	ds_read_b128 v[160:163], v186 offset:32768
	ds_read_b128 v[164:167], v186 offset:33792
	ds_read_b128 v[168:171], v186 offset:34816
	ds_read_b128 v[172:175], v186 offset:35840
	ds_read_b128 v[176:179], v187 offset:32768
	ds_read_b128 v[190:193], v187 offset:33792
	ds_read_b128 v[194:197], v187 offset:34816
	ds_read_b128 v[198:201], v187 offset:35840
	ds_read_b128 v[202:205], v187 offset:36864
	ds_read_b128 v[206:209], v187 offset:37888
	ds_read_b128 v[210:213], v187 offset:38912
	ds_read_b128 v[214:217], v187 offset:39936
	ds_read_b128 v[220:223], v187 offset:49152
	ds_read_b128 v[224:227], v187 offset:50176
	ds_read_b128 v[228:231], v187 offset:51200
	ds_read_b128 v[232:235], v187 offset:52224
	ds_read_b128 v[236:239], v187 offset:53248
	ds_read_b128 v[240:243], v187 offset:54272
	ds_read_b128 v[244:247], v187 offset:55296
	ds_read_b128 v[248:251], v187 offset:56320
	s_nop 15
	s_nop 15
	s_waitcnt lgkmcnt(0)
	s_barrier
	v_mfma_f32_16x16x32_bf16 v[72:75], v[144:147], v[176:179], v[72:75]
	v_mfma_f32_16x16x32_bf16 v[76:79], v[152:155], v[176:179], v[76:79]
	v_mfma_f32_16x16x32_bf16 v[96:99], v[144:147], v[194:197], v[96:99]
	v_mfma_f32_16x16x32_bf16 v[100:103], v[152:155], v[194:197], v[100:103]
	v_mfma_f32_16x16x32_bf16 v[120:123], v[144:147], v[202:205], v[120:123]
	v_mfma_f32_16x16x32_bf16 v[124:127], v[152:155], v[202:205], v[124:127]
	v_mfma_f32_16x16x32_bf16 v[92:95], v[144:147], v[210:213], v[92:95]
	v_mfma_f32_16x16x32_bf16 v[84:87], v[152:155], v[210:213], v[84:87]
	v_mfma_f32_16x16x32_bf16 v[72:75], v[148:151], v[190:193], v[72:75]
	v_mfma_f32_16x16x32_bf16 v[76:79], v[156:159], v[190:193], v[76:79]
	v_mfma_f32_16x16x32_bf16 v[96:99], v[148:151], v[198:201], v[96:99]
	v_mfma_f32_16x16x32_bf16 v[100:103], v[156:159], v[198:201], v[100:103]
	v_mfma_f32_16x16x32_bf16 v[120:123], v[148:151], v[206:209], v[120:123]
	v_mfma_f32_16x16x32_bf16 v[124:127], v[156:159], v[206:209], v[124:127]
	v_mfma_f32_16x16x32_bf16 v[92:95], v[148:151], v[214:217], v[92:95]
	v_mfma_f32_16x16x32_bf16 v[84:87], v[156:159], v[214:217], v[84:87]
	v_mfma_f32_16x16x32_bf16 v[80:83], v[160:163], v[176:179], v[80:83]
	v_mfma_f32_16x16x32_bf16 v[88:91], v[168:171], v[176:179], v[88:91]
	v_mfma_f32_16x16x32_bf16 v[108:111], v[160:163], v[194:197], v[108:111]
	v_mfma_f32_16x16x32_bf16 v[112:115], v[168:171], v[194:197], v[112:115]
	v_mfma_f32_16x16x32_bf16 v[116:119], v[160:163], v[202:205], v[116:119]
	v_mfma_f32_16x16x32_bf16 v[104:107], v[168:171], v[202:205], v[104:107]
	v_mfma_f32_16x16x32_bf16 v[68:71], v[160:163], v[210:213], v[68:71]
	v_mfma_f32_16x16x32_bf16 v[64:67], v[168:171], v[210:213], v[64:67]
	v_mfma_f32_16x16x32_bf16 v[80:83], v[164:167], v[190:193], v[80:83]
	v_mfma_f32_16x16x32_bf16 v[88:91], v[172:175], v[190:193], v[88:91]
	v_mfma_f32_16x16x32_bf16 v[108:111], v[164:167], v[198:201], v[108:111]
	v_mfma_f32_16x16x32_bf16 v[112:115], v[172:175], v[198:201], v[112:115]
	v_mfma_f32_16x16x32_bf16 v[116:119], v[164:167], v[206:209], v[116:119]
	v_mfma_f32_16x16x32_bf16 v[104:107], v[172:175], v[206:209], v[104:107]
	v_mfma_f32_16x16x32_bf16 v[68:71], v[164:167], v[214:217], v[68:71]
	v_mfma_f32_16x16x32_bf16 v[64:67], v[172:175], v[214:217], v[64:67]
	v_mfma_f32_16x16x32_bf16 v[60:63], v[144:147], v[220:223], v[60:63]
	v_mfma_f32_16x16x32_bf16 v[56:59], v[152:155], v[220:223], v[56:59]
	v_mfma_f32_16x16x32_bf16 v[44:47], v[144:147], v[228:231], v[44:47]
	v_mfma_f32_16x16x32_bf16 v[40:43], v[152:155], v[228:231], v[40:43]
	v_mfma_f32_16x16x32_bf16 v[28:31], v[144:147], v[236:239], v[28:31]
	v_mfma_f32_16x16x32_bf16 v[24:27], v[152:155], v[236:239], v[24:27]
	v_mfma_f32_16x16x32_bf16 v[12:15], v[144:147], v[244:247], v[12:15]
	v_mfma_f32_16x16x32_bf16 v[8:11], v[152:155], v[244:247], v[8:11]
	v_mfma_f32_16x16x32_bf16 v[60:63], v[148:151], v[224:227], v[60:63]
	v_mfma_f32_16x16x32_bf16 v[56:59], v[156:159], v[224:227], v[56:59]
	v_mfma_f32_16x16x32_bf16 v[44:47], v[148:151], v[232:235], v[44:47]
	v_mfma_f32_16x16x32_bf16 v[40:43], v[156:159], v[232:235], v[40:43]
	v_mfma_f32_16x16x32_bf16 v[28:31], v[148:151], v[240:243], v[28:31]
	v_mfma_f32_16x16x32_bf16 v[24:27], v[156:159], v[240:243], v[24:27]
	v_mfma_f32_16x16x32_bf16 v[12:15], v[148:151], v[248:251], v[12:15]
	v_mfma_f32_16x16x32_bf16 v[8:11], v[156:159], v[248:251], v[8:11]
	v_mfma_f32_16x16x32_bf16 v[52:55], v[160:163], v[220:223], v[52:55]
	v_mfma_f32_16x16x32_bf16 v[48:51], v[168:171], v[220:223], v[48:51]
	v_mfma_f32_16x16x32_bf16 v[36:39], v[160:163], v[228:231], v[36:39]
	v_mfma_f32_16x16x32_bf16 v[32:35], v[168:171], v[228:231], v[32:35]
	v_mfma_f32_16x16x32_bf16 v[20:23], v[160:163], v[236:239], v[20:23]
	v_mfma_f32_16x16x32_bf16 v[16:19], v[168:171], v[236:239], v[16:19]
	v_mfma_f32_16x16x32_bf16 v[4:7], v[160:163], v[244:247], v[4:7]
	v_mfma_f32_16x16x32_bf16 v[0:3], v[168:171], v[244:247], v[0:3]
	v_mfma_f32_16x16x32_bf16 v[52:55], v[164:167], v[224:227], v[52:55]
	v_mfma_f32_16x16x32_bf16 v[48:51], v[172:175], v[224:227], v[48:51]
	v_mfma_f32_16x16x32_bf16 v[36:39], v[164:167], v[232:235], v[36:39]
	v_mfma_f32_16x16x32_bf16 v[32:35], v[172:175], v[232:235], v[32:35]
	v_mfma_f32_16x16x32_bf16 v[20:23], v[164:167], v[240:243], v[20:23]
	v_mfma_f32_16x16x32_bf16 v[16:19], v[172:175], v[240:243], v[16:19]
	v_mfma_f32_16x16x32_bf16 v[4:7], v[164:167], v[248:251], v[4:7]
	v_mfma_f32_16x16x32_bf16 v[0:3], v[172:175], v[248:251], v[0:3]
	s_waitcnt vmcnt(0)
	s_barrier
	s_add_i32 s56, s56, 2
	s_add_u32 s46, s46, 0x100
	s_addc_u32 s47, s47, 0
	s_cmpk_gt_u32 s56, 0x55
	s_mov_b64 s[22:23], s[24:25]
	s_cbranch_scc0 .LBB0_940
	s_branch .Lk64_done_p7
.Lk64_trail_p7:
	s_add_u32 vcc_lo, s22, 0x80
	s_addc_u32 vcc_hi, s23, 0
	s_add_i32 m0, s30, 0xa000
	s_nop 0
	global_load_lds_dwordx4 v132, vcc
	s_add_u32 vcc_lo, vcc_lo, 0x58000
	s_addc_u32 vcc_hi, vcc_hi, 0
	s_add_i32 m0, s30, 0x9000
	s_nop 0
	global_load_lds_dwordx4 v128, vcc
	s_add_u32 vcc_lo, vcc_lo, 0x108000
	s_addc_u32 vcc_hi, vcc_hi, 0
	s_add_i32 m0, s30, 0xe000
	s_nop 0
	global_load_lds_dwordx4 v132, vcc
	s_add_u32 vcc_lo, vcc_lo, 0x58000
	s_addc_u32 vcc_hi, vcc_hi, 0
	s_add_i32 m0, s30, 0xd000
	s_nop 0
	global_load_lds_dwordx4 v128, vcc
	s_add_u32 vcc_lo, s28, 0x0
	s_addc_u32 vcc_hi, s29, 0
	s_mov_b32 m0, s30
	s_nop 0
	global_load_lds_dwordx4 v128, vcc
	s_sub_u32 vcc_lo, vcc_lo, 0x58000
	s_subb_u32 vcc_hi, vcc_hi, 0
	s_sub_i32 m0, s30, 0x1000
	s_nop 0
	global_load_lds_dwordx4 v128, vcc
	s_add_u32 vcc_lo, vcc_lo, 0x1b8000
	s_addc_u32 vcc_hi, vcc_hi, 0
	s_add_i32 m0, s30, 0x4000
	s_nop 0
	global_load_lds_dwordx4 v128, vcc
	s_sub_u32 vcc_lo, vcc_lo, 0x58000
	s_subb_u32 vcc_hi, vcc_hi, 0
	s_add_i32 m0, s30, 0x3000
	s_nop 0
	global_load_lds_dwordx4 v128, vcc
	ds_read_b128 v[144:147], v185 offset:0
	ds_read_b128 v[148:151], v185 offset:1024
	ds_read_b128 v[152:155], v185 offset:2048
	ds_read_b128 v[156:159], v185 offset:3072
	ds_read_b128 v[160:163], v186 offset:0
	ds_read_b128 v[164:167], v186 offset:1024
	ds_read_b128 v[168:171], v186 offset:2048
	ds_read_b128 v[172:175], v186 offset:3072
	ds_read_b128 v[176:179], v187 offset:0
	ds_read_b128 v[190:193], v187 offset:1024
	ds_read_b128 v[194:197], v187 offset:2048
	ds_read_b128 v[198:201], v187 offset:3072
	ds_read_b128 v[202:205], v187 offset:4096
	ds_read_b128 v[206:209], v187 offset:5120
	ds_read_b128 v[210:213], v187 offset:6144
	ds_read_b128 v[214:217], v187 offset:7168
	ds_read_b128 v[220:223], v187 offset:16384
	ds_read_b128 v[224:227], v187 offset:17408
	ds_read_b128 v[228:231], v187 offset:18432
	ds_read_b128 v[232:235], v187 offset:19456
	ds_read_b128 v[236:239], v187 offset:20480
	ds_read_b128 v[240:243], v187 offset:21504
	ds_read_b128 v[244:247], v187 offset:22528
	ds_read_b128 v[248:251], v187 offset:23552
	s_nop 15
	s_nop 15
	s_waitcnt lgkmcnt(0)
	s_barrier
	v_mfma_f32_16x16x32_bf16 v[72:75], v[144:147], v[176:179], v[72:75]
	v_mfma_f32_16x16x32_bf16 v[76:79], v[152:155], v[176:179], v[76:79]
	v_mfma_f32_16x16x32_bf16 v[96:99], v[144:147], v[194:197], v[96:99]
	v_mfma_f32_16x16x32_bf16 v[100:103], v[152:155], v[194:197], v[100:103]
	v_mfma_f32_16x16x32_bf16 v[120:123], v[144:147], v[202:205], v[120:123]
	v_mfma_f32_16x16x32_bf16 v[124:127], v[152:155], v[202:205], v[124:127]
	v_mfma_f32_16x16x32_bf16 v[92:95], v[144:147], v[210:213], v[92:95]
	v_mfma_f32_16x16x32_bf16 v[84:87], v[152:155], v[210:213], v[84:87]
	v_mfma_f32_16x16x32_bf16 v[72:75], v[148:151], v[190:193], v[72:75]
	v_mfma_f32_16x16x32_bf16 v[76:79], v[156:159], v[190:193], v[76:79]
	v_mfma_f32_16x16x32_bf16 v[96:99], v[148:151], v[198:201], v[96:99]
	v_mfma_f32_16x16x32_bf16 v[100:103], v[156:159], v[198:201], v[100:103]
	v_mfma_f32_16x16x32_bf16 v[120:123], v[148:151], v[206:209], v[120:123]
	v_mfma_f32_16x16x32_bf16 v[124:127], v[156:159], v[206:209], v[124:127]
	v_mfma_f32_16x16x32_bf16 v[92:95], v[148:151], v[214:217], v[92:95]
	v_mfma_f32_16x16x32_bf16 v[84:87], v[156:159], v[214:217], v[84:87]
	v_mfma_f32_16x16x32_bf16 v[80:83], v[160:163], v[176:179], v[80:83]
	v_mfma_f32_16x16x32_bf16 v[88:91], v[168:171], v[176:179], v[88:91]
	v_mfma_f32_16x16x32_bf16 v[108:111], v[160:163], v[194:197], v[108:111]
	v_mfma_f32_16x16x32_bf16 v[112:115], v[168:171], v[194:197], v[112:115]
	v_mfma_f32_16x16x32_bf16 v[116:119], v[160:163], v[202:205], v[116:119]
	v_mfma_f32_16x16x32_bf16 v[104:107], v[168:171], v[202:205], v[104:107]
	v_mfma_f32_16x16x32_bf16 v[68:71], v[160:163], v[210:213], v[68:71]
	v_mfma_f32_16x16x32_bf16 v[64:67], v[168:171], v[210:213], v[64:67]
	v_mfma_f32_16x16x32_bf16 v[80:83], v[164:167], v[190:193], v[80:83]
	v_mfma_f32_16x16x32_bf16 v[88:91], v[172:175], v[190:193], v[88:91]
	v_mfma_f32_16x16x32_bf16 v[108:111], v[164:167], v[198:201], v[108:111]
	v_mfma_f32_16x16x32_bf16 v[112:115], v[172:175], v[198:201], v[112:115]
	v_mfma_f32_16x16x32_bf16 v[116:119], v[164:167], v[206:209], v[116:119]
	v_mfma_f32_16x16x32_bf16 v[104:107], v[172:175], v[206:209], v[104:107]
	v_mfma_f32_16x16x32_bf16 v[68:71], v[164:167], v[214:217], v[68:71]
	v_mfma_f32_16x16x32_bf16 v[64:67], v[172:175], v[214:217], v[64:67]
	v_mfma_f32_16x16x32_bf16 v[60:63], v[144:147], v[220:223], v[60:63]
	v_mfma_f32_16x16x32_bf16 v[56:59], v[152:155], v[220:223], v[56:59]
	v_mfma_f32_16x16x32_bf16 v[44:47], v[144:147], v[228:231], v[44:47]
	v_mfma_f32_16x16x32_bf16 v[40:43], v[152:155], v[228:231], v[40:43]
	v_mfma_f32_16x16x32_bf16 v[28:31], v[144:147], v[236:239], v[28:31]
	v_mfma_f32_16x16x32_bf16 v[24:27], v[152:155], v[236:239], v[24:27]
	v_mfma_f32_16x16x32_bf16 v[12:15], v[144:147], v[244:247], v[12:15]
	v_mfma_f32_16x16x32_bf16 v[8:11], v[152:155], v[244:247], v[8:11]
	v_mfma_f32_16x16x32_bf16 v[60:63], v[148:151], v[224:227], v[60:63]
	v_mfma_f32_16x16x32_bf16 v[56:59], v[156:159], v[224:227], v[56:59]
	v_mfma_f32_16x16x32_bf16 v[44:47], v[148:151], v[232:235], v[44:47]
	v_mfma_f32_16x16x32_bf16 v[40:43], v[156:159], v[232:235], v[40:43]
	v_mfma_f32_16x16x32_bf16 v[28:31], v[148:151], v[240:243], v[28:31]
	v_mfma_f32_16x16x32_bf16 v[24:27], v[156:159], v[240:243], v[24:27]
	v_mfma_f32_16x16x32_bf16 v[12:15], v[148:151], v[248:251], v[12:15]
	v_mfma_f32_16x16x32_bf16 v[8:11], v[156:159], v[248:251], v[8:11]
	v_mfma_f32_16x16x32_bf16 v[52:55], v[160:163], v[220:223], v[52:55]
	v_mfma_f32_16x16x32_bf16 v[48:51], v[168:171], v[220:223], v[48:51]
	v_mfma_f32_16x16x32_bf16 v[36:39], v[160:163], v[228:231], v[36:39]
	v_mfma_f32_16x16x32_bf16 v[32:35], v[168:171], v[228:231], v[32:35]
	v_mfma_f32_16x16x32_bf16 v[20:23], v[160:163], v[236:239], v[20:23]
	v_mfma_f32_16x16x32_bf16 v[16:19], v[168:171], v[236:239], v[16:19]
	v_mfma_f32_16x16x32_bf16 v[4:7], v[160:163], v[244:247], v[4:7]
	v_mfma_f32_16x16x32_bf16 v[0:3], v[168:171], v[244:247], v[0:3]
	v_mfma_f32_16x16x32_bf16 v[52:55], v[164:167], v[224:227], v[52:55]
	v_mfma_f32_16x16x32_bf16 v[48:51], v[172:175], v[224:227], v[48:51]
	v_mfma_f32_16x16x32_bf16 v[36:39], v[164:167], v[232:235], v[36:39]
	v_mfma_f32_16x16x32_bf16 v[32:35], v[172:175], v[232:235], v[32:35]
	v_mfma_f32_16x16x32_bf16 v[20:23], v[164:167], v[240:243], v[20:23]
	v_mfma_f32_16x16x32_bf16 v[16:19], v[172:175], v[240:243], v[16:19]
	v_mfma_f32_16x16x32_bf16 v[4:7], v[164:167], v[248:251], v[4:7]
	v_mfma_f32_16x16x32_bf16 v[0:3], v[172:175], v[248:251], v[0:3]
	s_waitcnt vmcnt(0)
	s_barrier
	s_add_u32 vcc_lo, s28, 0x0
	s_addc_u32 vcc_hi, s29, 0
	s_add_i32 m0, s30, 0x2000
	s_nop 0
	global_load_lds_dwordx4 v132, vcc
	s_add_u32 vcc_lo, vcc_lo, 0x58000
	s_addc_u32 vcc_hi, vcc_hi, 0
	s_add_i32 m0, s30, 0x1000
	s_nop 0
	global_load_lds_dwordx4 v128, vcc
	s_add_u32 vcc_lo, vcc_lo, 0x108000
	s_addc_u32 vcc_hi, vcc_hi, 0
	s_add_i32 m0, s30, 0x6000
	s_nop 0
	global_load_lds_dwordx4 v132, vcc
	s_add_u32 vcc_lo, vcc_lo, 0x58000
	s_addc_u32 vcc_hi, vcc_hi, 0
	s_add_i32 m0, s30, 0x5000
	s_nop 0
	global_load_lds_dwordx4 v128, vcc
	s_add_u32 vcc_lo, s28, 0x80
	s_addc_u32 vcc_hi, s29, 0
	s_add_i32 m0, s30, 0x8000
	s_nop 0
	global_load_lds_dwordx4 v128, vcc
	s_sub_u32 vcc_lo, vcc_lo, 0x58000
	s_subb_u32 vcc_hi, vcc_hi, 0
	s_add_i32 m0, s30, 0x7000
	s_nop 0
	global_load_lds_dwordx4 v128, vcc
	s_add_u32 vcc_lo, vcc_lo, 0x1b8000
	s_addc_u32 vcc_hi, vcc_hi, 0
	s_add_i32 m0, s30, 0xc000
	s_nop 0
	global_load_lds_dwordx4 v128, vcc
	s_sub_u32 vcc_lo, vcc_lo, 0x58000
	s_subb_u32 vcc_hi, vcc_hi, 0
	s_add_i32 m0, s30, 0xb000
	s_nop 0
	global_load_lds_dwordx4 v128, vcc
	ds_read_b128 v[144:147], v185 offset:32768
	ds_read_b128 v[148:151], v185 offset:33792
	ds_read_b128 v[152:155], v185 offset:34816
	ds_read_b128 v[156:159], v185 offset:35840
	ds_read_b128 v[160:163], v186 offset:32768
	ds_read_b128 v[164:167], v186 offset:33792
	ds_read_b128 v[168:171], v186 offset:34816
	ds_read_b128 v[172:175], v186 offset:35840
	ds_read_b128 v[176:179], v187 offset:32768
	ds_read_b128 v[190:193], v187 offset:33792
	ds_read_b128 v[194:197], v187 offset:34816
	ds_read_b128 v[198:201], v187 offset:35840
	ds_read_b128 v[202:205], v187 offset:36864
	ds_read_b128 v[206:209], v187 offset:37888
	ds_read_b128 v[210:213], v187 offset:38912
	ds_read_b128 v[214:217], v187 offset:39936
	ds_read_b128 v[220:223], v187 offset:49152
	ds_read_b128 v[224:227], v187 offset:50176
	ds_read_b128 v[228:231], v187 offset:51200
	ds_read_b128 v[232:235], v187 offset:52224
	ds_read_b128 v[236:239], v187 offset:53248
	ds_read_b128 v[240:243], v187 offset:54272
	ds_read_b128 v[244:247], v187 offset:55296
	ds_read_b128 v[248:251], v187 offset:56320
	s_nop 15
	s_nop 15
	s_waitcnt lgkmcnt(0)
	s_barrier
	v_mfma_f32_16x16x32_bf16 v[72:75], v[144:147], v[176:179], v[72:75]
	v_mfma_f32_16x16x32_bf16 v[76:79], v[152:155], v[176:179], v[76:79]
	v_mfma_f32_16x16x32_bf16 v[96:99], v[144:147], v[194:197], v[96:99]
	v_mfma_f32_16x16x32_bf16 v[100:103], v[152:155], v[194:197], v[100:103]
	v_mfma_f32_16x16x32_bf16 v[120:123], v[144:147], v[202:205], v[120:123]
	v_mfma_f32_16x16x32_bf16 v[124:127], v[152:155], v[202:205], v[124:127]
	v_mfma_f32_16x16x32_bf16 v[92:95], v[144:147], v[210:213], v[92:95]
	v_mfma_f32_16x16x32_bf16 v[84:87], v[152:155], v[210:213], v[84:87]
	v_mfma_f32_16x16x32_bf16 v[72:75], v[148:151], v[190:193], v[72:75]
	v_mfma_f32_16x16x32_bf16 v[76:79], v[156:159], v[190:193], v[76:79]
	v_mfma_f32_16x16x32_bf16 v[96:99], v[148:151], v[198:201], v[96:99]
	v_mfma_f32_16x16x32_bf16 v[100:103], v[156:159], v[198:201], v[100:103]
	v_mfma_f32_16x16x32_bf16 v[120:123], v[148:151], v[206:209], v[120:123]
	v_mfma_f32_16x16x32_bf16 v[124:127], v[156:159], v[206:209], v[124:127]
	v_mfma_f32_16x16x32_bf16 v[92:95], v[148:151], v[214:217], v[92:95]
	v_mfma_f32_16x16x32_bf16 v[84:87], v[156:159], v[214:217], v[84:87]
	v_mfma_f32_16x16x32_bf16 v[80:83], v[160:163], v[176:179], v[80:83]
	v_mfma_f32_16x16x32_bf16 v[88:91], v[168:171], v[176:179], v[88:91]
	v_mfma_f32_16x16x32_bf16 v[108:111], v[160:163], v[194:197], v[108:111]
	v_mfma_f32_16x16x32_bf16 v[112:115], v[168:171], v[194:197], v[112:115]
	v_mfma_f32_16x16x32_bf16 v[116:119], v[160:163], v[202:205], v[116:119]
	v_mfma_f32_16x16x32_bf16 v[104:107], v[168:171], v[202:205], v[104:107]
	v_mfma_f32_16x16x32_bf16 v[68:71], v[160:163], v[210:213], v[68:71]
	v_mfma_f32_16x16x32_bf16 v[64:67], v[168:171], v[210:213], v[64:67]
	v_mfma_f32_16x16x32_bf16 v[80:83], v[164:167], v[190:193], v[80:83]
	v_mfma_f32_16x16x32_bf16 v[88:91], v[172:175], v[190:193], v[88:91]
	v_mfma_f32_16x16x32_bf16 v[108:111], v[164:167], v[198:201], v[108:111]
	v_mfma_f32_16x16x32_bf16 v[112:115], v[172:175], v[198:201], v[112:115]
	v_mfma_f32_16x16x32_bf16 v[116:119], v[164:167], v[206:209], v[116:119]
	v_mfma_f32_16x16x32_bf16 v[104:107], v[172:175], v[206:209], v[104:107]
	v_mfma_f32_16x16x32_bf16 v[68:71], v[164:167], v[214:217], v[68:71]
	v_mfma_f32_16x16x32_bf16 v[64:67], v[172:175], v[214:217], v[64:67]
	v_mfma_f32_16x16x32_bf16 v[60:63], v[144:147], v[220:223], v[60:63]
	v_mfma_f32_16x16x32_bf16 v[56:59], v[152:155], v[220:223], v[56:59]
	v_mfma_f32_16x16x32_bf16 v[44:47], v[144:147], v[228:231], v[44:47]
	v_mfma_f32_16x16x32_bf16 v[40:43], v[152:155], v[228:231], v[40:43]
	v_mfma_f32_16x16x32_bf16 v[28:31], v[144:147], v[236:239], v[28:31]
	v_mfma_f32_16x16x32_bf16 v[24:27], v[152:155], v[236:239], v[24:27]
	v_mfma_f32_16x16x32_bf16 v[12:15], v[144:147], v[244:247], v[12:15]
	v_mfma_f32_16x16x32_bf16 v[8:11], v[152:155], v[244:247], v[8:11]
	v_mfma_f32_16x16x32_bf16 v[60:63], v[148:151], v[224:227], v[60:63]
	v_mfma_f32_16x16x32_bf16 v[56:59], v[156:159], v[224:227], v[56:59]
	v_mfma_f32_16x16x32_bf16 v[44:47], v[148:151], v[232:235], v[44:47]
	v_mfma_f32_16x16x32_bf16 v[40:43], v[156:159], v[232:235], v[40:43]
	v_mfma_f32_16x16x32_bf16 v[28:31], v[148:151], v[240:243], v[28:31]
	v_mfma_f32_16x16x32_bf16 v[24:27], v[156:159], v[240:243], v[24:27]
	v_mfma_f32_16x16x32_bf16 v[12:15], v[148:151], v[248:251], v[12:15]
	v_mfma_f32_16x16x32_bf16 v[8:11], v[156:159], v[248:251], v[8:11]
	v_mfma_f32_16x16x32_bf16 v[52:55], v[160:163], v[220:223], v[52:55]
	v_mfma_f32_16x16x32_bf16 v[48:51], v[168:171], v[220:223], v[48:51]
	v_mfma_f32_16x16x32_bf16 v[36:39], v[160:163], v[228:231], v[36:39]
	v_mfma_f32_16x16x32_bf16 v[32:35], v[168:171], v[228:231], v[32:35]
	v_mfma_f32_16x16x32_bf16 v[20:23], v[160:163], v[236:239], v[20:23]
	v_mfma_f32_16x16x32_bf16 v[16:19], v[168:171], v[236:239], v[16:19]
	v_mfma_f32_16x16x32_bf16 v[4:7], v[160:163], v[244:247], v[4:7]
	v_mfma_f32_16x16x32_bf16 v[0:3], v[168:171], v[244:247], v[0:3]
	v_mfma_f32_16x16x32_bf16 v[52:55], v[164:167], v[224:227], v[52:55]
	v_mfma_f32_16x16x32_bf16 v[48:51], v[172:175], v[224:227], v[48:51]
	v_mfma_f32_16x16x32_bf16 v[36:39], v[164:167], v[232:235], v[36:39]
	v_mfma_f32_16x16x32_bf16 v[32:35], v[172:175], v[232:235], v[32:35]
	v_mfma_f32_16x16x32_bf16 v[20:23], v[164:167], v[240:243], v[20:23]
	v_mfma_f32_16x16x32_bf16 v[16:19], v[172:175], v[240:243], v[16:19]
	v_mfma_f32_16x16x32_bf16 v[4:7], v[164:167], v[248:251], v[4:7]
	v_mfma_f32_16x16x32_bf16 v[0:3], v[172:175], v[248:251], v[0:3]
	s_waitcnt vmcnt(0)
	s_barrier
	s_add_i32 s56, s56, 2
	s_add_u32 s46, s46, 0x100
	s_addc_u32 s47, s47, 0
	s_cmpk_gt_u32 s56, 0x55
	s_mov_b64 s[22:23], s[24:25]
	s_cbranch_scc0 .LBB0_940
